# v24 + next-unit decode moved from the unit-loop header into the peeled first body (after its ds_reads and stage loads), last-body selects of the peeled body folded; 11 GEMM phases
# baseline (speedup 1.0000x reference)
; #define PG8_STAGE(bufoff, gbase, voff) do { _Pragma("unroll") for (int _i = 0; _i < 2; ++_i) \
;         __builtin_amdgcn_global_load_lds((const unsigned*)((const char*)(gbase) + (voff)[_i]), (PG8_LAS unsigned*)(lds + (bufoff) + ldsw + _i * 8192), 16, 0, 0); } while (0)
; #define PG8_LDA(dst, b, h) do { _Pragma("unroll") for (int m = 0; m < 4; ++m) _Pragma("unroll") for (int k = 0; k < 2; ++k) dst[m][k] = *(const PG8_LAS bf16x8*)(lds + PG8_SA(b, h) + aoff + m * 2048 + k * 1024); } while (0)
; #define PG8_LDB(dst, b, h) do { _Pragma("unroll") for (int n = 0; n < 2; ++n) _Pragma("unroll") for (int k = 0; k < 2; ++k) dst[n][k] = *(const PG8_LAS bf16x8*)(lds + PG8_SB(b, h) + boff + n * 2048 + k * 1024); } while (0)
; #define PG8_MMA(ai, bj, At, Bt) do { __builtin_amdgcn_s_setprio(1); _Pragma("unroll") for (int m = 0; m < 4; ++m) _Pragma("unroll") for (int n = 0; n < 2; ++n) _Pragma("unroll") for (int k = 0; k < 2; ++k) \
;         acc[ai][bj][m][n] = __builtin_amdgcn_mfma_f32_16x16x32_bf16(Bt[n][k], At[m][k], acc[ai][bj][m][n], 0, 0, 0); __builtin_amdgcn_s_setprio(0); } while (0)
; #define PG8_WAIT_V(n) asm volatile("s_waitcnt vmcnt(" #n ")" ::: "memory")
; #define PG8_WAIT_L(n) asm volatile("s_waitcnt lgkmcnt(" #n ")" ::: "memory")
; #define PG8_BAR __builtin_amdgcn_s_barrier()
; #define PG8_SCHED __builtin_amdgcn_sched_barrier(0)
;     __host__ __device__ bool next(int i, Unit& u) const {
;         const long L = (long)i * G + c; if (L >= nwg) return false;
;         int wgid = (int)L; { const int q = nwg / NXCD, r = nwg % NXCD, xcd = wgid % NXCD, off = wgid / NXCD; wgid = (xcd < r ? xcd * (q + 1) : r * (q + 1) + (xcd - r) * q) + off; }
;         const int nig = WGM * nN, gid = wgid / nig, fm = gid * WGM, gsz = (nM - fm) < WGM ? (nM - fm) : WGM;
;         u.pm = fm + ((wgid % nig) % gsz); u.pn = (wgid % nig) / gsz; return true;
;     }
; template <class Epi, class Sched, bool ALIGN_EPI = false, bool SP2 = false>
; __device__ __forceinline__ void gemm_phase(PG8_LAS unsigned char* lds, const Gemm g, const Sched& S, const Epi& E) {
;     ...
;             PG8_LDB(B0, 0, 0); PG8_LDB(B1, 0, 1); PG8_SCHED; PG8_LDA(At, 0, 0); PG8_STAGE(PG8_SA(1, 1), a1 + hstepA, voffA);
;             PG8_WAIT_V(8); PG8_WAIT_L(0); PG8_BAR; PG8_MMA(0, 0, At, B0); PG8_MMA(0, 1, At, B1); PG8_BAR; PG8_SCHED;
.LBB0_182:
	s_mov_b32 s100, s34
	s_mov_b32 s101, s35
	s_mov_b32 s43, s36
	s_mov_b32 s61, s37
	s_add_u32 s34, s34, 0x80080
	s_addc_u32 s35, s35, 0
	s_add_u32 s40, s36, 0x100
	s_addc_u32 s41, s37, 0
	ds_read_b128 v[162:165], v158
	ds_read_b128 v[166:169], v158 offset:1024
	ds_read_b128 v[170:173], v158 offset:2048
	ds_read_b128 v[174:177], v158 offset:3072
	ds_read_b128 v[178:181], v159
	ds_read_b128 v[182:185], v159 offset:1024
	ds_read_b128 v[186:189], v159 offset:2048
	ds_read_b128 v[190:193], v159 offset:3072
	s_add_u32 s36, s34, 0xfff80080
	s_addc_u32 s37, s35, -1
	s_mov_b32 s39, s37
	s_mov_b32 s38, s36
	s_mov_b32 s37, s41
	s_mov_b32 s36, s40
	v_lshl_add_u64 v[156:157], s[34:35], 0, v[148:149]
	s_add_i32 m0, s45, 0xc000
	ds_read_b128 v[194:197], v160
	ds_read_b128 v[198:201], v160 offset:1024
	ds_read_b128 v[202:205], v160 offset:2048
	ds_read_b128 v[210:213], v160 offset:3072
	ds_read_b128 v[214:217], v160 offset:4096
	ds_read_b128 v[218:221], v160 offset:5120
	ds_read_b128 v[222:225], v160 offset:6144
	ds_read_b128 v[226:229], v160 offset:7168
	global_load_lds_dwordx4 v[156:157], off
	v_lshl_add_u64 v[156:157], s[34:35], 0, v[150:151]
	s_add_i32 m0, s45, 0xe000
	s_nop 0
	global_load_lds_dwordx4 v[156:157], off
	s_add_i32 s49, s49, 1
	s_mul_i32 s1, s49, s54
	s_mul_hi_u32 s8, s49, s33
	s_add_i32 s8, s8, s1
	s_mul_i32 s1, s49, s33
	s_add_u32 s28, s1, s70
	s_addc_u32 s29, s8, s55
	v_cmp_gt_i64_e32 vcc, s[28:29], v[154:155]
	v_cmp_lt_i64_e64 s[8:9], s[28:29], v[152:153]
	s_cbranch_vccnz .LBB0_184
	s_ashr_i32 s1, s28, 31
	s_lshr_b32 s1, s1, 29
	s_add_i32 s1, s28, s1
	s_ashr_i32 s11, s1, 3
	s_and_b32 s1, s1, -8
	s_sub_i32 s1, s28, s1
	s_lshr_b32 s24, s1, 31
	s_or_b32 s24, s24, 0x294
	s_mul_i32 s1, s24, s1
	s_add_i32 s1, s1, s11
	s_mul_hi_i32 s11, s1, 0x3e0f83e1
	s_lshr_b32 s24, s11, 31
	s_ashr_i32 s11, s11, 5
	s_add_i32 s11, s11, s24
	s_lshl_b32 s25, s11, 2
	s_sub_i32 s24, 0xa0, s25
	s_min_i32 s26, s24, 4
	s_abs_i32 s24, s26
	v_cvt_f32_u32_e32 v2, s24
	s_sub_i32 s28, 0, s24
	s_mulk_i32 s11, 0x84
	s_sub_i32 s1, s1, s11
	v_rcp_iflag_f32_e32 v2, v2
	s_abs_i32 s11, s1
	s_xor_b32 s27, s1, s26
	s_ashr_i32 s27, s27, 31
	v_mul_f32_e32 v2, 0x4f7ffffe, v2
	v_cvt_u32_f32_e32 v2, v2
	s_nop 0
	v_readfirstlane_b32 s29, v2
	s_mul_i32 s28, s28, s29
	s_mul_hi_u32 s28, s29, s28
	s_add_i32 s29, s29, s28
	s_mul_hi_u32 s28, s11, s29
	s_mul_i32 s29, s28, s24
	s_sub_i32 s11, s11, s29
	s_add_i32 s30, s28, 1
	s_sub_i32 s29, s11, s24
	s_cmp_ge_u32 s11, s24
	s_cselect_b32 s28, s30, s28
	s_cselect_b32 s11, s29, s11
	s_add_i32 s29, s28, 1
	s_cmp_ge_u32 s11, s24
	s_cselect_b32 s11, s29, s28
	s_xor_b32 s11, s11, s27
	s_sub_i32 s24, s11, s27
	s_mul_i32 s11, s24, s26
	s_sub_i32 s1, s1, s11
	s_add_i32 s26, s1, s25
.LBB0_184:
	s_ashr_i32 s27, s26, 31
	s_lshl_b64 s[28:29], s[26:27], 20
	s_add_u32 s28, s86, s28
	s_addc_u32 s29, s87, s29
	s_and_b64 s[30:31], s[8:9], exec
	s_cselect_b32 s1, s29, s101
	s_cselect_b32 s11, s28, s100
	s_ashr_i32 s25, s24, 31
	s_lshl_b64 s[30:31], s[24:25], 20
	s_add_u32 s30, s64, s30
	s_addc_u32 s31, s65, s31
	s_and_b64 s[98:99], s[8:9], exec
	s_cselect_b32 s25, s31, s61
	s_cselect_b32 s27, s30, s43
	s_mov_b32 s42, -2
	s_waitcnt vmcnt(8)
	s_waitcnt lgkmcnt(0)
	s_barrier
	s_setprio 1
	s_waitcnt lgkmcnt(0)
	v_mfma_f32_16x16x32_bf16 v[126:129], v[162:165], v[194:197], 0
	v_mfma_f32_16x16x32_bf16 v[122:125], v[170:173], v[194:197], 0
	v_mfma_f32_16x16x32_bf16 v[110:113], v[162:165], v[202:205], 0
	v_mfma_f32_16x16x32_bf16 v[106:109], v[170:173], v[202:205], 0
	v_mfma_f32_16x16x32_bf16 v[94:97], v[162:165], v[214:217], 0
	v_mfma_f32_16x16x32_bf16 v[90:93], v[170:173], v[214:217], 0
	v_mfma_f32_16x16x32_bf16 v[78:81], v[162:165], v[222:225], 0
	v_mfma_f32_16x16x32_bf16 v[74:77], v[170:173], v[222:225], 0
	v_mfma_f32_16x16x32_bf16 v[126:129], v[166:169], v[198:201], v[126:129]
	v_mfma_f32_16x16x32_bf16 v[122:125], v[174:177], v[198:201], v[122:125]
	v_mfma_f32_16x16x32_bf16 v[110:113], v[166:169], v[210:213], v[110:113]
	v_mfma_f32_16x16x32_bf16 v[106:109], v[174:177], v[210:213], v[106:109]
	v_mfma_f32_16x16x32_bf16 v[94:97], v[166:169], v[218:221], v[94:97]
	v_mfma_f32_16x16x32_bf16 v[90:93], v[174:177], v[218:221], v[90:93]
	v_mfma_f32_16x16x32_bf16 v[78:81], v[166:169], v[226:229], v[78:81]
	v_mfma_f32_16x16x32_bf16 v[74:77], v[174:177], v[226:229], v[74:77]
	s_setprio 0
	s_setprio 1
	v_mfma_f32_16x16x32_bf16 v[118:121], v[178:181], v[194:197], 0
	v_mfma_f32_16x16x32_bf16 v[114:117], v[186:189], v[194:197], 0
	v_mfma_f32_16x16x32_bf16 v[102:105], v[178:181], v[202:205], 0
	v_mfma_f32_16x16x32_bf16 v[98:101], v[186:189], v[202:205], 0
	v_mfma_f32_16x16x32_bf16 v[86:89], v[178:181], v[214:217], 0
	v_mfma_f32_16x16x32_bf16 v[82:85], v[186:189], v[214:217], 0
	v_mfma_f32_16x16x32_bf16 v[70:73], v[178:181], v[222:225], 0
	v_mfma_f32_16x16x32_bf16 v[66:69], v[186:189], v[222:225], 0
	v_mfma_f32_16x16x32_bf16 v[118:121], v[182:185], v[198:201], v[118:121]
	v_mfma_f32_16x16x32_bf16 v[114:117], v[190:193], v[198:201], v[114:117]
	v_mfma_f32_16x16x32_bf16 v[102:105], v[182:185], v[210:213], v[102:105]
	v_mfma_f32_16x16x32_bf16 v[98:101], v[190:193], v[210:213], v[98:101]
	v_mfma_f32_16x16x32_bf16 v[86:89], v[182:185], v[218:221], v[86:89]
	v_mfma_f32_16x16x32_bf16 v[82:85], v[190:193], v[218:221], v[82:85]
	v_mfma_f32_16x16x32_bf16 v[70:73], v[182:185], v[226:229], v[70:73]
	v_mfma_f32_16x16x32_bf16 v[66:69], v[190:193], v[226:229], v[66:69]
	s_setprio 0
	s_barrier
; #define PG8_STAGE(bufoff, gbase, voff) do { _Pragma("unroll") for (int _i = 0; _i < 2; ++_i) \
;         __builtin_amdgcn_global_load_lds((const unsigned*)((const char*)(gbase) + (voff)[_i]), (PG8_LAS unsigned*)(lds + (bufoff) + ldsw + _i * 8192), 16, 0, 0); } while (0)
; #define PG8_LDA(dst, b, h) do { _Pragma("unroll") for (int m = 0; m < 4; ++m) _Pragma("unroll") for (int k = 0; k < 2; ++k) dst[m][k] = *(const PG8_LAS bf16x8*)(lds + PG8_SA(b, h) + aoff + m * 2048 + k * 1024); } while (0)
; #define PG8_LDB(dst, b, h) do { _Pragma("unroll") for (int n = 0; n < 2; ++n) _Pragma("unroll") for (int k = 0; k < 2; ++k) dst[n][k] = *(const PG8_LAS bf16x8*)(lds + PG8_SB(b, h) + boff + n * 2048 + k * 1024); } while (0)
; #define PG8_MMA(ai, bj, At, Bt) do { __builtin_amdgcn_s_setprio(1); _Pragma("unroll") for (int m = 0; m < 4; ++m) _Pragma("unroll") for (int n = 0; n < 2; ++n) _Pragma("unroll") for (int k = 0; k < 2; ++k) \
;         acc[ai][bj][m][n] = __builtin_amdgcn_mfma_f32_16x16x32_bf16(Bt[n][k], At[m][k], acc[ai][bj][m][n], 0, 0, 0); __builtin_amdgcn_s_setprio(0); } while (0)
; #define PG8_WAIT_V(n) asm volatile("s_waitcnt vmcnt(" #n ")" ::: "memory")
; #define PG8_WAIT_L(n) asm volatile("s_waitcnt lgkmcnt(" #n ")" ::: "memory")
; #define PG8_BAR __builtin_amdgcn_s_barrier()
; #define PG8_SCHED __builtin_amdgcn_sched_barrier(0)
; template <class Epi, class Sched, bool ALIGN_EPI = false, bool SP2 = false>
; __device__ __forceinline__ void gemm_phase(PG8_LAS unsigned char* lds, const Gemm g, const Sched& S, const Epi& E) {
;     ...
;             PG8_LDA(At, 0, 1); PG8_STAGE(PG8_SB(0, 0), b2, voffB); PG8_STAGE(PG8_SB(0, 1), b2 + hstepB, voffB); PG8_STAGE(PG8_SA(0, 0), a2, voffA);
;             PG8_WAIT_V(8); PG8_WAIT_L(0); PG8_BAR; PG8_MMA(1, 0, At, B0); PG8_MMA(1, 1, At, B1); PG8_BAR; PG8_SCHED;
;             PG8_LDB(B0, 1, 0); PG8_LDB(B1, 1, 1); PG8_SCHED; PG8_LDA(At, 1, 0); PG8_STAGE(PG8_SA(0, 1), a2 + hstepA, voffA);
	s_add_i32 s43, s56, s44
	v_lshl_add_u64 v[156:157], s[36:37], 0, v[132:133]
	s_mov_b32 m0, s43
	ds_read_b128 v[194:197], v160 offset:16384
	ds_read_b128 v[198:201], v160 offset:17408
	ds_read_b128 v[202:205], v160 offset:18432
	ds_read_b128 v[210:213], v160 offset:19456
	ds_read_b128 v[214:217], v160 offset:20480
	ds_read_b128 v[218:221], v160 offset:21504
	ds_read_b128 v[222:225], v160 offset:22528
	ds_read_b128 v[226:229], v160 offset:23552
	global_load_lds_dwordx4 v[156:157], off
	s_add_i32 m0, s43, 0x2000
	s_add_u32 s62, s36, 0x80000
	v_lshl_add_u64 v[206:207], s[36:37], 0, v[136:137]
	s_addc_u32 s63, s37, 0
	s_add_i32 s43, s57, s44
	global_load_lds_dwordx4 v[206:207], off
	v_lshl_add_u64 v[230:231], s[62:63], 0, v[132:133]
	s_mov_b32 m0, s43
	v_lshl_add_u64 v[232:233], s[38:39], 0, v[134:135]
	global_load_lds_dwordx4 v[230:231], off
	v_lshl_add_u64 v[230:231], s[62:63], 0, v[136:137]
	s_add_i32 m0, s43, 0x2000
	s_nop 0
	global_load_lds_dwordx4 v[230:231], off
	v_lshl_add_u64 v[230:231], s[38:39], 0, v[130:131]
	s_mov_b32 m0, s45
	s_nop 0
	global_load_lds_dwordx4 v[230:231], off
	s_mov_b32 m0, s46
	s_nop 0
	global_load_lds_dwordx4 v[232:233], off
	s_waitcnt vmcnt(8)
	s_waitcnt lgkmcnt(0)
	s_barrier
	s_setprio 1
	s_waitcnt lgkmcnt(0)
	v_mfma_f32_16x16x32_bf16 v[62:65], v[162:165], v[194:197], 0
	v_mfma_f32_16x16x32_bf16 v[58:61], v[170:173], v[194:197], 0
	v_mfma_f32_16x16x32_bf16 v[46:49], v[162:165], v[202:205], 0
	v_mfma_f32_16x16x32_bf16 v[42:45], v[170:173], v[202:205], 0
	v_mfma_f32_16x16x32_bf16 v[30:33], v[162:165], v[214:217], 0
	v_mfma_f32_16x16x32_bf16 v[26:29], v[170:173], v[214:217], 0
	v_mfma_f32_16x16x32_bf16 v[14:17], v[162:165], v[222:225], 0
	v_mfma_f32_16x16x32_bf16 v[10:13], v[170:173], v[222:225], 0
	v_mfma_f32_16x16x32_bf16 v[62:65], v[166:169], v[198:201], v[62:65]
	v_mfma_f32_16x16x32_bf16 v[58:61], v[174:177], v[198:201], v[58:61]
	v_mfma_f32_16x16x32_bf16 v[46:49], v[166:169], v[210:213], v[46:49]
	v_mfma_f32_16x16x32_bf16 v[42:45], v[174:177], v[210:213], v[42:45]
	v_mfma_f32_16x16x32_bf16 v[30:33], v[166:169], v[218:221], v[30:33]
	v_mfma_f32_16x16x32_bf16 v[26:29], v[174:177], v[218:221], v[26:29]
	v_mfma_f32_16x16x32_bf16 v[14:17], v[166:169], v[226:229], v[14:17]
	v_mfma_f32_16x16x32_bf16 v[10:13], v[174:177], v[226:229], v[10:13]
	s_setprio 0
	s_setprio 1
	v_mfma_f32_16x16x32_bf16 v[54:57], v[178:181], v[194:197], 0
	v_mfma_f32_16x16x32_bf16 v[50:53], v[186:189], v[194:197], 0
	v_mfma_f32_16x16x32_bf16 v[38:41], v[178:181], v[202:205], 0
	v_mfma_f32_16x16x32_bf16 v[34:37], v[186:189], v[202:205], 0
	v_mfma_f32_16x16x32_bf16 v[22:25], v[178:181], v[214:217], 0
	v_mfma_f32_16x16x32_bf16 v[18:21], v[186:189], v[214:217], 0
	v_mfma_f32_16x16x32_bf16 v[6:9], v[178:181], v[222:225], 0
	v_mfma_f32_16x16x32_bf16 v[2:5], v[186:189], v[222:225], 0
	v_mfma_f32_16x16x32_bf16 v[54:57], v[182:185], v[198:201], v[54:57]
	v_mfma_f32_16x16x32_bf16 v[50:53], v[190:193], v[198:201], v[50:53]
	v_mfma_f32_16x16x32_bf16 v[38:41], v[182:185], v[210:213], v[38:41]
	v_mfma_f32_16x16x32_bf16 v[34:37], v[190:193], v[210:213], v[34:37]
	v_mfma_f32_16x16x32_bf16 v[22:25], v[182:185], v[218:221], v[22:25]
	v_mfma_f32_16x16x32_bf16 v[18:21], v[190:193], v[218:221], v[18:21]
	v_mfma_f32_16x16x32_bf16 v[6:9], v[182:185], v[226:229], v[6:9]
	v_mfma_f32_16x16x32_bf16 v[2:5], v[190:193], v[226:229], v[2:5]
	s_setprio 0
	s_barrier
	s_add_i32 s43, 0, 0x18000
	v_add_u32_e32 v138, s43, v143
	s_add_i32 s61, 0, 0x1c000
	ds_read_b128 v[162:165], v138
	ds_read_b128 v[166:169], v138 offset:1024
	ds_read_b128 v[170:173], v138 offset:2048
	ds_read_b128 v[174:177], v138 offset:3072
	v_add_u32_e32 v138, s61, v143
	ds_read_b128 v[178:181], v138
	ds_read_b128 v[182:185], v138 offset:1024
	ds_read_b128 v[186:189], v138 offset:2048
	ds_read_b128 v[190:193], v138 offset:3072
	s_add_u32 s38, s38, 0x80000
	s_addc_u32 s39, s39, 0
	s_mov_b32 m0, s47
	v_lshl_add_u64 v[234:235], s[38:39], 0, v[130:131]
	ds_read_b128 v[194:197], v160 offset:32768
	ds_read_b128 v[198:201], v160 offset:33792
	ds_read_b128 v[202:205], v160 offset:34816
	ds_read_b128 v[210:213], v160 offset:35840
	ds_read_b128 v[214:217], v160 offset:36864
	ds_read_b128 v[218:221], v160 offset:37888
	ds_read_b128 v[222:225], v160 offset:38912
	ds_read_b128 v[226:229], v160 offset:39936
	global_load_lds_dwordx4 v[234:235], off
	v_lshl_add_u64 v[234:235], s[38:39], 0, v[134:135]
	s_mov_b32 m0, s48
	s_nop 0
	global_load_lds_dwordx4 v[234:235], off
	s_waitcnt vmcnt(8)
	s_waitcnt lgkmcnt(0)
	s_barrier
; #define PG8_STAGE(bufoff, gbase, voff) do { _Pragma("unroll") for (int _i = 0; _i < 2; ++_i) \
;         __builtin_amdgcn_global_load_lds((const unsigned*)((const char*)(gbase) + (voff)[_i]), (PG8_LAS unsigned*)(lds + (bufoff) + ldsw + _i * 8192), 16, 0, 0); } while (0)
; #define PG8_LDA(dst, b, h) do { _Pragma("unroll") for (int m = 0; m < 4; ++m) _Pragma("unroll") for (int k = 0; k < 2; ++k) dst[m][k] = *(const PG8_LAS bf16x8*)(lds + PG8_SA(b, h) + aoff + m * 2048 + k * 1024); } while (0)
; #define PG8_MMA(ai, bj, At, Bt) do { __builtin_amdgcn_s_setprio(1); _Pragma("unroll") for (int m = 0; m < 4; ++m) _Pragma("unroll") for (int n = 0; n < 2; ++n) _Pragma("unroll") for (int k = 0; k < 2; ++k) \
;         acc[ai][bj][m][n] = __builtin_amdgcn_mfma_f32_16x16x32_bf16(Bt[n][k], At[m][k], acc[ai][bj][m][n], 0, 0, 0); __builtin_amdgcn_s_setprio(0); } while (0)
; #define PG8_WAIT_V(n) asm volatile("s_waitcnt vmcnt(" #n ")" ::: "memory")
; #define PG8_WAIT_L(n) asm volatile("s_waitcnt lgkmcnt(" #n ")" ::: "memory")
; #define PG8_BAR __builtin_amdgcn_s_barrier()
; #define PG8_SCHED __builtin_amdgcn_sched_barrier(0)
; template <class Epi, class Sched, bool ALIGN_EPI = false, bool SP2 = false>
; __device__ __forceinline__ void gemm_phase(PG8_LAS unsigned char* lds, const Gemm g, const Sched& S, const Epi& E) {
;     ...
;             PG8_WAIT_V(8); PG8_WAIT_L(0); PG8_BAR; PG8_MMA(0, 0, At, B0); PG8_MMA(0, 1, At, B1); PG8_BAR; PG8_SCHED;
;             PG8_LDA(At, 1, 1); PG8_STAGE(PG8_SB(1, 0), b3, voffB); PG8_STAGE(PG8_SB(1, 1), b3 + hstepB, voffB); PG8_STAGE(PG8_SA(1, 0), a3, voffA);
;             PG8_WAIT_V(8); PG8_WAIT_L(0); PG8_BAR; PG8_MMA(1, 0, At, B0); PG8_MMA(1, 1, At, B1); PG8_BAR; PG8_SCHED;
	s_setprio 1
	s_waitcnt lgkmcnt(0)
	v_mfma_f32_16x16x32_bf16 v[126:129], v[162:165], v[194:197], v[126:129]
	v_mfma_f32_16x16x32_bf16 v[122:125], v[170:173], v[194:197], v[122:125]
	v_mfma_f32_16x16x32_bf16 v[110:113], v[162:165], v[202:205], v[110:113]
	v_mfma_f32_16x16x32_bf16 v[106:109], v[170:173], v[202:205], v[106:109]
	v_mfma_f32_16x16x32_bf16 v[94:97], v[162:165], v[214:217], v[94:97]
	v_mfma_f32_16x16x32_bf16 v[90:93], v[170:173], v[214:217], v[90:93]
	v_mfma_f32_16x16x32_bf16 v[78:81], v[162:165], v[222:225], v[78:81]
	v_mfma_f32_16x16x32_bf16 v[74:77], v[170:173], v[222:225], v[74:77]
	v_mfma_f32_16x16x32_bf16 v[126:129], v[166:169], v[198:201], v[126:129]
	v_mfma_f32_16x16x32_bf16 v[122:125], v[174:177], v[198:201], v[122:125]
	v_mfma_f32_16x16x32_bf16 v[110:113], v[166:169], v[210:213], v[110:113]
	v_mfma_f32_16x16x32_bf16 v[106:109], v[174:177], v[210:213], v[106:109]
	v_mfma_f32_16x16x32_bf16 v[94:97], v[166:169], v[218:221], v[94:97]
	v_mfma_f32_16x16x32_bf16 v[90:93], v[174:177], v[218:221], v[90:93]
	v_mfma_f32_16x16x32_bf16 v[78:81], v[166:169], v[226:229], v[78:81]
	v_mfma_f32_16x16x32_bf16 v[74:77], v[174:177], v[226:229], v[74:77]
	s_setprio 0
	s_setprio 1
	v_mfma_f32_16x16x32_bf16 v[118:121], v[178:181], v[194:197], v[118:121]
	v_mfma_f32_16x16x32_bf16 v[114:117], v[186:189], v[194:197], v[114:117]
	v_mfma_f32_16x16x32_bf16 v[102:105], v[178:181], v[202:205], v[102:105]
	v_mfma_f32_16x16x32_bf16 v[98:101], v[186:189], v[202:205], v[98:101]
	v_mfma_f32_16x16x32_bf16 v[86:89], v[178:181], v[214:217], v[86:89]
	v_mfma_f32_16x16x32_bf16 v[82:85], v[186:189], v[214:217], v[82:85]
	v_mfma_f32_16x16x32_bf16 v[70:73], v[178:181], v[222:225], v[70:73]
	v_mfma_f32_16x16x32_bf16 v[66:69], v[186:189], v[222:225], v[66:69]
	v_mfma_f32_16x16x32_bf16 v[118:121], v[182:185], v[198:201], v[118:121]
	v_mfma_f32_16x16x32_bf16 v[114:117], v[190:193], v[198:201], v[114:117]
	v_mfma_f32_16x16x32_bf16 v[102:105], v[182:185], v[210:213], v[102:105]
	v_mfma_f32_16x16x32_bf16 v[98:101], v[190:193], v[210:213], v[98:101]
	v_mfma_f32_16x16x32_bf16 v[86:89], v[182:185], v[218:221], v[86:89]
	v_mfma_f32_16x16x32_bf16 v[82:85], v[190:193], v[218:221], v[82:85]
	v_mfma_f32_16x16x32_bf16 v[70:73], v[182:185], v[226:229], v[70:73]
	v_mfma_f32_16x16x32_bf16 v[66:69], v[190:193], v[226:229], v[66:69]
	s_setprio 0
	s_barrier
	s_add_i32 s38, s43, s44
	v_lshl_add_u64 v[156:157], v[156:157], 0, s[20:21]
	s_mov_b32 m0, s38
	ds_read_b128 v[194:197], v160 offset:49152
	ds_read_b128 v[198:201], v160 offset:50176
	ds_read_b128 v[202:205], v160 offset:51200
	ds_read_b128 v[210:213], v160 offset:52224
	ds_read_b128 v[214:217], v160 offset:53248
	ds_read_b128 v[218:221], v160 offset:54272
	ds_read_b128 v[222:225], v160 offset:55296
	ds_read_b128 v[226:229], v160 offset:56320
	global_load_lds_dwordx4 v[156:157], off
	s_add_i32 m0, s38, 0x2000
	s_add_u32 s36, s36, 0x80080
	v_lshl_add_u64 v[156:157], v[206:207], 0, s[20:21]
	s_addc_u32 s37, s37, 0
	s_add_i32 s38, s61, s44
	global_load_lds_dwordx4 v[156:157], off
	v_lshl_add_u64 v[156:157], s[36:37], 0, v[132:133]
	s_mov_b32 m0, s38
	s_nop 0
	global_load_lds_dwordx4 v[156:157], off
	v_lshl_add_u64 v[156:157], s[36:37], 0, v[136:137]
	s_add_i32 m0, s38, 0x2000
	s_nop 0
	global_load_lds_dwordx4 v[156:157], off
	v_lshl_add_u64 v[156:157], v[230:231], 0, s[20:21]
	s_mov_b32 m0, s52
	s_nop 0
	global_load_lds_dwordx4 v[156:157], off
	v_lshl_add_u64 v[156:157], v[232:233], 0, s[20:21]
	s_mov_b32 m0, s53
	s_nop 0
	global_load_lds_dwordx4 v[156:157], off
	s_waitcnt vmcnt(8)
	s_waitcnt lgkmcnt(0)
	s_barrier
	s_setprio 1
	s_waitcnt lgkmcnt(0)
	v_mfma_f32_16x16x32_bf16 v[62:65], v[162:165], v[194:197], v[62:65]
	v_mfma_f32_16x16x32_bf16 v[58:61], v[170:173], v[194:197], v[58:61]
	v_mfma_f32_16x16x32_bf16 v[46:49], v[162:165], v[202:205], v[46:49]
	v_mfma_f32_16x16x32_bf16 v[42:45], v[170:173], v[202:205], v[42:45]
	v_mfma_f32_16x16x32_bf16 v[30:33], v[162:165], v[214:217], v[30:33]
	v_mfma_f32_16x16x32_bf16 v[26:29], v[170:173], v[214:217], v[26:29]
	v_mfma_f32_16x16x32_bf16 v[14:17], v[162:165], v[222:225], v[14:17]
	v_mfma_f32_16x16x32_bf16 v[10:13], v[170:173], v[222:225], v[10:13]
	v_mfma_f32_16x16x32_bf16 v[62:65], v[166:169], v[198:201], v[62:65]
	v_mfma_f32_16x16x32_bf16 v[58:61], v[174:177], v[198:201], v[58:61]
	v_mfma_f32_16x16x32_bf16 v[46:49], v[166:169], v[210:213], v[46:49]
	v_mfma_f32_16x16x32_bf16 v[42:45], v[174:177], v[210:213], v[42:45]
	v_mfma_f32_16x16x32_bf16 v[30:33], v[166:169], v[218:221], v[30:33]
	v_mfma_f32_16x16x32_bf16 v[26:29], v[174:177], v[218:221], v[26:29]
	v_mfma_f32_16x16x32_bf16 v[14:17], v[166:169], v[226:229], v[14:17]
	v_mfma_f32_16x16x32_bf16 v[10:13], v[174:177], v[226:229], v[10:13]
	s_setprio 0
	s_setprio 1
	v_mfma_f32_16x16x32_bf16 v[54:57], v[178:181], v[194:197], v[54:57]
	v_mfma_f32_16x16x32_bf16 v[50:53], v[186:189], v[194:197], v[50:53]
	v_mfma_f32_16x16x32_bf16 v[38:41], v[178:181], v[202:205], v[38:41]
	v_mfma_f32_16x16x32_bf16 v[34:37], v[186:189], v[202:205], v[34:37]
	v_mfma_f32_16x16x32_bf16 v[22:25], v[178:181], v[214:217], v[22:25]
	v_mfma_f32_16x16x32_bf16 v[18:21], v[186:189], v[214:217], v[18:21]
	v_mfma_f32_16x16x32_bf16 v[6:9], v[178:181], v[222:225], v[6:9]
	v_mfma_f32_16x16x32_bf16 v[2:5], v[186:189], v[222:225], v[2:5]
	v_mfma_f32_16x16x32_bf16 v[54:57], v[182:185], v[198:201], v[54:57]
	v_mfma_f32_16x16x32_bf16 v[50:53], v[190:193], v[198:201], v[50:53]
	v_mfma_f32_16x16x32_bf16 v[38:41], v[182:185], v[210:213], v[38:41]
	v_mfma_f32_16x16x32_bf16 v[34:37], v[190:193], v[210:213], v[34:37]
	v_mfma_f32_16x16x32_bf16 v[22:25], v[182:185], v[218:221], v[22:25]
	v_mfma_f32_16x16x32_bf16 v[18:21], v[190:193], v[218:221], v[18:21]
	v_mfma_f32_16x16x32_bf16 v[6:9], v[182:185], v[226:229], v[6:9]
	v_mfma_f32_16x16x32_bf16 v[2:5], v[190:193], v[226:229], v[2:5]
	s_setprio 0
	s_barrier
	s_add_i32 s42, s42, 2
	s_add_u32 s34, s34, 0x100
	s_addc_u32 s35, s35, 0
	s_add_u32 s40, s40, 0x100
	s_addc_u32 s41, s41, 0
	s_cmp_gt_u32 s42, 29
	s_cbranch_scc1 .Lpeel_exit_2
	.p2align 6

; #define PG8_STAGE(bufoff, gbase, voff) do { _Pragma("unroll") for (int _i = 0; _i < 2; ++_i) \
;         __builtin_amdgcn_global_load_lds((const unsigned*)((const char*)(gbase) + (voff)[_i]), (PG8_LAS unsigned*)(lds + (bufoff) + ldsw + _i * 8192), 16, 0, 0); } while (0)
; #define PG8_LDA(dst, b, h) do { _Pragma("unroll") for (int m = 0; m < 4; ++m) _Pragma("unroll") for (int k = 0; k < 2; ++k) dst[m][k] = *(const PG8_LAS bf16x8*)(lds + PG8_SA(b, h) + aoff + m * 2048 + k * 1024); } while (0)
; #define PG8_LDB(dst, b, h) do { _Pragma("unroll") for (int n = 0; n < 2; ++n) _Pragma("unroll") for (int k = 0; k < 2; ++k) dst[n][k] = *(const PG8_LAS bf16x8*)(lds + PG8_SB(b, h) + boff + n * 2048 + k * 1024); } while (0)
; #define PG8_MMA(ai, bj, At, Bt) do { __builtin_amdgcn_s_setprio(1); _Pragma("unroll") for (int m = 0; m < 4; ++m) _Pragma("unroll") for (int n = 0; n < 2; ++n) _Pragma("unroll") for (int k = 0; k < 2; ++k) \
;         acc[ai][bj][m][n] = __builtin_amdgcn_mfma_f32_16x16x32_bf16(Bt[n][k], At[m][k], acc[ai][bj][m][n], 0, 0, 0); __builtin_amdgcn_s_setprio(0); } while (0)
; #define PG8_WAIT_V(n) asm volatile("s_waitcnt vmcnt(" #n ")" ::: "memory")
; #define PG8_WAIT_L(n) asm volatile("s_waitcnt lgkmcnt(" #n ")" ::: "memory")
; #define PG8_BAR __builtin_amdgcn_s_barrier()
; #define PG8_SCHED __builtin_amdgcn_sched_barrier(0)
;     __host__ __device__ bool next(int i, Unit& u) const {
;         const long L = (long)i * G + c; if (L >= nwg) return false;
;         int wgid = (int)L; { const int q = nwg / NXCD, r = nwg % NXCD, xcd = wgid % NXCD, off = wgid / NXCD; wgid = (xcd < r ? xcd * (q + 1) : r * (q + 1) + (xcd - r) * q) + off; }
;         const int nig = WGM * nN, gid = wgid / nig, fm = gid * WGM, gsz = (nM - fm) < WGM ? (nM - fm) : WGM;
;         u.pm = fm + ((wgid % nig) % gsz); u.pn = (wgid % nig) / gsz; return true;
;     }
; template <class Epi, class Sched, bool ALIGN_EPI = false, bool SP2 = false>
; __device__ __forceinline__ void gemm_phase(PG8_LAS unsigned char* lds, const Gemm g, const Sched& S, const Epi& E) {
;     ...
;             PG8_LDB(B0, 0, 0); PG8_LDB(B1, 0, 1); PG8_SCHED; PG8_LDA(At, 0, 0); PG8_STAGE(PG8_SA(1, 1), a1 + hstepA, voffA);
;             PG8_WAIT_V(8); PG8_WAIT_L(0); PG8_BAR; PG8_MMA(0, 0, At, B0); PG8_MMA(0, 1, At, B1); PG8_BAR; PG8_SCHED;
.LBB0_799:
	s_mov_b32 s100, s38
	s_mov_b32 s101, s39
	s_mov_b32 s66, s40
	s_mov_b32 s67, s41
	s_add_u32 s38, s38, 0x80080
	s_addc_u32 s39, s39, 0
	s_add_u32 s63, s40, 0x100
	s_addc_u32 s64, s41, 0
	ds_read_b128 v[152:155], v148
	ds_read_b128 v[156:159], v148 offset:1024
	ds_read_b128 v[160:163], v148 offset:2048
	ds_read_b128 v[164:167], v148 offset:3072
	ds_read_b128 v[168:171], v149
	ds_read_b128 v[172:175], v149 offset:1024
	ds_read_b128 v[176:179], v149 offset:2048
	ds_read_b128 v[180:183], v149 offset:3072
	s_add_u32 s40, s38, 0xfff80080
	s_addc_u32 s41, s39, -1
	s_mov_b32 s43, s41
	s_mov_b32 s42, s40
	s_mov_b32 s41, s64
	s_mov_b32 s40, s63
	v_lshl_add_u64 v[218:219], s[38:39], 0, v[138:139]
	s_add_i32 m0, s27, 0xc000
	ds_read_b128 v[184:187], v150
	ds_read_b128 v[188:191], v150 offset:1024
	ds_read_b128 v[192:195], v150 offset:2048
	ds_read_b128 v[196:199], v150 offset:3072
	ds_read_b128 v[200:203], v150 offset:4096
	ds_read_b128 v[204:207], v150 offset:5120
	ds_read_b128 v[210:213], v150 offset:6144
	ds_read_b128 v[214:217], v150 offset:7168
	global_load_lds_dwordx4 v[218:219], off
	v_lshl_add_u64 v[218:219], s[38:39], 0, v[140:141]
	s_add_i32 m0, s27, 0xe000
	s_nop 0
	global_load_lds_dwordx4 v[218:219], off
	s_add_i32 s50, s50, 1
	s_mul_i32 s4, s50, s53
	s_mul_hi_u32 s5, s50, s33
	s_add_i32 s5, s5, s4
	s_mul_i32 s4, s50, s33
	s_add_u32 s34, s4, s70
	s_addc_u32 s35, s5, s45
	v_cmp_gt_i64_e32 vcc, s[34:35], v[144:145]
	v_cmp_lt_i64_e64 s[4:5], s[34:35], v[142:143]
	s_cbranch_vccnz .LBB0_801
	s_ashr_i32 s28, s34, 31
	s_lshr_b32 s28, s28, 29
	s_add_i32 s28, s34, s28
	s_ashr_i32 s29, s28, 3
	s_and_b32 s28, s28, -8
	s_sub_i32 s28, s34, s28
	s_cmp_lt_i32 s28, 0
	s_cselect_b32 s30, s46, 0xa0
	s_mul_i32 s28, s30, s28
	s_add_i32 s28, s28, s29
	s_ashr_i32 s29, s28, 31
	s_lshr_b32 s29, s29, 27
	s_add_i32 s29, s28, s29
	s_ashr_i32 s30, s29, 5
	s_lshl_b32 s30, s30, 2
	s_sub_i32 s31, 0xa0, s30
	s_min_i32 s31, s31, 4
	s_abs_i32 s34, s31
	v_cvt_f32_u32_e32 v2, s34
	s_sub_i32 s36, 0, s34
	s_andn2_b32 s29, s29, 31
	s_sub_i32 s29, s28, s29
	v_rcp_iflag_f32_e32 v2, v2
	s_abs_i32 s28, s29
	s_xor_b32 s35, s29, s31
	s_ashr_i32 s35, s35, 31
	v_mul_f32_e32 v2, 0x4f7ffffe, v2
	v_cvt_u32_f32_e32 v2, v2
	s_nop 0
	v_readfirstlane_b32 s37, v2
	s_mul_i32 s36, s36, s37
	s_mul_hi_u32 s36, s37, s36
	s_add_i32 s37, s37, s36
	s_mul_hi_u32 s36, s28, s37
	s_mul_i32 s37, s36, s34
	s_sub_i32 s28, s28, s37
	s_add_i32 s98, s36, 1
	s_sub_i32 s37, s28, s34
	s_cmp_ge_u32 s28, s34
	s_cselect_b32 s36, s98, s36
	s_cselect_b32 s28, s37, s28
	s_add_i32 s37, s36, 1
	s_cmp_ge_u32 s28, s34
	s_cselect_b32 s28, s37, s36
	s_xor_b32 s28, s28, s35
	s_sub_i32 s28, s28, s35
	s_mul_i32 s31, s28, s31
	s_sub_i32 s29, s29, s31
	s_add_i32 s30, s29, s30
.LBB0_801:
	s_ashr_i32 s31, s30, 31
	s_lshl_b64 s[34:35], s[30:31], 20
	s_add_u32 s34, s6, s34
	s_addc_u32 s35, s7, s35
	s_and_b64 s[36:37], s[4:5], exec
	s_cselect_b32 s31, s35, s101
	s_cselect_b32 s61, s34, s100
	s_ashr_i32 s29, s28, 31
	s_lshl_b64 s[36:37], s[28:29], 20
	s_add_u32 s36, s88, s36
	s_addc_u32 s37, s89, s37
	s_and_b64 s[98:99], s[4:5], exec
	s_cselect_b32 s29, s37, s67
	s_cselect_b32 s62, s36, s66
	s_mov_b32 s65, -2
	s_waitcnt vmcnt(8)
	s_waitcnt lgkmcnt(0)
	s_barrier
	s_setprio 1
	s_waitcnt lgkmcnt(0)
	v_mfma_f32_16x16x32_bf16 v[126:129], v[152:155], v[184:187], 0
	v_mfma_f32_16x16x32_bf16 v[122:125], v[160:163], v[184:187], 0
	v_mfma_f32_16x16x32_bf16 v[118:121], v[152:155], v[192:195], 0
	v_mfma_f32_16x16x32_bf16 v[114:117], v[160:163], v[192:195], 0
	v_mfma_f32_16x16x32_bf16 v[102:105], v[152:155], v[200:203], 0
	v_mfma_f32_16x16x32_bf16 v[98:101], v[160:163], v[200:203], 0
	v_mfma_f32_16x16x32_bf16 v[86:89], v[152:155], v[210:213], 0
	v_mfma_f32_16x16x32_bf16 v[82:85], v[160:163], v[210:213], 0
	v_mfma_f32_16x16x32_bf16 v[126:129], v[156:159], v[188:191], v[126:129]
	v_mfma_f32_16x16x32_bf16 v[122:125], v[164:167], v[188:191], v[122:125]
	v_mfma_f32_16x16x32_bf16 v[118:121], v[156:159], v[196:199], v[118:121]
	v_mfma_f32_16x16x32_bf16 v[114:117], v[164:167], v[196:199], v[114:117]
	v_mfma_f32_16x16x32_bf16 v[102:105], v[156:159], v[204:207], v[102:105]
	v_mfma_f32_16x16x32_bf16 v[98:101], v[164:167], v[204:207], v[98:101]
	v_mfma_f32_16x16x32_bf16 v[86:89], v[156:159], v[214:217], v[86:89]
	v_mfma_f32_16x16x32_bf16 v[82:85], v[164:167], v[214:217], v[82:85]
	s_setprio 0
	s_setprio 1
	v_mfma_f32_16x16x32_bf16 v[110:113], v[168:171], v[184:187], 0
	v_mfma_f32_16x16x32_bf16 v[106:109], v[176:179], v[184:187], 0
	v_mfma_f32_16x16x32_bf16 v[94:97], v[168:171], v[192:195], 0
	v_mfma_f32_16x16x32_bf16 v[90:93], v[176:179], v[192:195], 0
	v_mfma_f32_16x16x32_bf16 v[78:81], v[168:171], v[200:203], 0
	v_mfma_f32_16x16x32_bf16 v[74:77], v[176:179], v[200:203], 0
	v_mfma_f32_16x16x32_bf16 v[70:73], v[168:171], v[210:213], 0
	v_mfma_f32_16x16x32_bf16 v[66:69], v[176:179], v[210:213], 0
	v_mfma_f32_16x16x32_bf16 v[110:113], v[172:175], v[188:191], v[110:113]
	v_mfma_f32_16x16x32_bf16 v[106:109], v[180:183], v[188:191], v[106:109]
	v_mfma_f32_16x16x32_bf16 v[94:97], v[172:175], v[196:199], v[94:97]
	v_mfma_f32_16x16x32_bf16 v[90:93], v[180:183], v[196:199], v[90:93]
	v_mfma_f32_16x16x32_bf16 v[78:81], v[172:175], v[204:207], v[78:81]
	v_mfma_f32_16x16x32_bf16 v[74:77], v[180:183], v[204:207], v[74:77]
	v_mfma_f32_16x16x32_bf16 v[70:73], v[172:175], v[214:217], v[70:73]
	v_mfma_f32_16x16x32_bf16 v[66:69], v[180:183], v[214:217], v[66:69]
	s_setprio 0
	s_barrier
; #define PG8_STAGE(bufoff, gbase, voff) do { _Pragma("unroll") for (int _i = 0; _i < 2; ++_i) \
;         __builtin_amdgcn_global_load_lds((const unsigned*)((const char*)(gbase) + (voff)[_i]), (PG8_LAS unsigned*)(lds + (bufoff) + ldsw + _i * 8192), 16, 0, 0); } while (0)
; #define PG8_LDA(dst, b, h) do { _Pragma("unroll") for (int m = 0; m < 4; ++m) _Pragma("unroll") for (int k = 0; k < 2; ++k) dst[m][k] = *(const PG8_LAS bf16x8*)(lds + PG8_SA(b, h) + aoff + m * 2048 + k * 1024); } while (0)
; #define PG8_LDB(dst, b, h) do { _Pragma("unroll") for (int n = 0; n < 2; ++n) _Pragma("unroll") for (int k = 0; k < 2; ++k) dst[n][k] = *(const PG8_LAS bf16x8*)(lds + PG8_SB(b, h) + boff + n * 2048 + k * 1024); } while (0)
; #define PG8_MMA(ai, bj, At, Bt) do { __builtin_amdgcn_s_setprio(1); _Pragma("unroll") for (int m = 0; m < 4; ++m) _Pragma("unroll") for (int n = 0; n < 2; ++n) _Pragma("unroll") for (int k = 0; k < 2; ++k) \
;         acc[ai][bj][m][n] = __builtin_amdgcn_mfma_f32_16x16x32_bf16(Bt[n][k], At[m][k], acc[ai][bj][m][n], 0, 0, 0); __builtin_amdgcn_s_setprio(0); } while (0)
; #define PG8_WAIT_V(n) asm volatile("s_waitcnt vmcnt(" #n ")" ::: "memory")
; #define PG8_WAIT_L(n) asm volatile("s_waitcnt lgkmcnt(" #n ")" ::: "memory")
; #define PG8_BAR __builtin_amdgcn_s_barrier()
; #define PG8_SCHED __builtin_amdgcn_sched_barrier(0)
; template <class Epi, class Sched, bool ALIGN_EPI = false, bool SP2 = false>
; __device__ __forceinline__ void gemm_phase(PG8_LAS unsigned char* lds, const Gemm g, const Sched& S, const Epi& E) {
;     ...
;             PG8_LDA(At, 0, 1); PG8_STAGE(PG8_SB(0, 0), b2, voffB); PG8_STAGE(PG8_SB(0, 1), b2 + hstepB, voffB); PG8_STAGE(PG8_SA(0, 0), a2, voffA);
;             PG8_WAIT_V(8); PG8_WAIT_L(0); PG8_BAR; PG8_MMA(1, 0, At, B0); PG8_MMA(1, 1, At, B1); PG8_BAR; PG8_SCHED;
;             PG8_LDB(B0, 1, 0); PG8_LDB(B1, 1, 1); PG8_SCHED; PG8_LDA(At, 1, 0); PG8_STAGE(PG8_SA(0, 1), a2 + hstepA, voffA);
	s_add_i32 s66, s54, s44
	v_lshl_add_u64 v[218:219], s[40:41], 0, v[134:135]
	s_mov_b32 m0, s66
	ds_read_b128 v[184:187], v150 offset:16384
	ds_read_b128 v[188:191], v150 offset:17408
	ds_read_b128 v[192:195], v150 offset:18432
	ds_read_b128 v[196:199], v150 offset:19456
	ds_read_b128 v[200:203], v150 offset:20480
	ds_read_b128 v[204:207], v150 offset:21504
	ds_read_b128 v[210:213], v150 offset:22528
	ds_read_b128 v[214:217], v150 offset:23552
	global_load_lds_dwordx4 v[218:219], off
	s_add_i32 m0, s66, 0x2000
	s_add_u32 s66, s40, 0x80000
	v_lshl_add_u64 v[220:221], s[40:41], 0, v[130:131]
	s_addc_u32 s67, s41, 0
	s_add_i32 s68, s55, s44
	global_load_lds_dwordx4 v[220:221], off
	v_lshl_add_u64 v[222:223], s[66:67], 0, v[134:135]
	s_mov_b32 m0, s68
	v_lshl_add_u64 v[224:225], s[42:43], 0, v[132:133]
	global_load_lds_dwordx4 v[222:223], off
	v_lshl_add_u64 v[222:223], s[66:67], 0, v[130:131]
	s_add_i32 m0, s68, 0x2000
	s_nop 0
	global_load_lds_dwordx4 v[222:223], off
	v_lshl_add_u64 v[222:223], s[42:43], 0, v[136:137]
	s_mov_b32 m0, s27
	s_nop 0
	global_load_lds_dwordx4 v[222:223], off
	s_mov_b32 m0, s47
	s_nop 0
	global_load_lds_dwordx4 v[224:225], off
	s_waitcnt vmcnt(8)
	s_waitcnt lgkmcnt(0)
	s_barrier
	s_setprio 1
	s_waitcnt lgkmcnt(0)
	v_mfma_f32_16x16x32_bf16 v[62:65], v[152:155], v[184:187], 0
	v_mfma_f32_16x16x32_bf16 v[58:61], v[160:163], v[184:187], 0
	v_mfma_f32_16x16x32_bf16 v[54:57], v[152:155], v[192:195], 0
	v_mfma_f32_16x16x32_bf16 v[50:53], v[160:163], v[192:195], 0
	v_mfma_f32_16x16x32_bf16 v[38:41], v[152:155], v[200:203], 0
	v_mfma_f32_16x16x32_bf16 v[34:37], v[160:163], v[200:203], 0
	v_mfma_f32_16x16x32_bf16 v[22:25], v[152:155], v[210:213], 0
	v_mfma_f32_16x16x32_bf16 v[18:21], v[160:163], v[210:213], 0
	v_mfma_f32_16x16x32_bf16 v[62:65], v[156:159], v[188:191], v[62:65]
	v_mfma_f32_16x16x32_bf16 v[58:61], v[164:167], v[188:191], v[58:61]
	v_mfma_f32_16x16x32_bf16 v[54:57], v[156:159], v[196:199], v[54:57]
	v_mfma_f32_16x16x32_bf16 v[50:53], v[164:167], v[196:199], v[50:53]
	v_mfma_f32_16x16x32_bf16 v[38:41], v[156:159], v[204:207], v[38:41]
	v_mfma_f32_16x16x32_bf16 v[34:37], v[164:167], v[204:207], v[34:37]
	v_mfma_f32_16x16x32_bf16 v[22:25], v[156:159], v[214:217], v[22:25]
	v_mfma_f32_16x16x32_bf16 v[18:21], v[164:167], v[214:217], v[18:21]
	s_setprio 0
	s_setprio 1
	v_mfma_f32_16x16x32_bf16 v[46:49], v[168:171], v[184:187], 0
	v_mfma_f32_16x16x32_bf16 v[42:45], v[176:179], v[184:187], 0
	v_mfma_f32_16x16x32_bf16 v[30:33], v[168:171], v[192:195], 0
	v_mfma_f32_16x16x32_bf16 v[26:29], v[176:179], v[192:195], 0
	v_mfma_f32_16x16x32_bf16 v[14:17], v[168:171], v[200:203], 0
	v_mfma_f32_16x16x32_bf16 v[10:13], v[176:179], v[200:203], 0
	v_mfma_f32_16x16x32_bf16 v[6:9], v[168:171], v[210:213], 0
	v_mfma_f32_16x16x32_bf16 v[2:5], v[176:179], v[210:213], 0
	v_mfma_f32_16x16x32_bf16 v[46:49], v[172:175], v[188:191], v[46:49]
	v_mfma_f32_16x16x32_bf16 v[42:45], v[180:183], v[188:191], v[42:45]
	v_mfma_f32_16x16x32_bf16 v[30:33], v[172:175], v[196:199], v[30:33]
	v_mfma_f32_16x16x32_bf16 v[26:29], v[180:183], v[196:199], v[26:29]
	v_mfma_f32_16x16x32_bf16 v[14:17], v[172:175], v[204:207], v[14:17]
	v_mfma_f32_16x16x32_bf16 v[10:13], v[180:183], v[204:207], v[10:13]
	v_mfma_f32_16x16x32_bf16 v[6:9], v[172:175], v[214:217], v[6:9]
	v_mfma_f32_16x16x32_bf16 v[2:5], v[180:183], v[214:217], v[2:5]
	s_setprio 0
	s_barrier
	s_add_i32 s66, 0, 0x18000
	v_add_u32_e32 v151, s66, v146
	s_add_i32 s67, 0, 0x1c000
	ds_read_b128 v[152:155], v151
	ds_read_b128 v[156:159], v151 offset:1024
	ds_read_b128 v[160:163], v151 offset:2048
	ds_read_b128 v[164:167], v151 offset:3072
	v_add_u32_e32 v151, s67, v146
	ds_read_b128 v[168:171], v151
	ds_read_b128 v[172:175], v151 offset:1024
	ds_read_b128 v[176:179], v151 offset:2048
	ds_read_b128 v[180:183], v151 offset:3072
	s_add_u32 s42, s42, 0x80000
	s_addc_u32 s43, s43, 0
	s_mov_b32 m0, s48
	v_lshl_add_u64 v[226:227], s[42:43], 0, v[136:137]
	ds_read_b128 v[184:187], v150 offset:32768
	ds_read_b128 v[188:191], v150 offset:33792
	ds_read_b128 v[192:195], v150 offset:34816
	ds_read_b128 v[196:199], v150 offset:35840
	ds_read_b128 v[200:203], v150 offset:36864
	ds_read_b128 v[204:207], v150 offset:37888
	ds_read_b128 v[210:213], v150 offset:38912
	ds_read_b128 v[214:217], v150 offset:39936
	global_load_lds_dwordx4 v[226:227], off
	v_lshl_add_u64 v[226:227], s[42:43], 0, v[132:133]
	s_mov_b32 m0, s49
	s_nop 0
	global_load_lds_dwordx4 v[226:227], off
	s_waitcnt vmcnt(8)
	s_waitcnt lgkmcnt(0)
	s_barrier
; #define PG8_STAGE(bufoff, gbase, voff) do { _Pragma("unroll") for (int _i = 0; _i < 2; ++_i) \
;         __builtin_amdgcn_global_load_lds((const unsigned*)((const char*)(gbase) + (voff)[_i]), (PG8_LAS unsigned*)(lds + (bufoff) + ldsw + _i * 8192), 16, 0, 0); } while (0)
; #define PG8_LDA(dst, b, h) do { _Pragma("unroll") for (int m = 0; m < 4; ++m) _Pragma("unroll") for (int k = 0; k < 2; ++k) dst[m][k] = *(const PG8_LAS bf16x8*)(lds + PG8_SA(b, h) + aoff + m * 2048 + k * 1024); } while (0)
; #define PG8_MMA(ai, bj, At, Bt) do { __builtin_amdgcn_s_setprio(1); _Pragma("unroll") for (int m = 0; m < 4; ++m) _Pragma("unroll") for (int n = 0; n < 2; ++n) _Pragma("unroll") for (int k = 0; k < 2; ++k) \
;         acc[ai][bj][m][n] = __builtin_amdgcn_mfma_f32_16x16x32_bf16(Bt[n][k], At[m][k], acc[ai][bj][m][n], 0, 0, 0); __builtin_amdgcn_s_setprio(0); } while (0)
; #define PG8_WAIT_V(n) asm volatile("s_waitcnt vmcnt(" #n ")" ::: "memory")
; #define PG8_WAIT_L(n) asm volatile("s_waitcnt lgkmcnt(" #n ")" ::: "memory")
; #define PG8_BAR __builtin_amdgcn_s_barrier()
; #define PG8_SCHED __builtin_amdgcn_sched_barrier(0)
; template <class Epi, class Sched, bool ALIGN_EPI = false, bool SP2 = false>
; __device__ __forceinline__ void gemm_phase(PG8_LAS unsigned char* lds, const Gemm g, const Sched& S, const Epi& E) {
;     ...
;             PG8_WAIT_V(8); PG8_WAIT_L(0); PG8_BAR; PG8_MMA(0, 0, At, B0); PG8_MMA(0, 1, At, B1); PG8_BAR; PG8_SCHED;
;             PG8_LDA(At, 1, 1); PG8_STAGE(PG8_SB(1, 0), b3, voffB); PG8_STAGE(PG8_SB(1, 1), b3 + hstepB, voffB); PG8_STAGE(PG8_SA(1, 0), a3, voffA);
;             PG8_WAIT_V(8); PG8_WAIT_L(0); PG8_BAR; PG8_MMA(1, 0, At, B0); PG8_MMA(1, 1, At, B1); PG8_BAR; PG8_SCHED;
	s_setprio 1
	s_waitcnt lgkmcnt(0)
	v_mfma_f32_16x16x32_bf16 v[126:129], v[152:155], v[184:187], v[126:129]
	v_mfma_f32_16x16x32_bf16 v[122:125], v[160:163], v[184:187], v[122:125]
	v_mfma_f32_16x16x32_bf16 v[118:121], v[152:155], v[192:195], v[118:121]
	v_mfma_f32_16x16x32_bf16 v[114:117], v[160:163], v[192:195], v[114:117]
	v_mfma_f32_16x16x32_bf16 v[102:105], v[152:155], v[200:203], v[102:105]
	v_mfma_f32_16x16x32_bf16 v[98:101], v[160:163], v[200:203], v[98:101]
	v_mfma_f32_16x16x32_bf16 v[86:89], v[152:155], v[210:213], v[86:89]
	v_mfma_f32_16x16x32_bf16 v[82:85], v[160:163], v[210:213], v[82:85]
	v_mfma_f32_16x16x32_bf16 v[126:129], v[156:159], v[188:191], v[126:129]
	v_mfma_f32_16x16x32_bf16 v[122:125], v[164:167], v[188:191], v[122:125]
	v_mfma_f32_16x16x32_bf16 v[118:121], v[156:159], v[196:199], v[118:121]
	v_mfma_f32_16x16x32_bf16 v[114:117], v[164:167], v[196:199], v[114:117]
	v_mfma_f32_16x16x32_bf16 v[102:105], v[156:159], v[204:207], v[102:105]
	v_mfma_f32_16x16x32_bf16 v[98:101], v[164:167], v[204:207], v[98:101]
	v_mfma_f32_16x16x32_bf16 v[86:89], v[156:159], v[214:217], v[86:89]
	v_mfma_f32_16x16x32_bf16 v[82:85], v[164:167], v[214:217], v[82:85]
	s_setprio 0
	s_setprio 1
	v_mfma_f32_16x16x32_bf16 v[110:113], v[168:171], v[184:187], v[110:113]
	v_mfma_f32_16x16x32_bf16 v[106:109], v[176:179], v[184:187], v[106:109]
	v_mfma_f32_16x16x32_bf16 v[94:97], v[168:171], v[192:195], v[94:97]
	v_mfma_f32_16x16x32_bf16 v[90:93], v[176:179], v[192:195], v[90:93]
	v_mfma_f32_16x16x32_bf16 v[78:81], v[168:171], v[200:203], v[78:81]
	v_mfma_f32_16x16x32_bf16 v[74:77], v[176:179], v[200:203], v[74:77]
	v_mfma_f32_16x16x32_bf16 v[70:73], v[168:171], v[210:213], v[70:73]
	v_mfma_f32_16x16x32_bf16 v[66:69], v[176:179], v[210:213], v[66:69]
	v_mfma_f32_16x16x32_bf16 v[110:113], v[172:175], v[188:191], v[110:113]
	v_mfma_f32_16x16x32_bf16 v[106:109], v[180:183], v[188:191], v[106:109]
	v_mfma_f32_16x16x32_bf16 v[94:97], v[172:175], v[196:199], v[94:97]
	v_mfma_f32_16x16x32_bf16 v[90:93], v[180:183], v[196:199], v[90:93]
	v_mfma_f32_16x16x32_bf16 v[78:81], v[172:175], v[204:207], v[78:81]
	v_mfma_f32_16x16x32_bf16 v[74:77], v[180:183], v[204:207], v[74:77]
	v_mfma_f32_16x16x32_bf16 v[70:73], v[172:175], v[214:217], v[70:73]
	v_mfma_f32_16x16x32_bf16 v[66:69], v[180:183], v[214:217], v[66:69]
	s_setprio 0
	s_barrier
	s_add_i32 s42, s66, s44
	v_lshl_add_u64 v[218:219], v[218:219], 0, s[10:11]
	s_mov_b32 m0, s42
	ds_read_b128 v[184:187], v150 offset:49152
	ds_read_b128 v[188:191], v150 offset:50176
	ds_read_b128 v[192:195], v150 offset:51200
	ds_read_b128 v[196:199], v150 offset:52224
	ds_read_b128 v[200:203], v150 offset:53248
	ds_read_b128 v[204:207], v150 offset:54272
	ds_read_b128 v[210:213], v150 offset:55296
	ds_read_b128 v[214:217], v150 offset:56320
	global_load_lds_dwordx4 v[218:219], off
	s_add_i32 m0, s42, 0x2000
	s_add_u32 s40, s40, 0x80080
	v_lshl_add_u64 v[218:219], v[220:221], 0, s[10:11]
	s_addc_u32 s41, s41, 0
	s_add_i32 s42, s67, s44
	global_load_lds_dwordx4 v[218:219], off
	v_lshl_add_u64 v[218:219], s[40:41], 0, v[134:135]
	s_mov_b32 m0, s42
	s_nop 0
	global_load_lds_dwordx4 v[218:219], off
	v_lshl_add_u64 v[218:219], s[40:41], 0, v[130:131]
	s_add_i32 m0, s42, 0x2000
	s_nop 0
	global_load_lds_dwordx4 v[218:219], off
	v_lshl_add_u64 v[218:219], v[222:223], 0, s[10:11]
	s_mov_b32 m0, s51
	s_nop 0
	global_load_lds_dwordx4 v[218:219], off
	v_lshl_add_u64 v[218:219], v[224:225], 0, s[10:11]
	s_mov_b32 m0, s52
	s_nop 0
	global_load_lds_dwordx4 v[218:219], off
	s_waitcnt vmcnt(8)
	s_waitcnt lgkmcnt(0)
	s_barrier
	s_setprio 1
	s_waitcnt lgkmcnt(0)
	v_mfma_f32_16x16x32_bf16 v[62:65], v[152:155], v[184:187], v[62:65]
	v_mfma_f32_16x16x32_bf16 v[58:61], v[160:163], v[184:187], v[58:61]
	v_mfma_f32_16x16x32_bf16 v[54:57], v[152:155], v[192:195], v[54:57]
	v_mfma_f32_16x16x32_bf16 v[50:53], v[160:163], v[192:195], v[50:53]
	v_mfma_f32_16x16x32_bf16 v[38:41], v[152:155], v[200:203], v[38:41]
	v_mfma_f32_16x16x32_bf16 v[34:37], v[160:163], v[200:203], v[34:37]
	v_mfma_f32_16x16x32_bf16 v[22:25], v[152:155], v[210:213], v[22:25]
	v_mfma_f32_16x16x32_bf16 v[18:21], v[160:163], v[210:213], v[18:21]
	v_mfma_f32_16x16x32_bf16 v[62:65], v[156:159], v[188:191], v[62:65]
	v_mfma_f32_16x16x32_bf16 v[58:61], v[164:167], v[188:191], v[58:61]
	v_mfma_f32_16x16x32_bf16 v[54:57], v[156:159], v[196:199], v[54:57]
	v_mfma_f32_16x16x32_bf16 v[50:53], v[164:167], v[196:199], v[50:53]
	v_mfma_f32_16x16x32_bf16 v[38:41], v[156:159], v[204:207], v[38:41]
	v_mfma_f32_16x16x32_bf16 v[34:37], v[164:167], v[204:207], v[34:37]
	v_mfma_f32_16x16x32_bf16 v[22:25], v[156:159], v[214:217], v[22:25]
	v_mfma_f32_16x16x32_bf16 v[18:21], v[164:167], v[214:217], v[18:21]
	s_setprio 0
	s_setprio 1
	v_mfma_f32_16x16x32_bf16 v[46:49], v[168:171], v[184:187], v[46:49]
	v_mfma_f32_16x16x32_bf16 v[42:45], v[176:179], v[184:187], v[42:45]
	v_mfma_f32_16x16x32_bf16 v[30:33], v[168:171], v[192:195], v[30:33]
	v_mfma_f32_16x16x32_bf16 v[26:29], v[176:179], v[192:195], v[26:29]
	v_mfma_f32_16x16x32_bf16 v[14:17], v[168:171], v[200:203], v[14:17]
	v_mfma_f32_16x16x32_bf16 v[10:13], v[176:179], v[200:203], v[10:13]
	v_mfma_f32_16x16x32_bf16 v[6:9], v[168:171], v[210:213], v[6:9]
	v_mfma_f32_16x16x32_bf16 v[2:5], v[176:179], v[210:213], v[2:5]
	v_mfma_f32_16x16x32_bf16 v[46:49], v[172:175], v[188:191], v[46:49]
	v_mfma_f32_16x16x32_bf16 v[42:45], v[180:183], v[188:191], v[42:45]
	v_mfma_f32_16x16x32_bf16 v[30:33], v[172:175], v[196:199], v[30:33]
	v_mfma_f32_16x16x32_bf16 v[26:29], v[180:183], v[196:199], v[26:29]
	v_mfma_f32_16x16x32_bf16 v[14:17], v[172:175], v[204:207], v[14:17]
	v_mfma_f32_16x16x32_bf16 v[10:13], v[180:183], v[204:207], v[10:13]
	v_mfma_f32_16x16x32_bf16 v[6:9], v[172:175], v[214:217], v[6:9]
	v_mfma_f32_16x16x32_bf16 v[2:5], v[180:183], v[214:217], v[2:5]
	s_setprio 0
	s_barrier
	s_add_i32 s65, s65, 2
	s_add_u32 s38, s38, 0x100
	s_addc_u32 s39, s39, 0
	s_add_u32 s63, s63, 0x100
	s_addc_u32 s64, s64, 0
	s_cmp_gt_u32 s65, 29
	s_cbranch_scc1 .Lpeel_exit_6
	.p2align 6

; #define PG8_STAGE(bufoff, gbase, voff) do { _Pragma("unroll") for (int _i = 0; _i < 2; ++_i) \
;         __builtin_amdgcn_global_load_lds((const unsigned*)((const char*)(gbase) + (voff)[_i]), (PG8_LAS unsigned*)(lds + (bufoff) + ldsw + _i * 8192), 16, 0, 0); } while (0)
; #define PG8_LDA(dst, b, h) do { _Pragma("unroll") for (int m = 0; m < 4; ++m) _Pragma("unroll") for (int k = 0; k < 2; ++k) dst[m][k] = *(const PG8_LAS bf16x8*)(lds + PG8_SA(b, h) + aoff + m * 2048 + k * 1024); } while (0)
; #define PG8_LDB(dst, b, h) do { _Pragma("unroll") for (int n = 0; n < 2; ++n) _Pragma("unroll") for (int k = 0; k < 2; ++k) dst[n][k] = *(const PG8_LAS bf16x8*)(lds + PG8_SB(b, h) + boff + n * 2048 + k * 1024); } while (0)
; #define PG8_MMA(ai, bj, At, Bt) do { __builtin_amdgcn_s_setprio(1); _Pragma("unroll") for (int m = 0; m < 4; ++m) _Pragma("unroll") for (int n = 0; n < 2; ++n) _Pragma("unroll") for (int k = 0; k < 2; ++k) \
;         acc[ai][bj][m][n] = __builtin_amdgcn_mfma_f32_16x16x32_bf16(Bt[n][k], At[m][k], acc[ai][bj][m][n], 0, 0, 0); __builtin_amdgcn_s_setprio(0); } while (0)
; #define PG8_WAIT_V(n) asm volatile("s_waitcnt vmcnt(" #n ")" ::: "memory")
; #define PG8_WAIT_L(n) asm volatile("s_waitcnt lgkmcnt(" #n ")" ::: "memory")
; #define PG8_BAR __builtin_amdgcn_s_barrier()
; #define PG8_SCHED __builtin_amdgcn_sched_barrier(0)
;     __host__ __device__ bool next(int i, Unit& u) const {
;         const long L = (long)i * G + c; if (L >= nwg) return false;
;         int wgid = (int)L; { const int q = nwg / NXCD, r = nwg % NXCD, xcd = wgid % NXCD, off = wgid / NXCD; wgid = (xcd < r ? xcd * (q + 1) : r * (q + 1) + (xcd - r) * q) + off; }
;         const int nig = WGM * nN, gid = wgid / nig, fm = gid * WGM, gsz = (nM - fm) < WGM ? (nM - fm) : WGM;
;         u.pm = fm + ((wgid % nig) % gsz); u.pn = (wgid % nig) / gsz; return true;
;     }
; template <class Epi, class Sched, bool ALIGN_EPI = false, bool SP2 = false>
; __device__ __forceinline__ void gemm_phase(PG8_LAS unsigned char* lds, const Gemm g, const Sched& S, const Epi& E) {
;     ...
;             PG8_LDB(B0, 0, 0); PG8_LDB(B1, 0, 1); PG8_SCHED; PG8_LDA(At, 0, 0); PG8_STAGE(PG8_SA(1, 1), a1 + hstepA, voffA);
;             PG8_WAIT_V(8); PG8_WAIT_L(0); PG8_BAR; PG8_MMA(0, 0, At, B0); PG8_MMA(0, 1, At, B1); PG8_BAR; PG8_SCHED;
.LBB0_937:
	s_mov_b32 s100, s26
	s_mov_b32 s101, s27
	s_mov_b32 s53, s28
	s_mov_b32 s54, s29
	s_add_u32 s26, s26, 0x80080
	s_addc_u32 s27, s27, 0
	s_add_u32 s50, s28, 0x100
	s_addc_u32 s51, s29, 0
	ds_read_b128 v[154:157], v150
	ds_read_b128 v[158:161], v150 offset:1024
	ds_read_b128 v[162:165], v150 offset:2048
	ds_read_b128 v[166:169], v150 offset:3072
	ds_read_b128 v[170:173], v151
	ds_read_b128 v[174:177], v151 offset:1024
	ds_read_b128 v[178:181], v151 offset:2048
	ds_read_b128 v[182:185], v151 offset:3072
	s_add_u32 s28, s26, 0xfff80080
	s_addc_u32 s29, s27, -1
	s_mov_b32 s31, s29
	s_mov_b32 s30, s28
	s_mov_b32 s29, s51
	s_mov_b32 s28, s50
	v_lshl_add_u64 v[146:147], s[26:27], 0, v[138:139]
	s_add_i32 m0, s25, 0xc000
	ds_read_b128 v[186:189], v152
	ds_read_b128 v[190:193], v152 offset:1024
	ds_read_b128 v[194:197], v152 offset:2048
	ds_read_b128 v[198:201], v152 offset:3072
	ds_read_b128 v[202:205], v152 offset:4096
	ds_read_b128 v[210:213], v152 offset:5120
	ds_read_b128 v[214:217], v152 offset:6144
	ds_read_b128 v[218:221], v152 offset:7168
	global_load_lds_dwordx4 v[146:147], off
	v_lshl_add_u64 v[146:147], s[26:27], 0, v[140:141]
	s_add_i32 m0, s25, 0xe000
	s_nop 0
	global_load_lds_dwordx4 v[146:147], off
	s_add_i32 s40, s40, 1
	s_mul_i32 s4, s40, s43
	s_mul_hi_u32 s5, s40, s33
	s_add_i32 s5, s5, s4
	s_mul_i32 s4, s40, s33
	s_add_u32 s14, s4, s70
	s_addc_u32 s15, s5, s35
	v_cmp_gt_i64_e32 vcc, s[14:15], v[144:145]
	v_cmp_lt_i64_e64 s[4:5], s[14:15], v[142:143]
	s_cbranch_vccnz .LBB0_939
	s_ashr_i32 s10, s14, 31
	s_lshr_b32 s10, s10, 29
	s_add_i32 s10, s14, s10
	s_ashr_i32 s11, s10, 3
	s_and_b32 s10, s10, -8
	s_sub_i32 s10, s14, s10
	s_cmp_lt_i32 s10, 0
	s_cselect_b32 s12, s36, 0x370
	s_mul_i32 s10, s12, s10
	s_add_i32 s10, s10, s11
	s_mul_hi_i32 s11, s10, 0x2e8ba2e9
	s_lshr_b32 s12, s11, 31
	s_ashr_i32 s11, s11, 5
	s_add_i32 s11, s11, s12
	s_lshl_b32 s12, s11, 2
	s_sub_i32 s13, 0xa0, s12
	s_min_i32 s13, s13, 4
	s_abs_i32 s14, s13
	v_cvt_f32_u32_e32 v2, s14
	s_sub_i32 s16, 0, s14
	s_mulk_i32 s11, 0xb0
	s_sub_i32 s11, s10, s11
	v_rcp_iflag_f32_e32 v2, v2
	s_abs_i32 s10, s11
	s_xor_b32 s15, s11, s13
	s_ashr_i32 s15, s15, 31
	v_mul_f32_e32 v2, 0x4f7ffffe, v2
	v_cvt_u32_f32_e32 v2, v2
	s_nop 0
	v_readfirstlane_b32 s17, v2
	s_mul_i32 s16, s16, s17
	s_mul_hi_u32 s16, s17, s16
	s_add_i32 s17, s17, s16
	s_mul_hi_u32 s16, s10, s17
	s_mul_i32 s17, s16, s14
	s_sub_i32 s10, s10, s17
	s_add_i32 s98, s16, 1
	s_sub_i32 s17, s10, s14
	s_cmp_ge_u32 s10, s14
	s_cselect_b32 s16, s98, s16
	s_cselect_b32 s10, s17, s10
	s_add_i32 s17, s16, 1
	s_cmp_ge_u32 s10, s14
	s_cselect_b32 s10, s17, s16
	s_xor_b32 s10, s10, s15
	s_sub_i32 s10, s10, s15
	s_mul_i32 s13, s10, s13
	s_sub_i32 s11, s11, s13
	s_add_i32 s12, s11, s12
.LBB0_939:
	s_ashr_i32 s13, s12, 31
	s_lshl_b64 s[14:15], s[12:13], 20
	s_add_u32 s14, s86, s14
	s_addc_u32 s15, s87, s15
	s_and_b64 s[16:17], s[4:5], exec
	s_cselect_b32 s13, s15, s101
	s_cselect_b32 s48, s14, s100
	s_ashr_i32 s11, s10, 31
	s_lshl_b64 s[16:17], s[10:11], 20
	v_readlane_b32 s98, v254, 0
	v_readlane_b32 s99, v254, 1
	s_add_u32 s16, s98, s16
	s_addc_u32 s17, s99, s17
	s_and_b64 s[98:99], s[4:5], exec
	s_cselect_b32 s11, s17, s54
	s_cselect_b32 s49, s16, s53
	s_mov_b32 s52, -2
	s_waitcnt vmcnt(8)
	s_waitcnt lgkmcnt(0)
	s_barrier
	s_setprio 1
	s_waitcnt lgkmcnt(0)
	v_mfma_f32_16x16x32_bf16 v[126:129], v[154:157], v[186:189], 0
	v_mfma_f32_16x16x32_bf16 v[122:125], v[162:165], v[186:189], 0
	v_mfma_f32_16x16x32_bf16 v[110:113], v[154:157], v[194:197], 0
	v_mfma_f32_16x16x32_bf16 v[106:109], v[162:165], v[194:197], 0
	v_mfma_f32_16x16x32_bf16 v[94:97], v[154:157], v[202:205], 0
	v_mfma_f32_16x16x32_bf16 v[90:93], v[162:165], v[202:205], 0
	v_mfma_f32_16x16x32_bf16 v[78:81], v[154:157], v[214:217], 0
	v_mfma_f32_16x16x32_bf16 v[74:77], v[162:165], v[214:217], 0
	v_mfma_f32_16x16x32_bf16 v[126:129], v[158:161], v[190:193], v[126:129]
	v_mfma_f32_16x16x32_bf16 v[122:125], v[166:169], v[190:193], v[122:125]
	v_mfma_f32_16x16x32_bf16 v[110:113], v[158:161], v[198:201], v[110:113]
	v_mfma_f32_16x16x32_bf16 v[106:109], v[166:169], v[198:201], v[106:109]
	v_mfma_f32_16x16x32_bf16 v[94:97], v[158:161], v[210:213], v[94:97]
	v_mfma_f32_16x16x32_bf16 v[90:93], v[166:169], v[210:213], v[90:93]
	v_mfma_f32_16x16x32_bf16 v[78:81], v[158:161], v[218:221], v[78:81]
	v_mfma_f32_16x16x32_bf16 v[74:77], v[166:169], v[218:221], v[74:77]
	s_setprio 0
	s_setprio 1
	v_mfma_f32_16x16x32_bf16 v[118:121], v[170:173], v[186:189], 0
	v_mfma_f32_16x16x32_bf16 v[114:117], v[178:181], v[186:189], 0
	v_mfma_f32_16x16x32_bf16 v[102:105], v[170:173], v[194:197], 0
	v_mfma_f32_16x16x32_bf16 v[98:101], v[178:181], v[194:197], 0
	v_mfma_f32_16x16x32_bf16 v[86:89], v[170:173], v[202:205], 0
	v_mfma_f32_16x16x32_bf16 v[82:85], v[178:181], v[202:205], 0
	v_mfma_f32_16x16x32_bf16 v[70:73], v[170:173], v[214:217], 0
	v_mfma_f32_16x16x32_bf16 v[66:69], v[178:181], v[214:217], 0
	v_mfma_f32_16x16x32_bf16 v[118:121], v[174:177], v[190:193], v[118:121]
	v_mfma_f32_16x16x32_bf16 v[114:117], v[182:185], v[190:193], v[114:117]
	v_mfma_f32_16x16x32_bf16 v[102:105], v[174:177], v[198:201], v[102:105]
	v_mfma_f32_16x16x32_bf16 v[98:101], v[182:185], v[198:201], v[98:101]
	v_mfma_f32_16x16x32_bf16 v[86:89], v[174:177], v[210:213], v[86:89]
	v_mfma_f32_16x16x32_bf16 v[82:85], v[182:185], v[210:213], v[82:85]
	v_mfma_f32_16x16x32_bf16 v[70:73], v[174:177], v[218:221], v[70:73]
	v_mfma_f32_16x16x32_bf16 v[66:69], v[182:185], v[218:221], v[66:69]
	s_setprio 0
	s_barrier
; #define PG8_STAGE(bufoff, gbase, voff) do { _Pragma("unroll") for (int _i = 0; _i < 2; ++_i) \
;         __builtin_amdgcn_global_load_lds((const unsigned*)((const char*)(gbase) + (voff)[_i]), (PG8_LAS unsigned*)(lds + (bufoff) + ldsw + _i * 8192), 16, 0, 0); } while (0)
; #define PG8_LDA(dst, b, h) do { _Pragma("unroll") for (int m = 0; m < 4; ++m) _Pragma("unroll") for (int k = 0; k < 2; ++k) dst[m][k] = *(const PG8_LAS bf16x8*)(lds + PG8_SA(b, h) + aoff + m * 2048 + k * 1024); } while (0)
; #define PG8_LDB(dst, b, h) do { _Pragma("unroll") for (int n = 0; n < 2; ++n) _Pragma("unroll") for (int k = 0; k < 2; ++k) dst[n][k] = *(const PG8_LAS bf16x8*)(lds + PG8_SB(b, h) + boff + n * 2048 + k * 1024); } while (0)
; #define PG8_MMA(ai, bj, At, Bt) do { __builtin_amdgcn_s_setprio(1); _Pragma("unroll") for (int m = 0; m < 4; ++m) _Pragma("unroll") for (int n = 0; n < 2; ++n) _Pragma("unroll") for (int k = 0; k < 2; ++k) \
;         acc[ai][bj][m][n] = __builtin_amdgcn_mfma_f32_16x16x32_bf16(Bt[n][k], At[m][k], acc[ai][bj][m][n], 0, 0, 0); __builtin_amdgcn_s_setprio(0); } while (0)
; #define PG8_WAIT_V(n) asm volatile("s_waitcnt vmcnt(" #n ")" ::: "memory")
; #define PG8_WAIT_L(n) asm volatile("s_waitcnt lgkmcnt(" #n ")" ::: "memory")
; #define PG8_BAR __builtin_amdgcn_s_barrier()
; #define PG8_SCHED __builtin_amdgcn_sched_barrier(0)
; template <class Epi, class Sched, bool ALIGN_EPI = false, bool SP2 = false>
; __device__ __forceinline__ void gemm_phase(PG8_LAS unsigned char* lds, const Gemm g, const Sched& S, const Epi& E) {
;     ...
;             PG8_LDA(At, 0, 1); PG8_STAGE(PG8_SB(0, 0), b2, voffB); PG8_STAGE(PG8_SB(0, 1), b2 + hstepB, voffB); PG8_STAGE(PG8_SA(0, 0), a2, voffA);
;             PG8_WAIT_V(8); PG8_WAIT_L(0); PG8_BAR; PG8_MMA(1, 0, At, B0); PG8_MMA(1, 1, At, B1); PG8_BAR; PG8_SCHED;
;             PG8_LDB(B0, 1, 0); PG8_LDB(B1, 1, 1); PG8_SCHED; PG8_LDA(At, 1, 0); PG8_STAGE(PG8_SA(0, 1), a2 + hstepA, voffA);
	s_add_i32 s53, s44, s34
	v_lshl_add_u64 v[146:147], s[28:29], 0, v[134:135]
	s_mov_b32 m0, s53
	ds_read_b128 v[186:189], v152 offset:16384
	ds_read_b128 v[190:193], v152 offset:17408
	ds_read_b128 v[194:197], v152 offset:18432
	ds_read_b128 v[198:201], v152 offset:19456
	ds_read_b128 v[202:205], v152 offset:20480
	ds_read_b128 v[210:213], v152 offset:21504
	ds_read_b128 v[214:217], v152 offset:22528
	ds_read_b128 v[218:221], v152 offset:23552
	global_load_lds_dwordx4 v[146:147], off
	s_add_i32 m0, s53, 0x2000
	s_add_u32 s54, s28, 0x80000
	v_lshl_add_u64 v[206:207], s[28:29], 0, v[130:131]
	s_addc_u32 s55, s29, 0
	s_add_i32 s53, s45, s34
	global_load_lds_dwordx4 v[206:207], off
	v_lshl_add_u64 v[222:223], s[54:55], 0, v[134:135]
	s_mov_b32 m0, s53
	v_lshl_add_u64 v[224:225], s[30:31], 0, v[132:133]
	global_load_lds_dwordx4 v[222:223], off
	v_lshl_add_u64 v[222:223], s[54:55], 0, v[130:131]
	s_add_i32 m0, s53, 0x2000
	s_nop 0
	global_load_lds_dwordx4 v[222:223], off
	v_lshl_add_u64 v[222:223], s[30:31], 0, v[136:137]
	s_mov_b32 m0, s25
	s_nop 0
	global_load_lds_dwordx4 v[222:223], off
	s_mov_b32 m0, s37
	s_nop 0
	global_load_lds_dwordx4 v[224:225], off
	s_waitcnt vmcnt(8)
	s_waitcnt lgkmcnt(0)
	s_barrier
	s_setprio 1
	s_waitcnt lgkmcnt(0)
	v_mfma_f32_16x16x32_bf16 v[62:65], v[154:157], v[186:189], 0
	v_mfma_f32_16x16x32_bf16 v[58:61], v[162:165], v[186:189], 0
	v_mfma_f32_16x16x32_bf16 v[46:49], v[154:157], v[194:197], 0
	v_mfma_f32_16x16x32_bf16 v[42:45], v[162:165], v[194:197], 0
	v_mfma_f32_16x16x32_bf16 v[30:33], v[154:157], v[202:205], 0
	v_mfma_f32_16x16x32_bf16 v[26:29], v[162:165], v[202:205], 0
	v_mfma_f32_16x16x32_bf16 v[14:17], v[154:157], v[214:217], 0
	v_mfma_f32_16x16x32_bf16 v[10:13], v[162:165], v[214:217], 0
	v_mfma_f32_16x16x32_bf16 v[62:65], v[158:161], v[190:193], v[62:65]
	v_mfma_f32_16x16x32_bf16 v[58:61], v[166:169], v[190:193], v[58:61]
	v_mfma_f32_16x16x32_bf16 v[46:49], v[158:161], v[198:201], v[46:49]
	v_mfma_f32_16x16x32_bf16 v[42:45], v[166:169], v[198:201], v[42:45]
	v_mfma_f32_16x16x32_bf16 v[30:33], v[158:161], v[210:213], v[30:33]
	v_mfma_f32_16x16x32_bf16 v[26:29], v[166:169], v[210:213], v[26:29]
	v_mfma_f32_16x16x32_bf16 v[14:17], v[158:161], v[218:221], v[14:17]
	v_mfma_f32_16x16x32_bf16 v[10:13], v[166:169], v[218:221], v[10:13]
	s_setprio 0
	s_setprio 1
	v_mfma_f32_16x16x32_bf16 v[54:57], v[170:173], v[186:189], 0
	v_mfma_f32_16x16x32_bf16 v[50:53], v[178:181], v[186:189], 0
	v_mfma_f32_16x16x32_bf16 v[38:41], v[170:173], v[194:197], 0
	v_mfma_f32_16x16x32_bf16 v[34:37], v[178:181], v[194:197], 0
	v_mfma_f32_16x16x32_bf16 v[22:25], v[170:173], v[202:205], 0
	v_mfma_f32_16x16x32_bf16 v[18:21], v[178:181], v[202:205], 0
	v_mfma_f32_16x16x32_bf16 v[6:9], v[170:173], v[214:217], 0
	v_mfma_f32_16x16x32_bf16 v[2:5], v[178:181], v[214:217], 0
	v_mfma_f32_16x16x32_bf16 v[54:57], v[174:177], v[190:193], v[54:57]
	v_mfma_f32_16x16x32_bf16 v[50:53], v[182:185], v[190:193], v[50:53]
	v_mfma_f32_16x16x32_bf16 v[38:41], v[174:177], v[198:201], v[38:41]
	v_mfma_f32_16x16x32_bf16 v[34:37], v[182:185], v[198:201], v[34:37]
	v_mfma_f32_16x16x32_bf16 v[22:25], v[174:177], v[210:213], v[22:25]
	v_mfma_f32_16x16x32_bf16 v[18:21], v[182:185], v[210:213], v[18:21]
	v_mfma_f32_16x16x32_bf16 v[6:9], v[174:177], v[218:221], v[6:9]
	v_mfma_f32_16x16x32_bf16 v[2:5], v[182:185], v[218:221], v[2:5]
	s_setprio 0
	s_barrier
	s_add_i32 s53, 0, 0x18000
	v_add_u32_e32 v153, s53, v148
	s_add_i32 s54, 0, 0x1c000
	ds_read_b128 v[154:157], v153
	ds_read_b128 v[158:161], v153 offset:1024
	ds_read_b128 v[162:165], v153 offset:2048
	ds_read_b128 v[166:169], v153 offset:3072
	v_add_u32_e32 v153, s54, v148
	ds_read_b128 v[170:173], v153
	ds_read_b128 v[174:177], v153 offset:1024
	ds_read_b128 v[178:181], v153 offset:2048
	ds_read_b128 v[182:185], v153 offset:3072
	s_add_u32 s30, s30, 0x80000
	s_addc_u32 s31, s31, 0
	s_mov_b32 m0, s38
	v_lshl_add_u64 v[226:227], s[30:31], 0, v[136:137]
	ds_read_b128 v[186:189], v152 offset:32768
	ds_read_b128 v[190:193], v152 offset:33792
	ds_read_b128 v[194:197], v152 offset:34816
	ds_read_b128 v[198:201], v152 offset:35840
	ds_read_b128 v[202:205], v152 offset:36864
	ds_read_b128 v[210:213], v152 offset:37888
	ds_read_b128 v[214:217], v152 offset:38912
	ds_read_b128 v[218:221], v152 offset:39936
	global_load_lds_dwordx4 v[226:227], off
	v_lshl_add_u64 v[226:227], s[30:31], 0, v[132:133]
	s_mov_b32 m0, s39
	s_nop 0
	global_load_lds_dwordx4 v[226:227], off
	s_waitcnt vmcnt(8)
	s_waitcnt lgkmcnt(0)
	s_barrier
; #define PG8_STAGE(bufoff, gbase, voff) do { _Pragma("unroll") for (int _i = 0; _i < 2; ++_i) \
;         __builtin_amdgcn_global_load_lds((const unsigned*)((const char*)(gbase) + (voff)[_i]), (PG8_LAS unsigned*)(lds + (bufoff) + ldsw + _i * 8192), 16, 0, 0); } while (0)
; #define PG8_LDA(dst, b, h) do { _Pragma("unroll") for (int m = 0; m < 4; ++m) _Pragma("unroll") for (int k = 0; k < 2; ++k) dst[m][k] = *(const PG8_LAS bf16x8*)(lds + PG8_SA(b, h) + aoff + m * 2048 + k * 1024); } while (0)
; #define PG8_MMA(ai, bj, At, Bt) do { __builtin_amdgcn_s_setprio(1); _Pragma("unroll") for (int m = 0; m < 4; ++m) _Pragma("unroll") for (int n = 0; n < 2; ++n) _Pragma("unroll") for (int k = 0; k < 2; ++k) \
;         acc[ai][bj][m][n] = __builtin_amdgcn_mfma_f32_16x16x32_bf16(Bt[n][k], At[m][k], acc[ai][bj][m][n], 0, 0, 0); __builtin_amdgcn_s_setprio(0); } while (0)
; #define PG8_WAIT_V(n) asm volatile("s_waitcnt vmcnt(" #n ")" ::: "memory")
; #define PG8_WAIT_L(n) asm volatile("s_waitcnt lgkmcnt(" #n ")" ::: "memory")
; #define PG8_BAR __builtin_amdgcn_s_barrier()
; #define PG8_SCHED __builtin_amdgcn_sched_barrier(0)
; template <class Epi, class Sched, bool ALIGN_EPI = false, bool SP2 = false>
; __device__ __forceinline__ void gemm_phase(PG8_LAS unsigned char* lds, const Gemm g, const Sched& S, const Epi& E) {
;     ...
;             PG8_WAIT_V(8); PG8_WAIT_L(0); PG8_BAR; PG8_MMA(0, 0, At, B0); PG8_MMA(0, 1, At, B1); PG8_BAR; PG8_SCHED;
;             PG8_LDA(At, 1, 1); PG8_STAGE(PG8_SB(1, 0), b3, voffB); PG8_STAGE(PG8_SB(1, 1), b3 + hstepB, voffB); PG8_STAGE(PG8_SA(1, 0), a3, voffA);
;             PG8_WAIT_V(8); PG8_WAIT_L(0); PG8_BAR; PG8_MMA(1, 0, At, B0); PG8_MMA(1, 1, At, B1); PG8_BAR; PG8_SCHED;
	s_setprio 1
	s_waitcnt lgkmcnt(0)
	v_mfma_f32_16x16x32_bf16 v[126:129], v[154:157], v[186:189], v[126:129]
	v_mfma_f32_16x16x32_bf16 v[122:125], v[162:165], v[186:189], v[122:125]
	v_mfma_f32_16x16x32_bf16 v[110:113], v[154:157], v[194:197], v[110:113]
	v_mfma_f32_16x16x32_bf16 v[106:109], v[162:165], v[194:197], v[106:109]
	v_mfma_f32_16x16x32_bf16 v[94:97], v[154:157], v[202:205], v[94:97]
	v_mfma_f32_16x16x32_bf16 v[90:93], v[162:165], v[202:205], v[90:93]
	v_mfma_f32_16x16x32_bf16 v[78:81], v[154:157], v[214:217], v[78:81]
	v_mfma_f32_16x16x32_bf16 v[74:77], v[162:165], v[214:217], v[74:77]
	v_mfma_f32_16x16x32_bf16 v[126:129], v[158:161], v[190:193], v[126:129]
	v_mfma_f32_16x16x32_bf16 v[122:125], v[166:169], v[190:193], v[122:125]
	v_mfma_f32_16x16x32_bf16 v[110:113], v[158:161], v[198:201], v[110:113]
	v_mfma_f32_16x16x32_bf16 v[106:109], v[166:169], v[198:201], v[106:109]
	v_mfma_f32_16x16x32_bf16 v[94:97], v[158:161], v[210:213], v[94:97]
	v_mfma_f32_16x16x32_bf16 v[90:93], v[166:169], v[210:213], v[90:93]
	v_mfma_f32_16x16x32_bf16 v[78:81], v[158:161], v[218:221], v[78:81]
	v_mfma_f32_16x16x32_bf16 v[74:77], v[166:169], v[218:221], v[74:77]
	s_setprio 0
	s_setprio 1
	v_mfma_f32_16x16x32_bf16 v[118:121], v[170:173], v[186:189], v[118:121]
	v_mfma_f32_16x16x32_bf16 v[114:117], v[178:181], v[186:189], v[114:117]
	v_mfma_f32_16x16x32_bf16 v[102:105], v[170:173], v[194:197], v[102:105]
	v_mfma_f32_16x16x32_bf16 v[98:101], v[178:181], v[194:197], v[98:101]
	v_mfma_f32_16x16x32_bf16 v[86:89], v[170:173], v[202:205], v[86:89]
	v_mfma_f32_16x16x32_bf16 v[82:85], v[178:181], v[202:205], v[82:85]
	v_mfma_f32_16x16x32_bf16 v[70:73], v[170:173], v[214:217], v[70:73]
	v_mfma_f32_16x16x32_bf16 v[66:69], v[178:181], v[214:217], v[66:69]
	v_mfma_f32_16x16x32_bf16 v[118:121], v[174:177], v[190:193], v[118:121]
	v_mfma_f32_16x16x32_bf16 v[114:117], v[182:185], v[190:193], v[114:117]
	v_mfma_f32_16x16x32_bf16 v[102:105], v[174:177], v[198:201], v[102:105]
	v_mfma_f32_16x16x32_bf16 v[98:101], v[182:185], v[198:201], v[98:101]
	v_mfma_f32_16x16x32_bf16 v[86:89], v[174:177], v[210:213], v[86:89]
	v_mfma_f32_16x16x32_bf16 v[82:85], v[182:185], v[210:213], v[82:85]
	v_mfma_f32_16x16x32_bf16 v[70:73], v[174:177], v[218:221], v[70:73]
	v_mfma_f32_16x16x32_bf16 v[66:69], v[182:185], v[218:221], v[66:69]
	s_setprio 0
	s_barrier
	s_add_i32 s30, s53, s34
	v_lshl_add_u64 v[146:147], v[146:147], 0, s[2:3]
	s_mov_b32 m0, s30
	ds_read_b128 v[186:189], v152 offset:49152
	ds_read_b128 v[190:193], v152 offset:50176
	ds_read_b128 v[194:197], v152 offset:51200
	ds_read_b128 v[198:201], v152 offset:52224
	ds_read_b128 v[202:205], v152 offset:53248
	ds_read_b128 v[210:213], v152 offset:54272
	ds_read_b128 v[214:217], v152 offset:55296
	ds_read_b128 v[218:221], v152 offset:56320
	global_load_lds_dwordx4 v[146:147], off
	s_add_i32 m0, s30, 0x2000
	s_add_u32 s28, s28, 0x80080
	v_lshl_add_u64 v[146:147], v[206:207], 0, s[2:3]
	s_addc_u32 s29, s29, 0
	s_add_i32 s30, s54, s34
	global_load_lds_dwordx4 v[146:147], off
	v_lshl_add_u64 v[146:147], s[28:29], 0, v[134:135]
	s_mov_b32 m0, s30
	s_nop 0
	global_load_lds_dwordx4 v[146:147], off
	v_lshl_add_u64 v[146:147], s[28:29], 0, v[130:131]
	s_add_i32 m0, s30, 0x2000
	s_nop 0
	global_load_lds_dwordx4 v[146:147], off
	v_lshl_add_u64 v[146:147], v[222:223], 0, s[2:3]
	s_mov_b32 m0, s41
	s_nop 0
	global_load_lds_dwordx4 v[146:147], off
	v_lshl_add_u64 v[146:147], v[224:225], 0, s[2:3]
	s_mov_b32 m0, s42
	s_nop 0
	global_load_lds_dwordx4 v[146:147], off
	s_waitcnt vmcnt(8)
	s_waitcnt lgkmcnt(0)
	s_barrier
	s_setprio 1
	s_waitcnt lgkmcnt(0)
	v_mfma_f32_16x16x32_bf16 v[62:65], v[154:157], v[186:189], v[62:65]
	v_mfma_f32_16x16x32_bf16 v[58:61], v[162:165], v[186:189], v[58:61]
	v_mfma_f32_16x16x32_bf16 v[46:49], v[154:157], v[194:197], v[46:49]
	v_mfma_f32_16x16x32_bf16 v[42:45], v[162:165], v[194:197], v[42:45]
	v_mfma_f32_16x16x32_bf16 v[30:33], v[154:157], v[202:205], v[30:33]
	v_mfma_f32_16x16x32_bf16 v[26:29], v[162:165], v[202:205], v[26:29]
	v_mfma_f32_16x16x32_bf16 v[14:17], v[154:157], v[214:217], v[14:17]
	v_mfma_f32_16x16x32_bf16 v[10:13], v[162:165], v[214:217], v[10:13]
	v_mfma_f32_16x16x32_bf16 v[62:65], v[158:161], v[190:193], v[62:65]
	v_mfma_f32_16x16x32_bf16 v[58:61], v[166:169], v[190:193], v[58:61]
	v_mfma_f32_16x16x32_bf16 v[46:49], v[158:161], v[198:201], v[46:49]
	v_mfma_f32_16x16x32_bf16 v[42:45], v[166:169], v[198:201], v[42:45]
	v_mfma_f32_16x16x32_bf16 v[30:33], v[158:161], v[210:213], v[30:33]
	v_mfma_f32_16x16x32_bf16 v[26:29], v[166:169], v[210:213], v[26:29]
	v_mfma_f32_16x16x32_bf16 v[14:17], v[158:161], v[218:221], v[14:17]
	v_mfma_f32_16x16x32_bf16 v[10:13], v[166:169], v[218:221], v[10:13]
	s_setprio 0
	s_setprio 1
	v_mfma_f32_16x16x32_bf16 v[54:57], v[170:173], v[186:189], v[54:57]
	v_mfma_f32_16x16x32_bf16 v[50:53], v[178:181], v[186:189], v[50:53]
	v_mfma_f32_16x16x32_bf16 v[38:41], v[170:173], v[194:197], v[38:41]
	v_mfma_f32_16x16x32_bf16 v[34:37], v[178:181], v[194:197], v[34:37]
	v_mfma_f32_16x16x32_bf16 v[22:25], v[170:173], v[202:205], v[22:25]
	v_mfma_f32_16x16x32_bf16 v[18:21], v[178:181], v[202:205], v[18:21]
	v_mfma_f32_16x16x32_bf16 v[6:9], v[170:173], v[214:217], v[6:9]
	v_mfma_f32_16x16x32_bf16 v[2:5], v[178:181], v[214:217], v[2:5]
	v_mfma_f32_16x16x32_bf16 v[54:57], v[174:177], v[190:193], v[54:57]
	v_mfma_f32_16x16x32_bf16 v[50:53], v[182:185], v[190:193], v[50:53]
	v_mfma_f32_16x16x32_bf16 v[38:41], v[174:177], v[198:201], v[38:41]
	v_mfma_f32_16x16x32_bf16 v[34:37], v[182:185], v[198:201], v[34:37]
	v_mfma_f32_16x16x32_bf16 v[22:25], v[174:177], v[210:213], v[22:25]
	v_mfma_f32_16x16x32_bf16 v[18:21], v[182:185], v[210:213], v[18:21]
	v_mfma_f32_16x16x32_bf16 v[6:9], v[174:177], v[218:221], v[6:9]
	v_mfma_f32_16x16x32_bf16 v[2:5], v[182:185], v[218:221], v[2:5]
	s_setprio 0
	s_barrier
	s_add_i32 s52, s52, 2
	s_add_u32 s26, s26, 0x100
	s_addc_u32 s27, s27, 0
	s_add_u32 s50, s50, 0x100
	s_addc_u32 s51, s51, 0
	s_cmp_gt_u32 s52, 29
	s_cbranch_scc1 .Lpeel_exit_8
	.p2align 6

; #define PG8_STAGE(bufoff, gbase, voff) do { _Pragma("unroll") for (int _i = 0; _i < 2; ++_i) \
;         __builtin_amdgcn_global_load_lds((const unsigned*)((const char*)(gbase) + (voff)[_i]), (PG8_LAS unsigned*)(lds + (bufoff) + ldsw + _i * 8192), 16, 0, 0); } while (0)
; #define PG8_LDA(dst, b, h) do { _Pragma("unroll") for (int m = 0; m < 4; ++m) _Pragma("unroll") for (int k = 0; k < 2; ++k) dst[m][k] = *(const PG8_LAS bf16x8*)(lds + PG8_SA(b, h) + aoff + m * 2048 + k * 1024); } while (0)
; #define PG8_LDB(dst, b, h) do { _Pragma("unroll") for (int n = 0; n < 2; ++n) _Pragma("unroll") for (int k = 0; k < 2; ++k) dst[n][k] = *(const PG8_LAS bf16x8*)(lds + PG8_SB(b, h) + boff + n * 2048 + k * 1024); } while (0)
; #define PG8_MMA(ai, bj, At, Bt) do { __builtin_amdgcn_s_setprio(1); _Pragma("unroll") for (int m = 0; m < 4; ++m) _Pragma("unroll") for (int n = 0; n < 2; ++n) _Pragma("unroll") for (int k = 0; k < 2; ++k) \
;         acc[ai][bj][m][n] = __builtin_amdgcn_mfma_f32_16x16x32_bf16(Bt[n][k], At[m][k], acc[ai][bj][m][n], 0, 0, 0); __builtin_amdgcn_s_setprio(0); } while (0)
; #define PG8_WAIT_V(n) asm volatile("s_waitcnt vmcnt(" #n ")" ::: "memory")
; #define PG8_WAIT_L(n) asm volatile("s_waitcnt lgkmcnt(" #n ")" ::: "memory")
; #define PG8_BAR __builtin_amdgcn_s_barrier()
; #define PG8_SCHED __builtin_amdgcn_sched_barrier(0)
;     __host__ __device__ bool next(int i, Unit& u) const {
;         const long L = (long)i * G + c; if (L >= nwg) return false;
;         int wgid = (int)L; { const int q = nwg / NXCD, r = nwg % NXCD, xcd = wgid % NXCD, off = wgid / NXCD; wgid = (xcd < r ? xcd * (q + 1) : r * (q + 1) + (xcd - r) * q) + off; }
;         const int nig = WGM * nN, gid = wgid / nig, fm = gid * WGM, gsz = (nM - fm) < WGM ? (nM - fm) : WGM;
;         u.pm = fm + ((wgid % nig) % gsz); u.pn = (wgid % nig) / gsz; return true;
;     }
; template <class Epi, class Sched, bool ALIGN_EPI = false, bool SP2 = false>
; __device__ __forceinline__ void gemm_phase(PG8_LAS unsigned char* lds, const Gemm g, const Sched& S, const Epi& E) {
;     ...
;             PG8_LDB(B0, 0, 0); PG8_LDB(B1, 0, 1); PG8_SCHED; PG8_LDA(At, 0, 0); PG8_STAGE(PG8_SA(1, 1), a1 + hstepA, voffA);
;             PG8_WAIT_V(8); PG8_WAIT_L(0); PG8_BAR; PG8_MMA(0, 0, At, B0); PG8_MMA(0, 1, At, B1); PG8_BAR; PG8_SCHED;
.LBB0_1354:
	s_mov_b32 s100, s2
	s_mov_b32 s101, s3
	s_mov_b32 s58, s36
	s_mov_b32 s59, s37
	s_add_u32 s2, s2, 0x80080
	s_addc_u32 s3, s3, 0
	s_add_u32 s55, s36, 0x100
	s_addc_u32 s56, s37, 0
	ds_read_b128 v[66:69], v170
	ds_read_b128 v[70:73], v170 offset:1024
	ds_read_b128 v[74:77], v170 offset:2048
	ds_read_b128 v[78:81], v170 offset:3072
	ds_read_b128 v[162:165], v171
	ds_read_b128 v[174:177], v171 offset:1024
	ds_read_b128 v[178:181], v171 offset:2048
	ds_read_b128 v[182:185], v171 offset:3072
	s_add_u32 s36, s2, 0xfff80080
	s_addc_u32 s37, s3, -1
	s_mov_b32 s39, s37
	s_mov_b32 s38, s36
	s_mov_b32 s37, s56
	s_mov_b32 s36, s55
	v_lshl_add_u64 v[166:167], s[2:3], 0, v[154:155]
	s_add_i32 m0, s43, 0xc000
	ds_read_b128 v[186:189], v172
	ds_read_b128 v[190:193], v172 offset:1024
	ds_read_b128 v[194:197], v172 offset:2048
	ds_read_b128 v[198:201], v172 offset:3072
	ds_read_b128 v[202:205], v172 offset:4096
	ds_read_b128 v[210:213], v172 offset:5120
	ds_read_b128 v[214:217], v172 offset:6144
	ds_read_b128 v[218:221], v172 offset:7168
	global_load_lds_dwordx4 v[166:167], off
	v_lshl_add_u64 v[166:167], s[2:3], 0, v[156:157]
	s_add_i32 m0, s43, 0xe000
	s_nop 0
	global_load_lds_dwordx4 v[166:167], off
	s_add_i32 s47, s47, 1
	s_mul_i32 s4, s47, s50
	s_mul_hi_u32 s5, s47, s33
	s_add_i32 s5, s5, s4
	s_mul_i32 s4, s47, s33
	s_add_u32 s30, s4, s70
	s_addc_u32 s31, s5, s41
	v_cmp_gt_i64_e32 vcc, s[30:31], v[160:161]
	v_cmp_lt_i64_e64 s[4:5], s[30:31], v[158:159]
	s_cbranch_vccnz .LBB0_1356
	s_ashr_i32 s26, s30, 31
	s_lshr_b32 s26, s26, 29
	s_add_i32 s26, s30, s26
	s_ashr_i32 s27, s26, 3
	s_and_b32 s26, s26, -8
	s_sub_i32 s26, s30, s26
	s_cmp_lt_i32 s26, 0
	s_cselect_b32 s28, s42, 0xa0
	s_mul_i32 s26, s28, s26
	s_add_i32 s26, s26, s27
	s_ashr_i32 s27, s26, 31
	s_lshr_b32 s27, s27, 27
	s_add_i32 s27, s26, s27
	s_ashr_i32 s28, s27, 5
	s_lshl_b32 s28, s28, 2
	s_sub_i32 s29, 0xa0, s28
	s_min_i32 s29, s29, 4
	s_abs_i32 s30, s29
	v_cvt_f32_u32_e32 v2, s30
	s_sub_i32 s34, 0, s30
	s_andn2_b32 s27, s27, 31
	s_sub_i32 s27, s26, s27
	v_rcp_iflag_f32_e32 v2, v2
	s_abs_i32 s26, s27
	s_xor_b32 s31, s27, s29
	s_ashr_i32 s31, s31, 31
	v_mul_f32_e32 v2, 0x4f7ffffe, v2
	v_cvt_u32_f32_e32 v2, v2
	s_nop 0
	v_readfirstlane_b32 s35, v2
	s_mul_i32 s34, s34, s35
	s_mul_hi_u32 s34, s35, s34
	s_add_i32 s35, s35, s34
	s_mul_hi_u32 s34, s26, s35
	s_mul_i32 s35, s34, s30
	s_sub_i32 s26, s26, s35
	s_add_i32 s98, s34, 1
	s_sub_i32 s35, s26, s30
	s_cmp_ge_u32 s26, s30
	s_cselect_b32 s34, s98, s34
	s_cselect_b32 s26, s35, s26
	s_add_i32 s35, s34, 1
	s_cmp_ge_u32 s26, s30
	s_cselect_b32 s26, s35, s34
	s_xor_b32 s26, s26, s31
	s_sub_i32 s26, s26, s31
	s_mul_i32 s29, s26, s29
	s_sub_i32 s27, s27, s29
	s_add_i32 s28, s27, s28
.LBB0_1356:
	s_ashr_i32 s29, s28, 31
	s_lshl_b64 s[30:31], s[28:29], 20
	s_add_u32 s30, s86, s30
	s_addc_u32 s31, s87, s31
	s_and_b64 s[34:35], s[4:5], exec
	s_cselect_b32 s29, s31, s101
	s_cselect_b32 s53, s30, s100
	s_ashr_i32 s27, s26, 31
	s_lshl_b64 s[34:35], s[26:27], 20
	s_add_u32 s34, s88, s34
	s_addc_u32 s35, s89, s35
	s_and_b64 s[98:99], s[4:5], exec
	s_cselect_b32 s27, s35, s59
	s_cselect_b32 s54, s34, s58
	s_mov_b32 s57, -2
	s_waitcnt vmcnt(8)
	s_waitcnt lgkmcnt(0)
	s_barrier
	s_setprio 1
	s_waitcnt lgkmcnt(0)
	v_mfma_f32_16x16x32_bf16 v[142:145], v[66:69], v[186:189], 0
	v_mfma_f32_16x16x32_bf16 v[138:141], v[74:77], v[186:189], 0
	v_mfma_f32_16x16x32_bf16 v[126:129], v[66:69], v[194:197], 0
	v_mfma_f32_16x16x32_bf16 v[122:125], v[74:77], v[194:197], 0
	v_mfma_f32_16x16x32_bf16 v[110:113], v[66:69], v[202:205], 0
	v_mfma_f32_16x16x32_bf16 v[106:109], v[74:77], v[202:205], 0
	v_mfma_f32_16x16x32_bf16 v[94:97], v[66:69], v[214:217], 0
	v_mfma_f32_16x16x32_bf16 v[90:93], v[74:77], v[214:217], 0
	v_mfma_f32_16x16x32_bf16 v[142:145], v[70:73], v[190:193], v[142:145]
	v_mfma_f32_16x16x32_bf16 v[138:141], v[78:81], v[190:193], v[138:141]
	v_mfma_f32_16x16x32_bf16 v[126:129], v[70:73], v[198:201], v[126:129]
	v_mfma_f32_16x16x32_bf16 v[122:125], v[78:81], v[198:201], v[122:125]
	v_mfma_f32_16x16x32_bf16 v[110:113], v[70:73], v[210:213], v[110:113]
	v_mfma_f32_16x16x32_bf16 v[106:109], v[78:81], v[210:213], v[106:109]
	v_mfma_f32_16x16x32_bf16 v[94:97], v[70:73], v[218:221], v[94:97]
	v_mfma_f32_16x16x32_bf16 v[90:93], v[78:81], v[218:221], v[90:93]
	s_setprio 0
	s_setprio 1
	v_mfma_f32_16x16x32_bf16 v[134:137], v[162:165], v[186:189], 0
	v_mfma_f32_16x16x32_bf16 v[130:133], v[178:181], v[186:189], 0
	v_mfma_f32_16x16x32_bf16 v[118:121], v[162:165], v[194:197], 0
	v_mfma_f32_16x16x32_bf16 v[114:117], v[178:181], v[194:197], 0
	v_mfma_f32_16x16x32_bf16 v[102:105], v[162:165], v[202:205], 0
	v_mfma_f32_16x16x32_bf16 v[98:101], v[178:181], v[202:205], 0
	v_mfma_f32_16x16x32_bf16 v[86:89], v[162:165], v[214:217], 0
	v_mfma_f32_16x16x32_bf16 v[82:85], v[178:181], v[214:217], 0
	v_mfma_f32_16x16x32_bf16 v[134:137], v[174:177], v[190:193], v[134:137]
	v_mfma_f32_16x16x32_bf16 v[130:133], v[182:185], v[190:193], v[130:133]
	v_mfma_f32_16x16x32_bf16 v[118:121], v[174:177], v[198:201], v[118:121]
	v_mfma_f32_16x16x32_bf16 v[114:117], v[182:185], v[198:201], v[114:117]
	v_mfma_f32_16x16x32_bf16 v[102:105], v[174:177], v[210:213], v[102:105]
	v_mfma_f32_16x16x32_bf16 v[98:101], v[182:185], v[210:213], v[98:101]
	v_mfma_f32_16x16x32_bf16 v[86:89], v[174:177], v[218:221], v[86:89]
	v_mfma_f32_16x16x32_bf16 v[82:85], v[182:185], v[218:221], v[82:85]
	s_setprio 0
	s_barrier
; #define PG8_STAGE(bufoff, gbase, voff) do { _Pragma("unroll") for (int _i = 0; _i < 2; ++_i) \
;         __builtin_amdgcn_global_load_lds((const unsigned*)((const char*)(gbase) + (voff)[_i]), (PG8_LAS unsigned*)(lds + (bufoff) + ldsw + _i * 8192), 16, 0, 0); } while (0)
; #define PG8_LDA(dst, b, h) do { _Pragma("unroll") for (int m = 0; m < 4; ++m) _Pragma("unroll") for (int k = 0; k < 2; ++k) dst[m][k] = *(const PG8_LAS bf16x8*)(lds + PG8_SA(b, h) + aoff + m * 2048 + k * 1024); } while (0)
; #define PG8_LDB(dst, b, h) do { _Pragma("unroll") for (int n = 0; n < 2; ++n) _Pragma("unroll") for (int k = 0; k < 2; ++k) dst[n][k] = *(const PG8_LAS bf16x8*)(lds + PG8_SB(b, h) + boff + n * 2048 + k * 1024); } while (0)
; #define PG8_MMA(ai, bj, At, Bt) do { __builtin_amdgcn_s_setprio(1); _Pragma("unroll") for (int m = 0; m < 4; ++m) _Pragma("unroll") for (int n = 0; n < 2; ++n) _Pragma("unroll") for (int k = 0; k < 2; ++k) \
;         acc[ai][bj][m][n] = __builtin_amdgcn_mfma_f32_16x16x32_bf16(Bt[n][k], At[m][k], acc[ai][bj][m][n], 0, 0, 0); __builtin_amdgcn_s_setprio(0); } while (0)
; #define PG8_WAIT_V(n) asm volatile("s_waitcnt vmcnt(" #n ")" ::: "memory")
; #define PG8_WAIT_L(n) asm volatile("s_waitcnt lgkmcnt(" #n ")" ::: "memory")
; #define PG8_BAR __builtin_amdgcn_s_barrier()
; #define PG8_SCHED __builtin_amdgcn_sched_barrier(0)
; template <class Epi, class Sched, bool ALIGN_EPI = false, bool SP2 = false>
; __device__ __forceinline__ void gemm_phase(PG8_LAS unsigned char* lds, const Gemm g, const Sched& S, const Epi& E) {
;     ...
;             PG8_LDA(At, 0, 1); PG8_STAGE(PG8_SB(0, 0), b2, voffB); PG8_STAGE(PG8_SB(0, 1), b2 + hstepB, voffB); PG8_STAGE(PG8_SA(0, 0), a2, voffA);
;             PG8_WAIT_V(8); PG8_WAIT_L(0); PG8_BAR; PG8_MMA(1, 0, At, B0); PG8_MMA(1, 1, At, B1); PG8_BAR; PG8_SCHED;
;             PG8_LDB(B0, 1, 0); PG8_LDB(B1, 1, 1); PG8_SCHED; PG8_LDA(At, 1, 0); PG8_STAGE(PG8_SA(0, 1), a2 + hstepA, voffA);
	s_add_i32 s58, s51, s40
	v_lshl_add_u64 v[166:167], s[36:37], 0, v[150:151]
	s_mov_b32 m0, s58
	ds_read_b128 v[186:189], v172 offset:16384
	ds_read_b128 v[190:193], v172 offset:17408
	ds_read_b128 v[194:197], v172 offset:18432
	ds_read_b128 v[198:201], v172 offset:19456
	ds_read_b128 v[202:205], v172 offset:20480
	ds_read_b128 v[210:213], v172 offset:21504
	ds_read_b128 v[214:217], v172 offset:22528
	ds_read_b128 v[218:221], v172 offset:23552
	global_load_lds_dwordx4 v[166:167], off
	s_add_i32 m0, s58, 0x2000
	s_add_u32 s58, s36, 0x80000
	v_lshl_add_u64 v[206:207], s[36:37], 0, v[146:147]
	s_addc_u32 s59, s37, 0
	s_add_i32 s60, s52, s40
	global_load_lds_dwordx4 v[206:207], off
	v_lshl_add_u64 v[222:223], s[58:59], 0, v[150:151]
	s_mov_b32 m0, s60
	v_lshl_add_u64 v[224:225], s[38:39], 0, v[148:149]
	global_load_lds_dwordx4 v[222:223], off
	v_lshl_add_u64 v[222:223], s[58:59], 0, v[146:147]
	s_add_i32 m0, s60, 0x2000
	s_nop 0
	global_load_lds_dwordx4 v[222:223], off
	v_lshl_add_u64 v[222:223], s[38:39], 0, v[152:153]
	s_mov_b32 m0, s43
	s_nop 0
	global_load_lds_dwordx4 v[222:223], off
	s_mov_b32 m0, s44
	s_nop 0
	global_load_lds_dwordx4 v[224:225], off
	s_waitcnt vmcnt(8)
	s_waitcnt lgkmcnt(0)
	s_barrier
	s_setprio 1
	s_waitcnt lgkmcnt(0)
	v_mfma_f32_16x16x32_bf16 v[62:65], v[66:69], v[186:189], 0
	v_mfma_f32_16x16x32_bf16 v[58:61], v[74:77], v[186:189], 0
	v_mfma_f32_16x16x32_bf16 v[46:49], v[66:69], v[194:197], 0
	v_mfma_f32_16x16x32_bf16 v[42:45], v[74:77], v[194:197], 0
	v_mfma_f32_16x16x32_bf16 v[30:33], v[66:69], v[202:205], 0
	v_mfma_f32_16x16x32_bf16 v[26:29], v[74:77], v[202:205], 0
	v_mfma_f32_16x16x32_bf16 v[14:17], v[66:69], v[214:217], 0
	v_mfma_f32_16x16x32_bf16 v[10:13], v[74:77], v[214:217], 0
	v_mfma_f32_16x16x32_bf16 v[62:65], v[70:73], v[190:193], v[62:65]
	v_mfma_f32_16x16x32_bf16 v[58:61], v[78:81], v[190:193], v[58:61]
	v_mfma_f32_16x16x32_bf16 v[46:49], v[70:73], v[198:201], v[46:49]
	v_mfma_f32_16x16x32_bf16 v[42:45], v[78:81], v[198:201], v[42:45]
	v_mfma_f32_16x16x32_bf16 v[30:33], v[70:73], v[210:213], v[30:33]
	v_mfma_f32_16x16x32_bf16 v[26:29], v[78:81], v[210:213], v[26:29]
	v_mfma_f32_16x16x32_bf16 v[14:17], v[70:73], v[218:221], v[14:17]
	v_mfma_f32_16x16x32_bf16 v[10:13], v[78:81], v[218:221], v[10:13]
	s_setprio 0
	s_setprio 1
	v_mfma_f32_16x16x32_bf16 v[54:57], v[162:165], v[186:189], 0
	v_mfma_f32_16x16x32_bf16 v[50:53], v[178:181], v[186:189], 0
	v_mfma_f32_16x16x32_bf16 v[38:41], v[162:165], v[194:197], 0
	v_mfma_f32_16x16x32_bf16 v[34:37], v[178:181], v[194:197], 0
	v_mfma_f32_16x16x32_bf16 v[22:25], v[162:165], v[202:205], 0
	v_mfma_f32_16x16x32_bf16 v[18:21], v[178:181], v[202:205], 0
	v_mfma_f32_16x16x32_bf16 v[6:9], v[162:165], v[214:217], 0
	v_mfma_f32_16x16x32_bf16 v[2:5], v[178:181], v[214:217], 0
	v_mfma_f32_16x16x32_bf16 v[54:57], v[174:177], v[190:193], v[54:57]
	v_mfma_f32_16x16x32_bf16 v[50:53], v[182:185], v[190:193], v[50:53]
	v_mfma_f32_16x16x32_bf16 v[38:41], v[174:177], v[198:201], v[38:41]
	v_mfma_f32_16x16x32_bf16 v[34:37], v[182:185], v[198:201], v[34:37]
	v_mfma_f32_16x16x32_bf16 v[22:25], v[174:177], v[210:213], v[22:25]
	v_mfma_f32_16x16x32_bf16 v[18:21], v[182:185], v[210:213], v[18:21]
	v_mfma_f32_16x16x32_bf16 v[6:9], v[174:177], v[218:221], v[6:9]
	v_mfma_f32_16x16x32_bf16 v[2:5], v[182:185], v[218:221], v[2:5]
	s_setprio 0
	s_barrier
	s_add_i32 s58, 0, 0x18000
	s_add_i32 s59, 0, 0x1c000
	v_add_u32_e32 v78, s58, v168
	v_add_u32_e32 v173, s59, v168
	ds_read_b128 v[66:69], v78
	ds_read_b128 v[70:73], v78 offset:1024
	ds_read_b128 v[74:77], v78 offset:2048
	ds_read_b128 v[78:81], v78 offset:3072
	ds_read_b128 v[162:165], v173
	ds_read_b128 v[174:177], v173 offset:1024
	ds_read_b128 v[178:181], v173 offset:2048
	ds_read_b128 v[182:185], v173 offset:3072
	s_add_u32 s38, s38, 0x80000
	s_addc_u32 s39, s39, 0
	s_mov_b32 m0, s45
	v_lshl_add_u64 v[226:227], s[38:39], 0, v[152:153]
	ds_read_b128 v[186:189], v172 offset:32768
	ds_read_b128 v[190:193], v172 offset:33792
	ds_read_b128 v[194:197], v172 offset:34816
	ds_read_b128 v[198:201], v172 offset:35840
	ds_read_b128 v[202:205], v172 offset:36864
	ds_read_b128 v[210:213], v172 offset:37888
	ds_read_b128 v[214:217], v172 offset:38912
	ds_read_b128 v[218:221], v172 offset:39936
	global_load_lds_dwordx4 v[226:227], off
	v_lshl_add_u64 v[226:227], s[38:39], 0, v[148:149]
	s_mov_b32 m0, s46
	s_nop 0
	global_load_lds_dwordx4 v[226:227], off
	s_waitcnt vmcnt(8)
	s_waitcnt lgkmcnt(0)
	s_barrier
; #define PG8_STAGE(bufoff, gbase, voff) do { _Pragma("unroll") for (int _i = 0; _i < 2; ++_i) \
;         __builtin_amdgcn_global_load_lds((const unsigned*)((const char*)(gbase) + (voff)[_i]), (PG8_LAS unsigned*)(lds + (bufoff) + ldsw + _i * 8192), 16, 0, 0); } while (0)
; #define PG8_LDA(dst, b, h) do { _Pragma("unroll") for (int m = 0; m < 4; ++m) _Pragma("unroll") for (int k = 0; k < 2; ++k) dst[m][k] = *(const PG8_LAS bf16x8*)(lds + PG8_SA(b, h) + aoff + m * 2048 + k * 1024); } while (0)
; #define PG8_MMA(ai, bj, At, Bt) do { __builtin_amdgcn_s_setprio(1); _Pragma("unroll") for (int m = 0; m < 4; ++m) _Pragma("unroll") for (int n = 0; n < 2; ++n) _Pragma("unroll") for (int k = 0; k < 2; ++k) \
;         acc[ai][bj][m][n] = __builtin_amdgcn_mfma_f32_16x16x32_bf16(Bt[n][k], At[m][k], acc[ai][bj][m][n], 0, 0, 0); __builtin_amdgcn_s_setprio(0); } while (0)
; #define PG8_WAIT_V(n) asm volatile("s_waitcnt vmcnt(" #n ")" ::: "memory")
; #define PG8_WAIT_L(n) asm volatile("s_waitcnt lgkmcnt(" #n ")" ::: "memory")
; #define PG8_BAR __builtin_amdgcn_s_barrier()
; #define PG8_SCHED __builtin_amdgcn_sched_barrier(0)
; template <class Epi, class Sched, bool ALIGN_EPI = false, bool SP2 = false>
; __device__ __forceinline__ void gemm_phase(PG8_LAS unsigned char* lds, const Gemm g, const Sched& S, const Epi& E) {
;     ...
;             PG8_WAIT_V(8); PG8_WAIT_L(0); PG8_BAR; PG8_MMA(0, 0, At, B0); PG8_MMA(0, 1, At, B1); PG8_BAR; PG8_SCHED;
;             PG8_LDA(At, 1, 1); PG8_STAGE(PG8_SB(1, 0), b3, voffB); PG8_STAGE(PG8_SB(1, 1), b3 + hstepB, voffB); PG8_STAGE(PG8_SA(1, 0), a3, voffA);
;             PG8_WAIT_V(8); PG8_WAIT_L(0); PG8_BAR; PG8_MMA(1, 0, At, B0); PG8_MMA(1, 1, At, B1); PG8_BAR; PG8_SCHED;
	s_setprio 1
	s_waitcnt lgkmcnt(0)
	v_mfma_f32_16x16x32_bf16 v[142:145], v[66:69], v[186:189], v[142:145]
	v_mfma_f32_16x16x32_bf16 v[138:141], v[74:77], v[186:189], v[138:141]
	v_mfma_f32_16x16x32_bf16 v[126:129], v[66:69], v[194:197], v[126:129]
	v_mfma_f32_16x16x32_bf16 v[122:125], v[74:77], v[194:197], v[122:125]
	v_mfma_f32_16x16x32_bf16 v[110:113], v[66:69], v[202:205], v[110:113]
	v_mfma_f32_16x16x32_bf16 v[106:109], v[74:77], v[202:205], v[106:109]
	v_mfma_f32_16x16x32_bf16 v[94:97], v[66:69], v[214:217], v[94:97]
	v_mfma_f32_16x16x32_bf16 v[90:93], v[74:77], v[214:217], v[90:93]
	v_mfma_f32_16x16x32_bf16 v[142:145], v[70:73], v[190:193], v[142:145]
	v_mfma_f32_16x16x32_bf16 v[138:141], v[78:81], v[190:193], v[138:141]
	v_mfma_f32_16x16x32_bf16 v[126:129], v[70:73], v[198:201], v[126:129]
	v_mfma_f32_16x16x32_bf16 v[122:125], v[78:81], v[198:201], v[122:125]
	v_mfma_f32_16x16x32_bf16 v[110:113], v[70:73], v[210:213], v[110:113]
	v_mfma_f32_16x16x32_bf16 v[106:109], v[78:81], v[210:213], v[106:109]
	v_mfma_f32_16x16x32_bf16 v[94:97], v[70:73], v[218:221], v[94:97]
	v_mfma_f32_16x16x32_bf16 v[90:93], v[78:81], v[218:221], v[90:93]
	s_setprio 0
	s_setprio 1
	v_mfma_f32_16x16x32_bf16 v[134:137], v[162:165], v[186:189], v[134:137]
	v_mfma_f32_16x16x32_bf16 v[130:133], v[178:181], v[186:189], v[130:133]
	v_mfma_f32_16x16x32_bf16 v[118:121], v[162:165], v[194:197], v[118:121]
	v_mfma_f32_16x16x32_bf16 v[114:117], v[178:181], v[194:197], v[114:117]
	v_mfma_f32_16x16x32_bf16 v[102:105], v[162:165], v[202:205], v[102:105]
	v_mfma_f32_16x16x32_bf16 v[98:101], v[178:181], v[202:205], v[98:101]
	v_mfma_f32_16x16x32_bf16 v[86:89], v[162:165], v[214:217], v[86:89]
	v_mfma_f32_16x16x32_bf16 v[82:85], v[178:181], v[214:217], v[82:85]
	v_mfma_f32_16x16x32_bf16 v[134:137], v[174:177], v[190:193], v[134:137]
	v_mfma_f32_16x16x32_bf16 v[130:133], v[182:185], v[190:193], v[130:133]
	v_mfma_f32_16x16x32_bf16 v[118:121], v[174:177], v[198:201], v[118:121]
	v_mfma_f32_16x16x32_bf16 v[114:117], v[182:185], v[198:201], v[114:117]
	v_mfma_f32_16x16x32_bf16 v[102:105], v[174:177], v[210:213], v[102:105]
	v_mfma_f32_16x16x32_bf16 v[98:101], v[182:185], v[210:213], v[98:101]
	v_mfma_f32_16x16x32_bf16 v[86:89], v[174:177], v[218:221], v[86:89]
	v_mfma_f32_16x16x32_bf16 v[82:85], v[182:185], v[218:221], v[82:85]
	s_setprio 0
	s_barrier
	s_add_i32 s38, s58, s40
	v_lshl_add_u64 v[166:167], v[166:167], 0, s[14:15]
	s_mov_b32 m0, s38
	ds_read_b128 v[186:189], v172 offset:49152
	ds_read_b128 v[190:193], v172 offset:50176
	ds_read_b128 v[194:197], v172 offset:51200
	ds_read_b128 v[198:201], v172 offset:52224
	ds_read_b128 v[202:205], v172 offset:53248
	ds_read_b128 v[210:213], v172 offset:54272
	ds_read_b128 v[214:217], v172 offset:55296
	ds_read_b128 v[218:221], v172 offset:56320
	global_load_lds_dwordx4 v[166:167], off
	s_add_i32 m0, s38, 0x2000
	s_add_u32 s36, s36, 0x80080
	v_lshl_add_u64 v[166:167], v[206:207], 0, s[14:15]
	s_addc_u32 s37, s37, 0
	s_add_i32 s38, s59, s40
	global_load_lds_dwordx4 v[166:167], off
	v_lshl_add_u64 v[166:167], s[36:37], 0, v[150:151]
	s_mov_b32 m0, s38
	s_nop 0
	global_load_lds_dwordx4 v[166:167], off
	v_lshl_add_u64 v[166:167], s[36:37], 0, v[146:147]
	s_add_i32 m0, s38, 0x2000
	s_nop 0
	global_load_lds_dwordx4 v[166:167], off
	v_lshl_add_u64 v[166:167], v[222:223], 0, s[14:15]
	s_mov_b32 m0, s48
	s_nop 0
	global_load_lds_dwordx4 v[166:167], off
	v_lshl_add_u64 v[166:167], v[224:225], 0, s[14:15]
	s_mov_b32 m0, s49
	s_nop 0
	global_load_lds_dwordx4 v[166:167], off
	s_waitcnt vmcnt(8)
	s_waitcnt lgkmcnt(0)
	s_barrier
	s_setprio 1
	s_waitcnt lgkmcnt(0)
	v_mfma_f32_16x16x32_bf16 v[62:65], v[66:69], v[186:189], v[62:65]
	v_mfma_f32_16x16x32_bf16 v[58:61], v[74:77], v[186:189], v[58:61]
	v_mfma_f32_16x16x32_bf16 v[46:49], v[66:69], v[194:197], v[46:49]
	v_mfma_f32_16x16x32_bf16 v[42:45], v[74:77], v[194:197], v[42:45]
	v_mfma_f32_16x16x32_bf16 v[30:33], v[66:69], v[202:205], v[30:33]
	v_mfma_f32_16x16x32_bf16 v[26:29], v[74:77], v[202:205], v[26:29]
	v_mfma_f32_16x16x32_bf16 v[14:17], v[66:69], v[214:217], v[14:17]
	v_mfma_f32_16x16x32_bf16 v[10:13], v[74:77], v[214:217], v[10:13]
	v_mfma_f32_16x16x32_bf16 v[62:65], v[70:73], v[190:193], v[62:65]
	v_mfma_f32_16x16x32_bf16 v[58:61], v[78:81], v[190:193], v[58:61]
	v_mfma_f32_16x16x32_bf16 v[46:49], v[70:73], v[198:201], v[46:49]
	v_mfma_f32_16x16x32_bf16 v[42:45], v[78:81], v[198:201], v[42:45]
	v_mfma_f32_16x16x32_bf16 v[30:33], v[70:73], v[210:213], v[30:33]
	v_mfma_f32_16x16x32_bf16 v[26:29], v[78:81], v[210:213], v[26:29]
	v_mfma_f32_16x16x32_bf16 v[14:17], v[70:73], v[218:221], v[14:17]
	v_mfma_f32_16x16x32_bf16 v[10:13], v[78:81], v[218:221], v[10:13]
	s_setprio 0
	s_setprio 1
	v_mfma_f32_16x16x32_bf16 v[54:57], v[162:165], v[186:189], v[54:57]
	v_mfma_f32_16x16x32_bf16 v[50:53], v[178:181], v[186:189], v[50:53]
	v_mfma_f32_16x16x32_bf16 v[38:41], v[162:165], v[194:197], v[38:41]
	v_mfma_f32_16x16x32_bf16 v[34:37], v[178:181], v[194:197], v[34:37]
	v_mfma_f32_16x16x32_bf16 v[22:25], v[162:165], v[202:205], v[22:25]
	v_mfma_f32_16x16x32_bf16 v[18:21], v[178:181], v[202:205], v[18:21]
	v_mfma_f32_16x16x32_bf16 v[6:9], v[162:165], v[214:217], v[6:9]
	v_mfma_f32_16x16x32_bf16 v[2:5], v[178:181], v[214:217], v[2:5]
	v_mfma_f32_16x16x32_bf16 v[54:57], v[174:177], v[190:193], v[54:57]
	v_mfma_f32_16x16x32_bf16 v[50:53], v[182:185], v[190:193], v[50:53]
	v_mfma_f32_16x16x32_bf16 v[38:41], v[174:177], v[198:201], v[38:41]
	v_mfma_f32_16x16x32_bf16 v[34:37], v[182:185], v[198:201], v[34:37]
	v_mfma_f32_16x16x32_bf16 v[22:25], v[174:177], v[210:213], v[22:25]
	v_mfma_f32_16x16x32_bf16 v[18:21], v[182:185], v[210:213], v[18:21]
	v_mfma_f32_16x16x32_bf16 v[6:9], v[174:177], v[218:221], v[6:9]
	v_mfma_f32_16x16x32_bf16 v[2:5], v[182:185], v[218:221], v[2:5]
	s_setprio 0
	s_barrier
	s_add_i32 s57, s57, 2
	s_add_u32 s2, s2, 0x100
	s_addc_u32 s3, s3, 0
	s_add_u32 s55, s55, 0x100
	s_addc_u32 s56, s56, 0
	s_cmp_gt_u32 s57, 29
	s_cbranch_scc1 .Lpeel_exit_14
	.p2align 6

; #define PG8_STAGE(bufoff, gbase, voff) do { _Pragma("unroll") for (int _i = 0; _i < 2; ++_i) \
;         __builtin_amdgcn_global_load_lds((const unsigned*)((const char*)(gbase) + (voff)[_i]), (PG8_LAS unsigned*)(lds + (bufoff) + ldsw + _i * 8192), 16, 0, 0); } while (0)
; #define PG8_LDA(dst, b, h) do { _Pragma("unroll") for (int m = 0; m < 4; ++m) _Pragma("unroll") for (int k = 0; k < 2; ++k) dst[m][k] = *(const PG8_LAS bf16x8*)(lds + PG8_SA(b, h) + aoff + m * 2048 + k * 1024); } while (0)
; #define PG8_LDB(dst, b, h) do { _Pragma("unroll") for (int n = 0; n < 2; ++n) _Pragma("unroll") for (int k = 0; k < 2; ++k) dst[n][k] = *(const PG8_LAS bf16x8*)(lds + PG8_SB(b, h) + boff + n * 2048 + k * 1024); } while (0)
; #define PG8_MMA(ai, bj, At, Bt) do { __builtin_amdgcn_s_setprio(1); _Pragma("unroll") for (int m = 0; m < 4; ++m) _Pragma("unroll") for (int n = 0; n < 2; ++n) _Pragma("unroll") for (int k = 0; k < 2; ++k) \
;         acc[ai][bj][m][n] = __builtin_amdgcn_mfma_f32_16x16x32_bf16(Bt[n][k], At[m][k], acc[ai][bj][m][n], 0, 0, 0); __builtin_amdgcn_s_setprio(0); } while (0)
; #define PG8_WAIT_V(n) asm volatile("s_waitcnt vmcnt(" #n ")" ::: "memory")
; #define PG8_WAIT_L(n) asm volatile("s_waitcnt lgkmcnt(" #n ")" ::: "memory")
; #define PG8_BAR __builtin_amdgcn_s_barrier()
; #define PG8_SCHED __builtin_amdgcn_sched_barrier(0)
;     __host__ __device__ bool next(int i, Unit& u) const {
;         const long L = (long)i * G + c; if (L >= nwg) return false;
;         int wgid = (int)L; { const int q = nwg / NXCD, r = nwg % NXCD, xcd = wgid % NXCD, off = wgid / NXCD; wgid = (xcd < r ? xcd * (q + 1) : r * (q + 1) + (xcd - r) * q) + off; }
;         const int nig = WGM * nN, gid = wgid / nig, fm = gid * WGM, gsz = (nM - fm) < WGM ? (nM - fm) : WGM;
;         u.pm = fm + ((wgid % nig) % gsz); u.pn = (wgid % nig) / gsz; return true;
;     }
; template <class Epi, class Sched, bool ALIGN_EPI = false, bool SP2 = false>
; __device__ __forceinline__ void gemm_phase(PG8_LAS unsigned char* lds, const Gemm g, const Sched& S, const Epi& E) {
;     ...
;             PG8_LDB(B0, 0, 0); PG8_LDB(B1, 0, 1); PG8_SCHED; PG8_LDA(At, 0, 0); PG8_STAGE(PG8_SA(1, 1), a1 + hstepA, voffA);
;             PG8_WAIT_V(8); PG8_WAIT_L(0); PG8_BAR; PG8_MMA(0, 0, At, B0); PG8_MMA(0, 1, At, B1); PG8_BAR; PG8_SCHED;
.LBB0_1484:
	s_mov_b32 s100, s22
	s_mov_b32 s101, s23
	s_mov_b32 s51, s24
	s_mov_b32 s52, s25
	s_add_u32 s22, s22, 0x80080
	s_addc_u32 s23, s23, 0
	s_add_u32 s48, s24, 0x100
	s_addc_u32 s49, s25, 0
	ds_read_b128 v[154:157], v150
	ds_read_b128 v[158:161], v150 offset:1024
	ds_read_b128 v[162:165], v150 offset:2048
	ds_read_b128 v[166:169], v150 offset:3072
	ds_read_b128 v[170:173], v151
	ds_read_b128 v[174:177], v151 offset:1024
	ds_read_b128 v[178:181], v151 offset:2048
	ds_read_b128 v[182:185], v151 offset:3072
	s_add_u32 s24, s22, 0xfff80080
	s_addc_u32 s25, s23, -1
	s_mov_b32 s27, s25
	s_mov_b32 s26, s24
	s_mov_b32 s25, s49
	s_mov_b32 s24, s48
	v_lshl_add_u64 v[146:147], s[22:23], 0, v[138:139]
	s_add_i32 m0, s21, 0xc000
	ds_read_b128 v[186:189], v152
	ds_read_b128 v[190:193], v152 offset:1024
	ds_read_b128 v[194:197], v152 offset:2048
	ds_read_b128 v[198:201], v152 offset:3072
	ds_read_b128 v[202:205], v152 offset:4096
	ds_read_b128 v[210:213], v152 offset:5120
	ds_read_b128 v[214:217], v152 offset:6144
	ds_read_b128 v[218:221], v152 offset:7168
	global_load_lds_dwordx4 v[146:147], off
	v_lshl_add_u64 v[146:147], s[22:23], 0, v[140:141]
	s_add_i32 m0, s21, 0xe000
	s_nop 0
	global_load_lds_dwordx4 v[146:147], off
	s_add_i32 s38, s38, 1
	s_mul_i32 s4, s38, s41
	s_mul_hi_u32 s5, s38, s28
	s_add_i32 s5, s5, s4
	s_mul_i32 s4, s38, s28
	s_add_u32 s14, s4, s70
	s_addc_u32 s15, s5, s33
	v_cmp_gt_i64_e32 vcc, s[14:15], v[144:145]
	v_cmp_lt_i64_e64 s[4:5], s[14:15], v[142:143]
	s_cbranch_vccnz .LBB0_1486
	s_ashr_i32 s10, s14, 31
	s_lshr_b32 s10, s10, 29
	s_add_i32 s10, s14, s10
	s_ashr_i32 s11, s10, 3
	s_and_b32 s10, s10, -8
	s_sub_i32 s10, s14, s10
	s_cmp_lt_i32 s10, 0
	s_cselect_b32 s12, s34, 0x370
	s_mul_i32 s10, s12, s10
	s_add_i32 s10, s10, s11
	s_mul_hi_i32 s11, s10, 0x2e8ba2e9
	s_lshr_b32 s12, s11, 31
	s_ashr_i32 s11, s11, 5
	s_add_i32 s11, s11, s12
	s_lshl_b32 s12, s11, 2
	s_sub_i32 s13, 0xa0, s12
	s_min_i32 s13, s13, 4
	s_abs_i32 s14, s13
	v_cvt_f32_u32_e32 v2, s14
	s_sub_i32 s16, 0, s14
	s_mulk_i32 s11, 0xb0
	s_sub_i32 s11, s10, s11
	v_rcp_iflag_f32_e32 v2, v2
	s_abs_i32 s10, s11
	s_xor_b32 s15, s11, s13
	s_ashr_i32 s15, s15, 31
	v_mul_f32_e32 v2, 0x4f7ffffe, v2
	v_cvt_u32_f32_e32 v2, v2
	s_nop 0
	v_readfirstlane_b32 s17, v2
	s_mul_i32 s16, s16, s17
	s_mul_hi_u32 s16, s17, s16
	s_add_i32 s17, s17, s16
	s_mul_hi_u32 s16, s10, s17
	s_mul_i32 s17, s16, s14
	s_sub_i32 s10, s10, s17
	s_add_i32 s98, s16, 1
	s_sub_i32 s17, s10, s14
	s_cmp_ge_u32 s10, s14
	s_cselect_b32 s16, s98, s16
	s_cselect_b32 s10, s17, s10
	s_add_i32 s17, s16, 1
	s_cmp_ge_u32 s10, s14
	s_cselect_b32 s10, s17, s16
	s_xor_b32 s10, s10, s15
	s_sub_i32 s10, s10, s15
	s_mul_i32 s13, s10, s13
	s_sub_i32 s11, s11, s13
	s_add_i32 s12, s11, s12
.LBB0_1486:
	s_ashr_i32 s13, s12, 31
	s_lshl_b64 s[14:15], s[12:13], 20
	s_add_u32 s14, s86, s14
	s_addc_u32 s15, s87, s15
	s_and_b64 s[16:17], s[4:5], exec
	s_cselect_b32 s13, s15, s101
	s_cselect_b32 s46, s14, s100
	s_ashr_i32 s11, s10, 31
	s_lshl_b64 s[16:17], s[10:11], 20
	s_add_u32 s16, s29, s16
	s_addc_u32 s17, s30, s17
	s_and_b64 s[98:99], s[4:5], exec
	s_cselect_b32 s11, s17, s52
	s_cselect_b32 s47, s16, s51
	s_mov_b32 s50, -2
	s_waitcnt vmcnt(8)
	s_waitcnt lgkmcnt(0)
	s_barrier
	s_setprio 1
	s_waitcnt lgkmcnt(0)
	v_mfma_f32_16x16x32_bf16 v[126:129], v[154:157], v[186:189], 0
	v_mfma_f32_16x16x32_bf16 v[122:125], v[162:165], v[186:189], 0
	v_mfma_f32_16x16x32_bf16 v[110:113], v[154:157], v[194:197], 0
	v_mfma_f32_16x16x32_bf16 v[106:109], v[162:165], v[194:197], 0
	v_mfma_f32_16x16x32_bf16 v[94:97], v[154:157], v[202:205], 0
	v_mfma_f32_16x16x32_bf16 v[90:93], v[162:165], v[202:205], 0
	v_mfma_f32_16x16x32_bf16 v[78:81], v[154:157], v[214:217], 0
	v_mfma_f32_16x16x32_bf16 v[74:77], v[162:165], v[214:217], 0
	v_mfma_f32_16x16x32_bf16 v[126:129], v[158:161], v[190:193], v[126:129]
	v_mfma_f32_16x16x32_bf16 v[122:125], v[166:169], v[190:193], v[122:125]
	v_mfma_f32_16x16x32_bf16 v[110:113], v[158:161], v[198:201], v[110:113]
	v_mfma_f32_16x16x32_bf16 v[106:109], v[166:169], v[198:201], v[106:109]
	v_mfma_f32_16x16x32_bf16 v[94:97], v[158:161], v[210:213], v[94:97]
	v_mfma_f32_16x16x32_bf16 v[90:93], v[166:169], v[210:213], v[90:93]
	v_mfma_f32_16x16x32_bf16 v[78:81], v[158:161], v[218:221], v[78:81]
	v_mfma_f32_16x16x32_bf16 v[74:77], v[166:169], v[218:221], v[74:77]
	s_setprio 0
	s_setprio 1
	v_mfma_f32_16x16x32_bf16 v[118:121], v[170:173], v[186:189], 0
	v_mfma_f32_16x16x32_bf16 v[114:117], v[178:181], v[186:189], 0
	v_mfma_f32_16x16x32_bf16 v[102:105], v[170:173], v[194:197], 0
	v_mfma_f32_16x16x32_bf16 v[98:101], v[178:181], v[194:197], 0
	v_mfma_f32_16x16x32_bf16 v[86:89], v[170:173], v[202:205], 0
	v_mfma_f32_16x16x32_bf16 v[82:85], v[178:181], v[202:205], 0
	v_mfma_f32_16x16x32_bf16 v[70:73], v[170:173], v[214:217], 0
	v_mfma_f32_16x16x32_bf16 v[66:69], v[178:181], v[214:217], 0
	v_mfma_f32_16x16x32_bf16 v[118:121], v[174:177], v[190:193], v[118:121]
	v_mfma_f32_16x16x32_bf16 v[114:117], v[182:185], v[190:193], v[114:117]
	v_mfma_f32_16x16x32_bf16 v[102:105], v[174:177], v[198:201], v[102:105]
	v_mfma_f32_16x16x32_bf16 v[98:101], v[182:185], v[198:201], v[98:101]
	v_mfma_f32_16x16x32_bf16 v[86:89], v[174:177], v[210:213], v[86:89]
	v_mfma_f32_16x16x32_bf16 v[82:85], v[182:185], v[210:213], v[82:85]
	v_mfma_f32_16x16x32_bf16 v[70:73], v[174:177], v[218:221], v[70:73]
	v_mfma_f32_16x16x32_bf16 v[66:69], v[182:185], v[218:221], v[66:69]
	s_setprio 0
	s_barrier
; #define PG8_STAGE(bufoff, gbase, voff) do { _Pragma("unroll") for (int _i = 0; _i < 2; ++_i) \
;         __builtin_amdgcn_global_load_lds((const unsigned*)((const char*)(gbase) + (voff)[_i]), (PG8_LAS unsigned*)(lds + (bufoff) + ldsw + _i * 8192), 16, 0, 0); } while (0)
; #define PG8_LDA(dst, b, h) do { _Pragma("unroll") for (int m = 0; m < 4; ++m) _Pragma("unroll") for (int k = 0; k < 2; ++k) dst[m][k] = *(const PG8_LAS bf16x8*)(lds + PG8_SA(b, h) + aoff + m * 2048 + k * 1024); } while (0)
; #define PG8_LDB(dst, b, h) do { _Pragma("unroll") for (int n = 0; n < 2; ++n) _Pragma("unroll") for (int k = 0; k < 2; ++k) dst[n][k] = *(const PG8_LAS bf16x8*)(lds + PG8_SB(b, h) + boff + n * 2048 + k * 1024); } while (0)
; #define PG8_MMA(ai, bj, At, Bt) do { __builtin_amdgcn_s_setprio(1); _Pragma("unroll") for (int m = 0; m < 4; ++m) _Pragma("unroll") for (int n = 0; n < 2; ++n) _Pragma("unroll") for (int k = 0; k < 2; ++k) \
;         acc[ai][bj][m][n] = __builtin_amdgcn_mfma_f32_16x16x32_bf16(Bt[n][k], At[m][k], acc[ai][bj][m][n], 0, 0, 0); __builtin_amdgcn_s_setprio(0); } while (0)
; #define PG8_WAIT_V(n) asm volatile("s_waitcnt vmcnt(" #n ")" ::: "memory")
; #define PG8_WAIT_L(n) asm volatile("s_waitcnt lgkmcnt(" #n ")" ::: "memory")
; #define PG8_BAR __builtin_amdgcn_s_barrier()
; #define PG8_SCHED __builtin_amdgcn_sched_barrier(0)
; template <class Epi, class Sched, bool ALIGN_EPI = false, bool SP2 = false>
; __device__ __forceinline__ void gemm_phase(PG8_LAS unsigned char* lds, const Gemm g, const Sched& S, const Epi& E) {
;     ...
;             PG8_LDA(At, 0, 1); PG8_STAGE(PG8_SB(0, 0), b2, voffB); PG8_STAGE(PG8_SB(0, 1), b2 + hstepB, voffB); PG8_STAGE(PG8_SA(0, 0), a2, voffA);
;             PG8_WAIT_V(8); PG8_WAIT_L(0); PG8_BAR; PG8_MMA(1, 0, At, B0); PG8_MMA(1, 1, At, B1); PG8_BAR; PG8_SCHED;
;             PG8_LDB(B0, 1, 0); PG8_LDB(B1, 1, 1); PG8_SCHED; PG8_LDA(At, 1, 0); PG8_STAGE(PG8_SA(0, 1), a2 + hstepA, voffA);
	s_add_i32 s51, s42, s31
	v_lshl_add_u64 v[146:147], s[24:25], 0, v[134:135]
	s_mov_b32 m0, s51
	ds_read_b128 v[186:189], v152 offset:16384
	ds_read_b128 v[190:193], v152 offset:17408
	ds_read_b128 v[194:197], v152 offset:18432
	ds_read_b128 v[198:201], v152 offset:19456
	ds_read_b128 v[202:205], v152 offset:20480
	ds_read_b128 v[210:213], v152 offset:21504
	ds_read_b128 v[214:217], v152 offset:22528
	ds_read_b128 v[218:221], v152 offset:23552
	global_load_lds_dwordx4 v[146:147], off
	s_add_i32 m0, s51, 0x2000
	s_add_u32 s52, s24, 0x80000
	v_lshl_add_u64 v[206:207], s[24:25], 0, v[130:131]
	s_addc_u32 s53, s25, 0
	s_add_i32 s51, s43, s31
	global_load_lds_dwordx4 v[206:207], off
	v_lshl_add_u64 v[222:223], s[52:53], 0, v[134:135]
	s_mov_b32 m0, s51
	v_lshl_add_u64 v[224:225], s[26:27], 0, v[132:133]
	global_load_lds_dwordx4 v[222:223], off
	v_lshl_add_u64 v[222:223], s[52:53], 0, v[130:131]
	s_add_i32 m0, s51, 0x2000
	s_nop 0
	global_load_lds_dwordx4 v[222:223], off
	v_lshl_add_u64 v[222:223], s[26:27], 0, v[136:137]
	s_mov_b32 m0, s21
	s_nop 0
	global_load_lds_dwordx4 v[222:223], off
	s_mov_b32 m0, s35
	s_nop 0
	global_load_lds_dwordx4 v[224:225], off
	s_waitcnt vmcnt(8)
	s_waitcnt lgkmcnt(0)
	s_barrier
	s_setprio 1
	s_waitcnt lgkmcnt(0)
	v_mfma_f32_16x16x32_bf16 v[62:65], v[154:157], v[186:189], 0
	v_mfma_f32_16x16x32_bf16 v[58:61], v[162:165], v[186:189], 0
	v_mfma_f32_16x16x32_bf16 v[46:49], v[154:157], v[194:197], 0
	v_mfma_f32_16x16x32_bf16 v[42:45], v[162:165], v[194:197], 0
	v_mfma_f32_16x16x32_bf16 v[30:33], v[154:157], v[202:205], 0
	v_mfma_f32_16x16x32_bf16 v[26:29], v[162:165], v[202:205], 0
	v_mfma_f32_16x16x32_bf16 v[14:17], v[154:157], v[214:217], 0
	v_mfma_f32_16x16x32_bf16 v[10:13], v[162:165], v[214:217], 0
	v_mfma_f32_16x16x32_bf16 v[62:65], v[158:161], v[190:193], v[62:65]
	v_mfma_f32_16x16x32_bf16 v[58:61], v[166:169], v[190:193], v[58:61]
	v_mfma_f32_16x16x32_bf16 v[46:49], v[158:161], v[198:201], v[46:49]
	v_mfma_f32_16x16x32_bf16 v[42:45], v[166:169], v[198:201], v[42:45]
	v_mfma_f32_16x16x32_bf16 v[30:33], v[158:161], v[210:213], v[30:33]
	v_mfma_f32_16x16x32_bf16 v[26:29], v[166:169], v[210:213], v[26:29]
	v_mfma_f32_16x16x32_bf16 v[14:17], v[158:161], v[218:221], v[14:17]
	v_mfma_f32_16x16x32_bf16 v[10:13], v[166:169], v[218:221], v[10:13]
	s_setprio 0
	s_setprio 1
	v_mfma_f32_16x16x32_bf16 v[54:57], v[170:173], v[186:189], 0
	v_mfma_f32_16x16x32_bf16 v[50:53], v[178:181], v[186:189], 0
	v_mfma_f32_16x16x32_bf16 v[38:41], v[170:173], v[194:197], 0
	v_mfma_f32_16x16x32_bf16 v[34:37], v[178:181], v[194:197], 0
	v_mfma_f32_16x16x32_bf16 v[22:25], v[170:173], v[202:205], 0
	v_mfma_f32_16x16x32_bf16 v[18:21], v[178:181], v[202:205], 0
	v_mfma_f32_16x16x32_bf16 v[6:9], v[170:173], v[214:217], 0
	v_mfma_f32_16x16x32_bf16 v[2:5], v[178:181], v[214:217], 0
	v_mfma_f32_16x16x32_bf16 v[54:57], v[174:177], v[190:193], v[54:57]
	v_mfma_f32_16x16x32_bf16 v[50:53], v[182:185], v[190:193], v[50:53]
	v_mfma_f32_16x16x32_bf16 v[38:41], v[174:177], v[198:201], v[38:41]
	v_mfma_f32_16x16x32_bf16 v[34:37], v[182:185], v[198:201], v[34:37]
	v_mfma_f32_16x16x32_bf16 v[22:25], v[174:177], v[210:213], v[22:25]
	v_mfma_f32_16x16x32_bf16 v[18:21], v[182:185], v[210:213], v[18:21]
	v_mfma_f32_16x16x32_bf16 v[6:9], v[174:177], v[218:221], v[6:9]
	v_mfma_f32_16x16x32_bf16 v[2:5], v[182:185], v[218:221], v[2:5]
	s_setprio 0
	s_barrier
	s_add_i32 s51, 0, 0x18000
	v_add_u32_e32 v153, s51, v148
	s_add_i32 s52, 0, 0x1c000
	ds_read_b128 v[154:157], v153
	ds_read_b128 v[158:161], v153 offset:1024
	ds_read_b128 v[162:165], v153 offset:2048
	ds_read_b128 v[166:169], v153 offset:3072
	v_add_u32_e32 v153, s52, v148
	ds_read_b128 v[170:173], v153
	ds_read_b128 v[174:177], v153 offset:1024
	ds_read_b128 v[178:181], v153 offset:2048
	ds_read_b128 v[182:185], v153 offset:3072
	s_add_u32 s26, s26, 0x80000
	s_addc_u32 s27, s27, 0
	s_mov_b32 m0, s36
	v_lshl_add_u64 v[226:227], s[26:27], 0, v[136:137]
	ds_read_b128 v[186:189], v152 offset:32768
	ds_read_b128 v[190:193], v152 offset:33792
	ds_read_b128 v[194:197], v152 offset:34816
	ds_read_b128 v[198:201], v152 offset:35840
	ds_read_b128 v[202:205], v152 offset:36864
	ds_read_b128 v[210:213], v152 offset:37888
	ds_read_b128 v[214:217], v152 offset:38912
	ds_read_b128 v[218:221], v152 offset:39936
	global_load_lds_dwordx4 v[226:227], off
	v_lshl_add_u64 v[226:227], s[26:27], 0, v[132:133]
	s_mov_b32 m0, s37
	s_nop 0
	global_load_lds_dwordx4 v[226:227], off
	s_waitcnt vmcnt(8)
	s_waitcnt lgkmcnt(0)
	s_barrier
; #define PG8_STAGE(bufoff, gbase, voff) do { _Pragma("unroll") for (int _i = 0; _i < 2; ++_i) \
;         __builtin_amdgcn_global_load_lds((const unsigned*)((const char*)(gbase) + (voff)[_i]), (PG8_LAS unsigned*)(lds + (bufoff) + ldsw + _i * 8192), 16, 0, 0); } while (0)
; #define PG8_LDA(dst, b, h) do { _Pragma("unroll") for (int m = 0; m < 4; ++m) _Pragma("unroll") for (int k = 0; k < 2; ++k) dst[m][k] = *(const PG8_LAS bf16x8*)(lds + PG8_SA(b, h) + aoff + m * 2048 + k * 1024); } while (0)
; #define PG8_MMA(ai, bj, At, Bt) do { __builtin_amdgcn_s_setprio(1); _Pragma("unroll") for (int m = 0; m < 4; ++m) _Pragma("unroll") for (int n = 0; n < 2; ++n) _Pragma("unroll") for (int k = 0; k < 2; ++k) \
;         acc[ai][bj][m][n] = __builtin_amdgcn_mfma_f32_16x16x32_bf16(Bt[n][k], At[m][k], acc[ai][bj][m][n], 0, 0, 0); __builtin_amdgcn_s_setprio(0); } while (0)
; #define PG8_WAIT_V(n) asm volatile("s_waitcnt vmcnt(" #n ")" ::: "memory")
; #define PG8_WAIT_L(n) asm volatile("s_waitcnt lgkmcnt(" #n ")" ::: "memory")
; #define PG8_BAR __builtin_amdgcn_s_barrier()
; #define PG8_SCHED __builtin_amdgcn_sched_barrier(0)
; template <class Epi, class Sched, bool ALIGN_EPI = false, bool SP2 = false>
; __device__ __forceinline__ void gemm_phase(PG8_LAS unsigned char* lds, const Gemm g, const Sched& S, const Epi& E) {
;     ...
;             PG8_WAIT_V(8); PG8_WAIT_L(0); PG8_BAR; PG8_MMA(0, 0, At, B0); PG8_MMA(0, 1, At, B1); PG8_BAR; PG8_SCHED;
;             PG8_LDA(At, 1, 1); PG8_STAGE(PG8_SB(1, 0), b3, voffB); PG8_STAGE(PG8_SB(1, 1), b3 + hstepB, voffB); PG8_STAGE(PG8_SA(1, 0), a3, voffA);
;             PG8_WAIT_V(8); PG8_WAIT_L(0); PG8_BAR; PG8_MMA(1, 0, At, B0); PG8_MMA(1, 1, At, B1); PG8_BAR; PG8_SCHED;
	s_setprio 1
	s_waitcnt lgkmcnt(0)
	v_mfma_f32_16x16x32_bf16 v[126:129], v[154:157], v[186:189], v[126:129]
	v_mfma_f32_16x16x32_bf16 v[122:125], v[162:165], v[186:189], v[122:125]
	v_mfma_f32_16x16x32_bf16 v[110:113], v[154:157], v[194:197], v[110:113]
	v_mfma_f32_16x16x32_bf16 v[106:109], v[162:165], v[194:197], v[106:109]
	v_mfma_f32_16x16x32_bf16 v[94:97], v[154:157], v[202:205], v[94:97]
	v_mfma_f32_16x16x32_bf16 v[90:93], v[162:165], v[202:205], v[90:93]
	v_mfma_f32_16x16x32_bf16 v[78:81], v[154:157], v[214:217], v[78:81]
	v_mfma_f32_16x16x32_bf16 v[74:77], v[162:165], v[214:217], v[74:77]
	v_mfma_f32_16x16x32_bf16 v[126:129], v[158:161], v[190:193], v[126:129]
	v_mfma_f32_16x16x32_bf16 v[122:125], v[166:169], v[190:193], v[122:125]
	v_mfma_f32_16x16x32_bf16 v[110:113], v[158:161], v[198:201], v[110:113]
	v_mfma_f32_16x16x32_bf16 v[106:109], v[166:169], v[198:201], v[106:109]
	v_mfma_f32_16x16x32_bf16 v[94:97], v[158:161], v[210:213], v[94:97]
	v_mfma_f32_16x16x32_bf16 v[90:93], v[166:169], v[210:213], v[90:93]
	v_mfma_f32_16x16x32_bf16 v[78:81], v[158:161], v[218:221], v[78:81]
	v_mfma_f32_16x16x32_bf16 v[74:77], v[166:169], v[218:221], v[74:77]
	s_setprio 0
	s_setprio 1
	v_mfma_f32_16x16x32_bf16 v[118:121], v[170:173], v[186:189], v[118:121]
	v_mfma_f32_16x16x32_bf16 v[114:117], v[178:181], v[186:189], v[114:117]
	v_mfma_f32_16x16x32_bf16 v[102:105], v[170:173], v[194:197], v[102:105]
	v_mfma_f32_16x16x32_bf16 v[98:101], v[178:181], v[194:197], v[98:101]
	v_mfma_f32_16x16x32_bf16 v[86:89], v[170:173], v[202:205], v[86:89]
	v_mfma_f32_16x16x32_bf16 v[82:85], v[178:181], v[202:205], v[82:85]
	v_mfma_f32_16x16x32_bf16 v[70:73], v[170:173], v[214:217], v[70:73]
	v_mfma_f32_16x16x32_bf16 v[66:69], v[178:181], v[214:217], v[66:69]
	v_mfma_f32_16x16x32_bf16 v[118:121], v[174:177], v[190:193], v[118:121]
	v_mfma_f32_16x16x32_bf16 v[114:117], v[182:185], v[190:193], v[114:117]
	v_mfma_f32_16x16x32_bf16 v[102:105], v[174:177], v[198:201], v[102:105]
	v_mfma_f32_16x16x32_bf16 v[98:101], v[182:185], v[198:201], v[98:101]
	v_mfma_f32_16x16x32_bf16 v[86:89], v[174:177], v[210:213], v[86:89]
	v_mfma_f32_16x16x32_bf16 v[82:85], v[182:185], v[210:213], v[82:85]
	v_mfma_f32_16x16x32_bf16 v[70:73], v[174:177], v[218:221], v[70:73]
	v_mfma_f32_16x16x32_bf16 v[66:69], v[182:185], v[218:221], v[66:69]
	s_setprio 0
	s_barrier
	s_add_i32 s26, s51, s31
	v_lshl_add_u64 v[146:147], v[146:147], 0, s[2:3]
	s_mov_b32 m0, s26
	ds_read_b128 v[186:189], v152 offset:49152
	ds_read_b128 v[190:193], v152 offset:50176
	ds_read_b128 v[194:197], v152 offset:51200
	ds_read_b128 v[198:201], v152 offset:52224
	ds_read_b128 v[202:205], v152 offset:53248
	ds_read_b128 v[210:213], v152 offset:54272
	ds_read_b128 v[214:217], v152 offset:55296
	ds_read_b128 v[218:221], v152 offset:56320
	global_load_lds_dwordx4 v[146:147], off
	s_add_i32 m0, s26, 0x2000
	s_add_u32 s24, s24, 0x80080
	v_lshl_add_u64 v[146:147], v[206:207], 0, s[2:3]
	s_addc_u32 s25, s25, 0
	s_add_i32 s26, s52, s31
	global_load_lds_dwordx4 v[146:147], off
	v_lshl_add_u64 v[146:147], s[24:25], 0, v[134:135]
	s_mov_b32 m0, s26
	s_nop 0
	global_load_lds_dwordx4 v[146:147], off
	v_lshl_add_u64 v[146:147], s[24:25], 0, v[130:131]
	s_add_i32 m0, s26, 0x2000
	s_nop 0
	global_load_lds_dwordx4 v[146:147], off
	v_lshl_add_u64 v[146:147], v[222:223], 0, s[2:3]
	s_mov_b32 m0, s39
	s_nop 0
	global_load_lds_dwordx4 v[146:147], off
	v_lshl_add_u64 v[146:147], v[224:225], 0, s[2:3]
	s_mov_b32 m0, s40
	s_nop 0
	global_load_lds_dwordx4 v[146:147], off
	s_waitcnt vmcnt(8)
	s_waitcnt lgkmcnt(0)
	s_barrier
	s_setprio 1
	s_waitcnt lgkmcnt(0)
	v_mfma_f32_16x16x32_bf16 v[62:65], v[154:157], v[186:189], v[62:65]
	v_mfma_f32_16x16x32_bf16 v[58:61], v[162:165], v[186:189], v[58:61]
	v_mfma_f32_16x16x32_bf16 v[46:49], v[154:157], v[194:197], v[46:49]
	v_mfma_f32_16x16x32_bf16 v[42:45], v[162:165], v[194:197], v[42:45]
	v_mfma_f32_16x16x32_bf16 v[30:33], v[154:157], v[202:205], v[30:33]
	v_mfma_f32_16x16x32_bf16 v[26:29], v[162:165], v[202:205], v[26:29]
	v_mfma_f32_16x16x32_bf16 v[14:17], v[154:157], v[214:217], v[14:17]
	v_mfma_f32_16x16x32_bf16 v[10:13], v[162:165], v[214:217], v[10:13]
	v_mfma_f32_16x16x32_bf16 v[62:65], v[158:161], v[190:193], v[62:65]
	v_mfma_f32_16x16x32_bf16 v[58:61], v[166:169], v[190:193], v[58:61]
	v_mfma_f32_16x16x32_bf16 v[46:49], v[158:161], v[198:201], v[46:49]
	v_mfma_f32_16x16x32_bf16 v[42:45], v[166:169], v[198:201], v[42:45]
	v_mfma_f32_16x16x32_bf16 v[30:33], v[158:161], v[210:213], v[30:33]
	v_mfma_f32_16x16x32_bf16 v[26:29], v[166:169], v[210:213], v[26:29]
	v_mfma_f32_16x16x32_bf16 v[14:17], v[158:161], v[218:221], v[14:17]
	v_mfma_f32_16x16x32_bf16 v[10:13], v[166:169], v[218:221], v[10:13]
	s_setprio 0
	s_setprio 1
	v_mfma_f32_16x16x32_bf16 v[54:57], v[170:173], v[186:189], v[54:57]
	v_mfma_f32_16x16x32_bf16 v[50:53], v[178:181], v[186:189], v[50:53]
	v_mfma_f32_16x16x32_bf16 v[38:41], v[170:173], v[194:197], v[38:41]
	v_mfma_f32_16x16x32_bf16 v[34:37], v[178:181], v[194:197], v[34:37]
	v_mfma_f32_16x16x32_bf16 v[22:25], v[170:173], v[202:205], v[22:25]
	v_mfma_f32_16x16x32_bf16 v[18:21], v[178:181], v[202:205], v[18:21]
	v_mfma_f32_16x16x32_bf16 v[6:9], v[170:173], v[214:217], v[6:9]
	v_mfma_f32_16x16x32_bf16 v[2:5], v[178:181], v[214:217], v[2:5]
	v_mfma_f32_16x16x32_bf16 v[54:57], v[174:177], v[190:193], v[54:57]
	v_mfma_f32_16x16x32_bf16 v[50:53], v[182:185], v[190:193], v[50:53]
	v_mfma_f32_16x16x32_bf16 v[38:41], v[174:177], v[198:201], v[38:41]
	v_mfma_f32_16x16x32_bf16 v[34:37], v[182:185], v[198:201], v[34:37]
	v_mfma_f32_16x16x32_bf16 v[22:25], v[174:177], v[210:213], v[22:25]
	v_mfma_f32_16x16x32_bf16 v[18:21], v[182:185], v[210:213], v[18:21]
	v_mfma_f32_16x16x32_bf16 v[6:9], v[174:177], v[218:221], v[6:9]
	v_mfma_f32_16x16x32_bf16 v[2:5], v[182:185], v[218:221], v[2:5]
	s_setprio 0
	s_barrier
	s_add_i32 s50, s50, 2
	s_add_u32 s22, s22, 0x100
	s_addc_u32 s23, s23, 0
	s_add_u32 s48, s48, 0x100
	s_addc_u32 s49, s49, 0
	s_cmp_gt_u32 s50, 29
	s_cbranch_scc1 .Lpeel_exit_16
	.p2align 6

; #define PG8_STAGE(bufoff, gbase, voff) do { _Pragma("unroll") for (int _i = 0; _i < 2; ++_i) \
;         __builtin_amdgcn_global_load_lds((const unsigned*)((const char*)(gbase) + (voff)[_i]), (PG8_LAS unsigned*)(lds + (bufoff) + ldsw + _i * 8192), 16, 0, 0); } while (0)
; #define PG8_LDA(dst, b, h) do { _Pragma("unroll") for (int m = 0; m < 4; ++m) _Pragma("unroll") for (int k = 0; k < 2; ++k) dst[m][k] = *(const PG8_LAS bf16x8*)(lds + PG8_SA(b, h) + aoff + m * 2048 + k * 1024); } while (0)
; #define PG8_LDB(dst, b, h) do { _Pragma("unroll") for (int n = 0; n < 2; ++n) _Pragma("unroll") for (int k = 0; k < 2; ++k) dst[n][k] = *(const PG8_LAS bf16x8*)(lds + PG8_SB(b, h) + boff + n * 2048 + k * 1024); } while (0)
; #define PG8_MMA(ai, bj, At, Bt) do { __builtin_amdgcn_s_setprio(1); _Pragma("unroll") for (int m = 0; m < 4; ++m) _Pragma("unroll") for (int n = 0; n < 2; ++n) _Pragma("unroll") for (int k = 0; k < 2; ++k) \
;         acc[ai][bj][m][n] = __builtin_amdgcn_mfma_f32_16x16x32_bf16(Bt[n][k], At[m][k], acc[ai][bj][m][n], 0, 0, 0); __builtin_amdgcn_s_setprio(0); } while (0)
; #define PG8_WAIT_V(n) asm volatile("s_waitcnt vmcnt(" #n ")" ::: "memory")
; #define PG8_WAIT_L(n) asm volatile("s_waitcnt lgkmcnt(" #n ")" ::: "memory")
; #define PG8_BAR __builtin_amdgcn_s_barrier()
; #define PG8_SCHED __builtin_amdgcn_sched_barrier(0)
;     __host__ __device__ bool next(int i, Unit& u) const {
;         const long L = (long)i * G + c; if (L >= nwg) return false;
;         int wgid = (int)L; { const int q = nwg / NXCD, r = nwg % NXCD, xcd = wgid % NXCD, off = wgid / NXCD; wgid = (xcd < r ? xcd * (q + 1) : r * (q + 1) + (xcd - r) * q) + off; }
;         const int nig = WGM * nN, gid = wgid / nig, fm = gid * WGM, gsz = (nM - fm) < WGM ? (nM - fm) : WGM;
;         u.pm = fm + ((wgid % nig) % gsz); u.pn = (wgid % nig) / gsz; return true;
;     }
; template <class Epi, class Sched, bool ALIGN_EPI = false, bool SP2 = false>
; __device__ __forceinline__ void gemm_phase(PG8_LAS unsigned char* lds, const Gemm g, const Sched& S, const Epi& E) {
;     ...
;             PG8_LDB(B0, 0, 0); PG8_LDB(B1, 0, 1); PG8_SCHED; PG8_LDA(At, 0, 0); PG8_STAGE(PG8_SA(1, 1), a1 + hstepA, voffA);
;             PG8_WAIT_V(8); PG8_WAIT_L(0); PG8_BAR; PG8_MMA(0, 0, At, B0); PG8_MMA(0, 1, At, B1); PG8_BAR; PG8_SCHED;
.LBB0_1836:
	s_mov_b32 s100, s12
	s_mov_b32 s101, s13
	s_mov_b32 s58, s30
	s_mov_b32 s59, s31
	s_add_u32 s12, s12, 0x80080
	s_addc_u32 s13, s13, 0
	s_add_u32 s37, s30, 0x100
	s_addc_u32 s38, s31, 0
	ds_read_b128 v[160:163], v143
	ds_read_b128 v[164:167], v143 offset:1024
	ds_read_b128 v[168:171], v143 offset:2048
	ds_read_b128 v[172:175], v143 offset:3072
	ds_read_b128 v[176:179], v156
	ds_read_b128 v[180:183], v156 offset:1024
	ds_read_b128 v[184:187], v156 offset:2048
	ds_read_b128 v[188:191], v156 offset:3072
	s_add_u32 s30, s12, 0xfff80080
	s_addc_u32 s31, s13, -1
	s_mov_b32 s35, s31
	s_mov_b32 s34, s30
	s_mov_b32 s31, s38
	s_mov_b32 s30, s37
	v_lshl_add_u64 v[226:227], s[12:13], 0, v[148:149]
	s_add_i32 m0, s17, 0xc000
	ds_read_b128 v[192:195], v157
	ds_read_b128 v[196:199], v157 offset:1024
	ds_read_b128 v[200:203], v157 offset:2048
	ds_read_b128 v[204:207], v157 offset:3072
	ds_read_b128 v[210:213], v157 offset:4096
	ds_read_b128 v[214:217], v157 offset:5120
	ds_read_b128 v[218:221], v157 offset:6144
	ds_read_b128 v[222:225], v157 offset:7168
	global_load_lds_dwordx4 v[226:227], off
	v_lshl_add_u64 v[226:227], s[12:13], 0, v[150:151]
	s_add_i32 m0, s17, 0xe000
	s_nop 0
	global_load_lds_dwordx4 v[226:227], off
	s_add_i32 s44, s44, 1
	s_mul_i32 s8, s44, s48
	s_mul_hi_u32 s9, s44, s33
	s_add_i32 s9, s9, s8
	s_mul_i32 s8, s44, s33
	s_add_u32 s26, s8, s70
	s_addc_u32 s27, s9, s49
	v_cmp_gt_i64_e32 vcc, s[26:27], v[154:155]
	v_cmp_lt_i64_e64 s[8:9], s[26:27], v[152:153]
	s_cbranch_vccnz .LBB0_1838
	s_ashr_i32 s11, s26, 31
	s_lshr_b32 s11, s11, 29
	s_add_i32 s11, s26, s11
	s_ashr_i32 s22, s11, 3
	s_and_b32 s11, s11, -8
	s_sub_i32 s11, s26, s11
	s_lshr_b32 s23, s11, 31
	s_or_b32 s23, s23, 0x334
	s_mul_i32 s11, s23, s11
	s_add_i32 s11, s11, s22
	s_mul_hi_i32 s22, s11, 0x63e7063f
	s_lshr_b32 s23, s22, 31
	s_ashr_i32 s22, s22, 6
	s_add_i32 s22, s22, s23
	s_lshl_b32 s23, s22, 2
	s_sub_i32 s24, 0xa0, s23
	s_min_i32 s24, s24, 4
	s_abs_i32 s25, s24
	v_cvt_f32_u32_e32 v2, s25
	s_sub_i32 s27, 0, s25
	s_mulk_i32 s22, 0xa4
	s_sub_i32 s11, s11, s22
	v_rcp_iflag_f32_e32 v2, v2
	s_abs_i32 s22, s11
	s_xor_b32 s26, s11, s24
	s_ashr_i32 s26, s26, 31
	v_mul_f32_e32 v2, 0x4f7ffffe, v2
	v_cvt_u32_f32_e32 v2, v2
	s_nop 0
	v_readfirstlane_b32 s28, v2
	s_mul_i32 s27, s27, s28
	s_mul_hi_u32 s27, s28, s27
	s_add_i32 s28, s28, s27
	s_mul_hi_u32 s27, s22, s28
	s_mul_i32 s28, s27, s25
	s_sub_i32 s22, s22, s28
	s_add_i32 s29, s27, 1
	s_sub_i32 s28, s22, s25
	s_cmp_ge_u32 s22, s25
	s_cselect_b32 s27, s29, s27
	s_cselect_b32 s22, s28, s22
	s_add_i32 s28, s27, 1
	s_cmp_ge_u32 s22, s25
	s_cselect_b32 s22, s28, s27
	s_xor_b32 s22, s22, s26
	s_sub_i32 s22, s22, s26
	s_mul_i32 s24, s22, s24
	s_sub_i32 s11, s11, s24
	s_add_i32 s24, s11, s23
.LBB0_1838:
	s_ashr_i32 s25, s24, 31
	s_lshl_b64 s[26:27], s[24:25], 20
	s_add_u32 s26, s86, s26
	s_addc_u32 s27, s87, s27
	s_and_b64 s[28:29], s[8:9], exec
	s_cselect_b32 s11, s27, s101
	s_cselect_b32 s25, s26, s100
	s_ashr_i32 s23, s22, 31
	s_lshl_b64 s[28:29], s[22:23], 20
	v_readlane_b32 s98, v254, 2
	v_readlane_b32 s99, v254, 3
	s_add_u32 s28, s98, s28
	s_addc_u32 s29, s99, s29
	s_and_b64 s[98:99], s[8:9], exec
	s_cselect_b32 s23, s29, s59
	s_cselect_b32 s36, s28, s58
	s_mov_b32 s39, -2
	s_waitcnt vmcnt(8)
	s_waitcnt lgkmcnt(0)
	s_barrier
	s_setprio 1
	s_waitcnt lgkmcnt(0)
	v_mfma_f32_16x16x32_bf16 v[126:129], v[160:163], v[192:195], 0
	v_mfma_f32_16x16x32_bf16 v[122:125], v[168:171], v[192:195], 0
	v_mfma_f32_16x16x32_bf16 v[110:113], v[160:163], v[200:203], 0
	v_mfma_f32_16x16x32_bf16 v[106:109], v[168:171], v[200:203], 0
	v_mfma_f32_16x16x32_bf16 v[94:97], v[160:163], v[210:213], 0
	v_mfma_f32_16x16x32_bf16 v[90:93], v[168:171], v[210:213], 0
	v_mfma_f32_16x16x32_bf16 v[78:81], v[160:163], v[218:221], 0
	v_mfma_f32_16x16x32_bf16 v[74:77], v[168:171], v[218:221], 0
	v_mfma_f32_16x16x32_bf16 v[126:129], v[164:167], v[196:199], v[126:129]
	v_mfma_f32_16x16x32_bf16 v[122:125], v[172:175], v[196:199], v[122:125]
	v_mfma_f32_16x16x32_bf16 v[110:113], v[164:167], v[204:207], v[110:113]
	v_mfma_f32_16x16x32_bf16 v[106:109], v[172:175], v[204:207], v[106:109]
	v_mfma_f32_16x16x32_bf16 v[94:97], v[164:167], v[214:217], v[94:97]
	v_mfma_f32_16x16x32_bf16 v[90:93], v[172:175], v[214:217], v[90:93]
	v_mfma_f32_16x16x32_bf16 v[78:81], v[164:167], v[222:225], v[78:81]
	v_mfma_f32_16x16x32_bf16 v[74:77], v[172:175], v[222:225], v[74:77]
	s_setprio 0
	s_setprio 1
	v_mfma_f32_16x16x32_bf16 v[118:121], v[176:179], v[192:195], 0
	v_mfma_f32_16x16x32_bf16 v[114:117], v[184:187], v[192:195], 0
	v_mfma_f32_16x16x32_bf16 v[102:105], v[176:179], v[200:203], 0
	v_mfma_f32_16x16x32_bf16 v[98:101], v[184:187], v[200:203], 0
	v_mfma_f32_16x16x32_bf16 v[86:89], v[176:179], v[210:213], 0
	v_mfma_f32_16x16x32_bf16 v[82:85], v[184:187], v[210:213], 0
	v_mfma_f32_16x16x32_bf16 v[70:73], v[176:179], v[218:221], 0
	v_mfma_f32_16x16x32_bf16 v[66:69], v[184:187], v[218:221], 0
	v_mfma_f32_16x16x32_bf16 v[118:121], v[180:183], v[196:199], v[118:121]
	v_mfma_f32_16x16x32_bf16 v[114:117], v[188:191], v[196:199], v[114:117]
	v_mfma_f32_16x16x32_bf16 v[102:105], v[180:183], v[204:207], v[102:105]
	v_mfma_f32_16x16x32_bf16 v[98:101], v[188:191], v[204:207], v[98:101]
	v_mfma_f32_16x16x32_bf16 v[86:89], v[180:183], v[214:217], v[86:89]
	v_mfma_f32_16x16x32_bf16 v[82:85], v[188:191], v[214:217], v[82:85]
	v_mfma_f32_16x16x32_bf16 v[70:73], v[180:183], v[222:225], v[70:73]
	v_mfma_f32_16x16x32_bf16 v[66:69], v[188:191], v[222:225], v[66:69]
	s_setprio 0
	s_barrier
; #define PG8_STAGE(bufoff, gbase, voff) do { _Pragma("unroll") for (int _i = 0; _i < 2; ++_i) \
;         __builtin_amdgcn_global_load_lds((const unsigned*)((const char*)(gbase) + (voff)[_i]), (PG8_LAS unsigned*)(lds + (bufoff) + ldsw + _i * 8192), 16, 0, 0); } while (0)
; #define PG8_LDA(dst, b, h) do { _Pragma("unroll") for (int m = 0; m < 4; ++m) _Pragma("unroll") for (int k = 0; k < 2; ++k) dst[m][k] = *(const PG8_LAS bf16x8*)(lds + PG8_SA(b, h) + aoff + m * 2048 + k * 1024); } while (0)
; #define PG8_LDB(dst, b, h) do { _Pragma("unroll") for (int n = 0; n < 2; ++n) _Pragma("unroll") for (int k = 0; k < 2; ++k) dst[n][k] = *(const PG8_LAS bf16x8*)(lds + PG8_SB(b, h) + boff + n * 2048 + k * 1024); } while (0)
; #define PG8_MMA(ai, bj, At, Bt) do { __builtin_amdgcn_s_setprio(1); _Pragma("unroll") for (int m = 0; m < 4; ++m) _Pragma("unroll") for (int n = 0; n < 2; ++n) _Pragma("unroll") for (int k = 0; k < 2; ++k) \
;         acc[ai][bj][m][n] = __builtin_amdgcn_mfma_f32_16x16x32_bf16(Bt[n][k], At[m][k], acc[ai][bj][m][n], 0, 0, 0); __builtin_amdgcn_s_setprio(0); } while (0)
; #define PG8_WAIT_V(n) asm volatile("s_waitcnt vmcnt(" #n ")" ::: "memory")
; #define PG8_WAIT_L(n) asm volatile("s_waitcnt lgkmcnt(" #n ")" ::: "memory")
; #define PG8_BAR __builtin_amdgcn_s_barrier()
; #define PG8_SCHED __builtin_amdgcn_sched_barrier(0)
; template <class Epi, class Sched, bool ALIGN_EPI = false, bool SP2 = false>
; __device__ __forceinline__ void gemm_phase(PG8_LAS unsigned char* lds, const Gemm g, const Sched& S, const Epi& E) {
;     ...
;             PG8_LDA(At, 0, 1); PG8_STAGE(PG8_SB(0, 0), b2, voffB); PG8_STAGE(PG8_SB(0, 1), b2 + hstepB, voffB); PG8_STAGE(PG8_SA(0, 0), a2, voffA);
;             PG8_WAIT_V(8); PG8_WAIT_L(0); PG8_BAR; PG8_MMA(1, 0, At, B0); PG8_MMA(1, 1, At, B1); PG8_BAR; PG8_SCHED;
;             PG8_LDB(B0, 1, 0); PG8_LDB(B1, 1, 1); PG8_SCHED; PG8_LDA(At, 1, 0); PG8_STAGE(PG8_SA(0, 1), a2 + hstepA, voffA);
	s_add_i32 s58, s50, s40
	v_lshl_add_u64 v[226:227], s[30:31], 0, v[132:133]
	s_mov_b32 m0, s58
	ds_read_b128 v[192:195], v157 offset:16384
	ds_read_b128 v[196:199], v157 offset:17408
	ds_read_b128 v[200:203], v157 offset:18432
	ds_read_b128 v[204:207], v157 offset:19456
	ds_read_b128 v[210:213], v157 offset:20480
	ds_read_b128 v[214:217], v157 offset:21504
	ds_read_b128 v[218:221], v157 offset:22528
	ds_read_b128 v[222:225], v157 offset:23552
	global_load_lds_dwordx4 v[226:227], off
	s_add_i32 m0, s58, 0x2000
	s_add_u32 s58, s30, 0x80000
	v_lshl_add_u64 v[228:229], s[30:31], 0, v[136:137]
	s_addc_u32 s59, s31, 0
	s_add_i32 s60, s51, s40
	global_load_lds_dwordx4 v[228:229], off
	v_lshl_add_u64 v[230:231], s[58:59], 0, v[132:133]
	s_mov_b32 m0, s60
	v_lshl_add_u64 v[232:233], s[34:35], 0, v[134:135]
	global_load_lds_dwordx4 v[230:231], off
	v_lshl_add_u64 v[230:231], s[58:59], 0, v[136:137]
	s_add_i32 m0, s60, 0x2000
	s_nop 0
	global_load_lds_dwordx4 v[230:231], off
	v_lshl_add_u64 v[230:231], s[34:35], 0, v[130:131]
	s_mov_b32 m0, s17
	s_nop 0
	global_load_lds_dwordx4 v[230:231], off
	s_mov_b32 m0, s41
	s_nop 0
	global_load_lds_dwordx4 v[232:233], off
	s_waitcnt vmcnt(8)
	s_waitcnt lgkmcnt(0)
	s_barrier
	s_setprio 1
	s_waitcnt lgkmcnt(0)
	v_mfma_f32_16x16x32_bf16 v[62:65], v[160:163], v[192:195], 0
	v_mfma_f32_16x16x32_bf16 v[58:61], v[168:171], v[192:195], 0
	v_mfma_f32_16x16x32_bf16 v[46:49], v[160:163], v[200:203], 0
	v_mfma_f32_16x16x32_bf16 v[42:45], v[168:171], v[200:203], 0
	v_mfma_f32_16x16x32_bf16 v[30:33], v[160:163], v[210:213], 0
	v_mfma_f32_16x16x32_bf16 v[26:29], v[168:171], v[210:213], 0
	v_mfma_f32_16x16x32_bf16 v[14:17], v[160:163], v[218:221], 0
	v_mfma_f32_16x16x32_bf16 v[10:13], v[168:171], v[218:221], 0
	v_mfma_f32_16x16x32_bf16 v[62:65], v[164:167], v[196:199], v[62:65]
	v_mfma_f32_16x16x32_bf16 v[58:61], v[172:175], v[196:199], v[58:61]
	v_mfma_f32_16x16x32_bf16 v[46:49], v[164:167], v[204:207], v[46:49]
	v_mfma_f32_16x16x32_bf16 v[42:45], v[172:175], v[204:207], v[42:45]
	v_mfma_f32_16x16x32_bf16 v[30:33], v[164:167], v[214:217], v[30:33]
	v_mfma_f32_16x16x32_bf16 v[26:29], v[172:175], v[214:217], v[26:29]
	v_mfma_f32_16x16x32_bf16 v[14:17], v[164:167], v[222:225], v[14:17]
	v_mfma_f32_16x16x32_bf16 v[10:13], v[172:175], v[222:225], v[10:13]
	s_setprio 0
	s_setprio 1
	v_mfma_f32_16x16x32_bf16 v[54:57], v[176:179], v[192:195], 0
	v_mfma_f32_16x16x32_bf16 v[50:53], v[184:187], v[192:195], 0
	v_mfma_f32_16x16x32_bf16 v[38:41], v[176:179], v[200:203], 0
	v_mfma_f32_16x16x32_bf16 v[34:37], v[184:187], v[200:203], 0
	v_mfma_f32_16x16x32_bf16 v[22:25], v[176:179], v[210:213], 0
	v_mfma_f32_16x16x32_bf16 v[18:21], v[184:187], v[210:213], 0
	v_mfma_f32_16x16x32_bf16 v[6:9], v[176:179], v[218:221], 0
	v_mfma_f32_16x16x32_bf16 v[2:5], v[184:187], v[218:221], 0
	v_mfma_f32_16x16x32_bf16 v[54:57], v[180:183], v[196:199], v[54:57]
	v_mfma_f32_16x16x32_bf16 v[50:53], v[188:191], v[196:199], v[50:53]
	v_mfma_f32_16x16x32_bf16 v[38:41], v[180:183], v[204:207], v[38:41]
	v_mfma_f32_16x16x32_bf16 v[34:37], v[188:191], v[204:207], v[34:37]
	v_mfma_f32_16x16x32_bf16 v[22:25], v[180:183], v[214:217], v[22:25]
	v_mfma_f32_16x16x32_bf16 v[18:21], v[188:191], v[214:217], v[18:21]
	v_mfma_f32_16x16x32_bf16 v[6:9], v[180:183], v[222:225], v[6:9]
	v_mfma_f32_16x16x32_bf16 v[2:5], v[188:191], v[222:225], v[2:5]
	s_setprio 0
	s_barrier
	s_add_i32 s58, 0, 0x18000
	v_add_u32_e32 v138, s58, v1
	s_add_i32 s59, 0, 0x1c000
	ds_read_b128 v[160:163], v138
	ds_read_b128 v[164:167], v138 offset:1024
	ds_read_b128 v[168:171], v138 offset:2048
	ds_read_b128 v[172:175], v138 offset:3072
	v_add_u32_e32 v138, s59, v1
	ds_read_b128 v[176:179], v138
	ds_read_b128 v[180:183], v138 offset:1024
	ds_read_b128 v[184:187], v138 offset:2048
	ds_read_b128 v[188:191], v138 offset:3072
	s_add_u32 s34, s34, 0x80000
	s_addc_u32 s35, s35, 0
	s_mov_b32 m0, s42
	v_lshl_add_u64 v[234:235], s[34:35], 0, v[130:131]
	ds_read_b128 v[192:195], v157 offset:32768
	ds_read_b128 v[196:199], v157 offset:33792
	ds_read_b128 v[200:203], v157 offset:34816
	ds_read_b128 v[204:207], v157 offset:35840
	ds_read_b128 v[210:213], v157 offset:36864
	ds_read_b128 v[214:217], v157 offset:37888
	ds_read_b128 v[218:221], v157 offset:38912
	ds_read_b128 v[222:225], v157 offset:39936
	global_load_lds_dwordx4 v[234:235], off
	v_lshl_add_u64 v[234:235], s[34:35], 0, v[134:135]
	s_mov_b32 m0, s43
	s_nop 0
	global_load_lds_dwordx4 v[234:235], off
	s_waitcnt vmcnt(8)
	s_waitcnt lgkmcnt(0)
	s_barrier
; #define PG8_STAGE(bufoff, gbase, voff) do { _Pragma("unroll") for (int _i = 0; _i < 2; ++_i) \
;         __builtin_amdgcn_global_load_lds((const unsigned*)((const char*)(gbase) + (voff)[_i]), (PG8_LAS unsigned*)(lds + (bufoff) + ldsw + _i * 8192), 16, 0, 0); } while (0)
; #define PG8_LDA(dst, b, h) do { _Pragma("unroll") for (int m = 0; m < 4; ++m) _Pragma("unroll") for (int k = 0; k < 2; ++k) dst[m][k] = *(const PG8_LAS bf16x8*)(lds + PG8_SA(b, h) + aoff + m * 2048 + k * 1024); } while (0)
; #define PG8_MMA(ai, bj, At, Bt) do { __builtin_amdgcn_s_setprio(1); _Pragma("unroll") for (int m = 0; m < 4; ++m) _Pragma("unroll") for (int n = 0; n < 2; ++n) _Pragma("unroll") for (int k = 0; k < 2; ++k) \
;         acc[ai][bj][m][n] = __builtin_amdgcn_mfma_f32_16x16x32_bf16(Bt[n][k], At[m][k], acc[ai][bj][m][n], 0, 0, 0); __builtin_amdgcn_s_setprio(0); } while (0)
; #define PG8_WAIT_V(n) asm volatile("s_waitcnt vmcnt(" #n ")" ::: "memory")
; #define PG8_WAIT_L(n) asm volatile("s_waitcnt lgkmcnt(" #n ")" ::: "memory")
; #define PG8_BAR __builtin_amdgcn_s_barrier()
; #define PG8_SCHED __builtin_amdgcn_sched_barrier(0)
; template <class Epi, class Sched, bool ALIGN_EPI = false, bool SP2 = false>
; __device__ __forceinline__ void gemm_phase(PG8_LAS unsigned char* lds, const Gemm g, const Sched& S, const Epi& E) {
;     ...
;             PG8_WAIT_V(8); PG8_WAIT_L(0); PG8_BAR; PG8_MMA(0, 0, At, B0); PG8_MMA(0, 1, At, B1); PG8_BAR; PG8_SCHED;
;             PG8_LDA(At, 1, 1); PG8_STAGE(PG8_SB(1, 0), b3, voffB); PG8_STAGE(PG8_SB(1, 1), b3 + hstepB, voffB); PG8_STAGE(PG8_SA(1, 0), a3, voffA);
;             PG8_WAIT_V(8); PG8_WAIT_L(0); PG8_BAR; PG8_MMA(1, 0, At, B0); PG8_MMA(1, 1, At, B1); PG8_BAR; PG8_SCHED;
	s_setprio 1
	s_waitcnt lgkmcnt(0)
	v_mfma_f32_16x16x32_bf16 v[126:129], v[160:163], v[192:195], v[126:129]
	v_mfma_f32_16x16x32_bf16 v[122:125], v[168:171], v[192:195], v[122:125]
	v_mfma_f32_16x16x32_bf16 v[110:113], v[160:163], v[200:203], v[110:113]
	v_mfma_f32_16x16x32_bf16 v[106:109], v[168:171], v[200:203], v[106:109]
	v_mfma_f32_16x16x32_bf16 v[94:97], v[160:163], v[210:213], v[94:97]
	v_mfma_f32_16x16x32_bf16 v[90:93], v[168:171], v[210:213], v[90:93]
	v_mfma_f32_16x16x32_bf16 v[78:81], v[160:163], v[218:221], v[78:81]
	v_mfma_f32_16x16x32_bf16 v[74:77], v[168:171], v[218:221], v[74:77]
	v_mfma_f32_16x16x32_bf16 v[126:129], v[164:167], v[196:199], v[126:129]
	v_mfma_f32_16x16x32_bf16 v[122:125], v[172:175], v[196:199], v[122:125]
	v_mfma_f32_16x16x32_bf16 v[110:113], v[164:167], v[204:207], v[110:113]
	v_mfma_f32_16x16x32_bf16 v[106:109], v[172:175], v[204:207], v[106:109]
	v_mfma_f32_16x16x32_bf16 v[94:97], v[164:167], v[214:217], v[94:97]
	v_mfma_f32_16x16x32_bf16 v[90:93], v[172:175], v[214:217], v[90:93]
	v_mfma_f32_16x16x32_bf16 v[78:81], v[164:167], v[222:225], v[78:81]
	v_mfma_f32_16x16x32_bf16 v[74:77], v[172:175], v[222:225], v[74:77]
	s_setprio 0
	s_setprio 1
	v_mfma_f32_16x16x32_bf16 v[118:121], v[176:179], v[192:195], v[118:121]
	v_mfma_f32_16x16x32_bf16 v[114:117], v[184:187], v[192:195], v[114:117]
	v_mfma_f32_16x16x32_bf16 v[102:105], v[176:179], v[200:203], v[102:105]
	v_mfma_f32_16x16x32_bf16 v[98:101], v[184:187], v[200:203], v[98:101]
	v_mfma_f32_16x16x32_bf16 v[86:89], v[176:179], v[210:213], v[86:89]
	v_mfma_f32_16x16x32_bf16 v[82:85], v[184:187], v[210:213], v[82:85]
	v_mfma_f32_16x16x32_bf16 v[70:73], v[176:179], v[218:221], v[70:73]
	v_mfma_f32_16x16x32_bf16 v[66:69], v[184:187], v[218:221], v[66:69]
	v_mfma_f32_16x16x32_bf16 v[118:121], v[180:183], v[196:199], v[118:121]
	v_mfma_f32_16x16x32_bf16 v[114:117], v[188:191], v[196:199], v[114:117]
	v_mfma_f32_16x16x32_bf16 v[102:105], v[180:183], v[204:207], v[102:105]
	v_mfma_f32_16x16x32_bf16 v[98:101], v[188:191], v[204:207], v[98:101]
	v_mfma_f32_16x16x32_bf16 v[86:89], v[180:183], v[214:217], v[86:89]
	v_mfma_f32_16x16x32_bf16 v[82:85], v[188:191], v[214:217], v[82:85]
	v_mfma_f32_16x16x32_bf16 v[70:73], v[180:183], v[222:225], v[70:73]
	v_mfma_f32_16x16x32_bf16 v[66:69], v[188:191], v[222:225], v[66:69]
	s_setprio 0
	s_barrier
	s_add_i32 s34, s58, s40
	v_lshl_add_u64 v[226:227], v[226:227], 0, s[14:15]
	s_mov_b32 m0, s34
	ds_read_b128 v[192:195], v157 offset:49152
	ds_read_b128 v[196:199], v157 offset:50176
	ds_read_b128 v[200:203], v157 offset:51200
	ds_read_b128 v[204:207], v157 offset:52224
	ds_read_b128 v[210:213], v157 offset:53248
	ds_read_b128 v[214:217], v157 offset:54272
	ds_read_b128 v[218:221], v157 offset:55296
	ds_read_b128 v[222:225], v157 offset:56320
	global_load_lds_dwordx4 v[226:227], off
	s_add_i32 m0, s34, 0x2000
	s_add_u32 s30, s30, 0x80080
	v_lshl_add_u64 v[226:227], v[228:229], 0, s[14:15]
	s_addc_u32 s31, s31, 0
	s_add_i32 s34, s59, s40
	global_load_lds_dwordx4 v[226:227], off
	v_lshl_add_u64 v[226:227], s[30:31], 0, v[132:133]
	s_mov_b32 m0, s34
	s_nop 0
	global_load_lds_dwordx4 v[226:227], off
	v_lshl_add_u64 v[226:227], s[30:31], 0, v[136:137]
	s_add_i32 m0, s34, 0x2000
	s_nop 0
	global_load_lds_dwordx4 v[226:227], off
	v_lshl_add_u64 v[226:227], v[230:231], 0, s[14:15]
	s_mov_b32 m0, s46
	s_nop 0
	global_load_lds_dwordx4 v[226:227], off
	v_lshl_add_u64 v[226:227], v[232:233], 0, s[14:15]
	s_mov_b32 m0, s47
	s_nop 0
	global_load_lds_dwordx4 v[226:227], off
	s_waitcnt vmcnt(8)
	s_waitcnt lgkmcnt(0)
	s_barrier
	s_setprio 1
	s_waitcnt lgkmcnt(0)
	v_mfma_f32_16x16x32_bf16 v[62:65], v[160:163], v[192:195], v[62:65]
	v_mfma_f32_16x16x32_bf16 v[58:61], v[168:171], v[192:195], v[58:61]
	v_mfma_f32_16x16x32_bf16 v[46:49], v[160:163], v[200:203], v[46:49]
	v_mfma_f32_16x16x32_bf16 v[42:45], v[168:171], v[200:203], v[42:45]
	v_mfma_f32_16x16x32_bf16 v[30:33], v[160:163], v[210:213], v[30:33]
	v_mfma_f32_16x16x32_bf16 v[26:29], v[168:171], v[210:213], v[26:29]
	v_mfma_f32_16x16x32_bf16 v[14:17], v[160:163], v[218:221], v[14:17]
	v_mfma_f32_16x16x32_bf16 v[10:13], v[168:171], v[218:221], v[10:13]
	v_mfma_f32_16x16x32_bf16 v[62:65], v[164:167], v[196:199], v[62:65]
	v_mfma_f32_16x16x32_bf16 v[58:61], v[172:175], v[196:199], v[58:61]
	v_mfma_f32_16x16x32_bf16 v[46:49], v[164:167], v[204:207], v[46:49]
	v_mfma_f32_16x16x32_bf16 v[42:45], v[172:175], v[204:207], v[42:45]
	v_mfma_f32_16x16x32_bf16 v[30:33], v[164:167], v[214:217], v[30:33]
	v_mfma_f32_16x16x32_bf16 v[26:29], v[172:175], v[214:217], v[26:29]
	v_mfma_f32_16x16x32_bf16 v[14:17], v[164:167], v[222:225], v[14:17]
	v_mfma_f32_16x16x32_bf16 v[10:13], v[172:175], v[222:225], v[10:13]
	s_setprio 0
	s_setprio 1
	v_mfma_f32_16x16x32_bf16 v[54:57], v[176:179], v[192:195], v[54:57]
	v_mfma_f32_16x16x32_bf16 v[50:53], v[184:187], v[192:195], v[50:53]
	v_mfma_f32_16x16x32_bf16 v[38:41], v[176:179], v[200:203], v[38:41]
	v_mfma_f32_16x16x32_bf16 v[34:37], v[184:187], v[200:203], v[34:37]
	v_mfma_f32_16x16x32_bf16 v[22:25], v[176:179], v[210:213], v[22:25]
	v_mfma_f32_16x16x32_bf16 v[18:21], v[184:187], v[210:213], v[18:21]
	v_mfma_f32_16x16x32_bf16 v[6:9], v[176:179], v[218:221], v[6:9]
	v_mfma_f32_16x16x32_bf16 v[2:5], v[184:187], v[218:221], v[2:5]
	v_mfma_f32_16x16x32_bf16 v[54:57], v[180:183], v[196:199], v[54:57]
	v_mfma_f32_16x16x32_bf16 v[50:53], v[188:191], v[196:199], v[50:53]
	v_mfma_f32_16x16x32_bf16 v[38:41], v[180:183], v[204:207], v[38:41]
	v_mfma_f32_16x16x32_bf16 v[34:37], v[188:191], v[204:207], v[34:37]
	v_mfma_f32_16x16x32_bf16 v[22:25], v[180:183], v[214:217], v[22:25]
	v_mfma_f32_16x16x32_bf16 v[18:21], v[188:191], v[214:217], v[18:21]
	v_mfma_f32_16x16x32_bf16 v[6:9], v[180:183], v[222:225], v[6:9]
	v_mfma_f32_16x16x32_bf16 v[2:5], v[188:191], v[222:225], v[2:5]
	s_setprio 0
	s_barrier
	s_add_i32 s39, s39, 2
	s_add_u32 s12, s12, 0x100
	s_addc_u32 s13, s13, 0
	s_add_u32 s37, s37, 0x100
	s_addc_u32 s38, s38, 0
	s_cmp_gt_u32 s39, 29
	s_cbranch_scc1 .Lpeel_exit_19
	.p2align 6

; #define PG8_STAGE(bufoff, gbase, voff) do { _Pragma("unroll") for (int _i = 0; _i < 2; ++_i) \
;         __builtin_amdgcn_global_load_lds((const unsigned*)((const char*)(gbase) + (voff)[_i]), (PG8_LAS unsigned*)(lds + (bufoff) + ldsw + _i * 8192), 16, 0, 0); } while (0)
; #define PG8_LDA(dst, b, h) do { _Pragma("unroll") for (int m = 0; m < 4; ++m) _Pragma("unroll") for (int k = 0; k < 2; ++k) dst[m][k] = *(const PG8_LAS bf16x8*)(lds + PG8_SA(b, h) + aoff + m * 2048 + k * 1024); } while (0)
; #define PG8_LDB(dst, b, h) do { _Pragma("unroll") for (int n = 0; n < 2; ++n) _Pragma("unroll") for (int k = 0; k < 2; ++k) dst[n][k] = *(const PG8_LAS bf16x8*)(lds + PG8_SB(b, h) + boff + n * 2048 + k * 1024); } while (0)
; #define PG8_MMA(ai, bj, At, Bt) do { __builtin_amdgcn_s_setprio(1); _Pragma("unroll") for (int m = 0; m < 4; ++m) _Pragma("unroll") for (int n = 0; n < 2; ++n) _Pragma("unroll") for (int k = 0; k < 2; ++k) \
;         acc[ai][bj][m][n] = __builtin_amdgcn_mfma_f32_16x16x32_bf16(Bt[n][k], At[m][k], acc[ai][bj][m][n], 0, 0, 0); __builtin_amdgcn_s_setprio(0); } while (0)
; #define PG8_WAIT_V(n) asm volatile("s_waitcnt vmcnt(" #n ")" ::: "memory")
; #define PG8_WAIT_L(n) asm volatile("s_waitcnt lgkmcnt(" #n ")" ::: "memory")
; #define PG8_BAR __builtin_amdgcn_s_barrier()
; #define PG8_SCHED __builtin_amdgcn_sched_barrier(0)
;     __host__ __device__ bool next(int i, Unit& u) const {
;         const long L = (long)i * G + c; if (L >= nwg) return false;
;         int wgid = (int)L; { const int q = nwg / NXCD, r = nwg % NXCD, xcd = wgid % NXCD, off = wgid / NXCD; wgid = (xcd < r ? xcd * (q + 1) : r * (q + 1) + (xcd - r) * q) + off; }
;         const int nig = WGM * nN, gid = wgid / nig, fm = gid * WGM, gsz = (nM - fm) < WGM ? (nM - fm) : WGM;
;         u.pm = fm + ((wgid % nig) % gsz); u.pn = (wgid % nig) / gsz; return true;
; template <class Epi, class Sched, bool ALIGN_EPI = false, bool SP2 = false>
; __device__ __forceinline__ void gemm_phase(PG8_LAS unsigned char* lds, const Gemm g, const Sched& S, const Epi& E) {
;     ...
;             PG8_LDB(B0, 0, 0); PG8_LDB(B1, 0, 1); PG8_SCHED; PG8_LDA(At, 0, 0); PG8_STAGE(PG8_SA(1, 1), a1 + hstepA, voffA);
;             PG8_WAIT_V(8); PG8_WAIT_L(0); PG8_BAR; PG8_MMA(0, 0, At, B0); PG8_MMA(0, 1, At, B1); PG8_BAR; PG8_SCHED;
.LBB0_2256:
	s_mov_b32 s100, s28
	s_mov_b32 s101, s29
	s_mov_b32 s58, s30
	s_mov_b32 s59, s31
	s_add_u32 s28, s28, 0x100080
	s_addc_u32 s29, s29, 0
	s_add_u32 s55, s30, 0x100
	s_addc_u32 s56, s31, 0
	ds_read_b128 v[152:155], v148
	ds_read_b128 v[156:159], v148 offset:1024
	ds_read_b128 v[160:163], v148 offset:2048
	ds_read_b128 v[164:167], v148 offset:3072
	ds_read_b128 v[168:171], v149
	ds_read_b128 v[172:175], v149 offset:1024
	ds_read_b128 v[176:179], v149 offset:2048
	ds_read_b128 v[180:183], v149 offset:3072
	s_add_u32 s30, s28, 0xfff00080
	s_addc_u32 s31, s29, -1
	s_mov_b32 s35, s31
	s_mov_b32 s34, s30
	s_mov_b32 s31, s56
	s_mov_b32 s30, s55
	v_lshl_add_u64 v[218:219], s[28:29], 0, v[138:139]
	s_add_i32 m0, s19, 0xc000
	ds_read_b128 v[184:187], v150
	ds_read_b128 v[188:191], v150 offset:1024
	ds_read_b128 v[192:195], v150 offset:2048
	ds_read_b128 v[196:199], v150 offset:3072
	ds_read_b128 v[200:203], v150 offset:4096
	ds_read_b128 v[204:207], v150 offset:5120
	ds_read_b128 v[210:213], v150 offset:6144
	ds_read_b128 v[214:217], v150 offset:7168
	global_load_lds_dwordx4 v[218:219], off
	v_lshl_add_u64 v[218:219], s[28:29], 0, v[140:141]
	s_add_i32 m0, s19, 0xe000
	s_nop 0
	global_load_lds_dwordx4 v[218:219], off
	s_add_i32 s42, s42, 1
	s_mul_i32 s4, s42, s45
	s_mul_hi_u32 s5, s42, s33
	s_add_i32 s5, s5, s4
	s_mul_i32 s4, s42, s33
	s_add_u32 s24, s4, s70
	s_addc_u32 s25, s5, s37
	v_cmp_gt_i64_e32 vcc, s[24:25], v[144:145]
	v_cmp_lt_i64_e64 s[4:5], s[24:25], v[142:143]
	s_cbranch_vccnz .LBB0_2258
	s_ashr_i32 s20, s24, 31
	s_lshr_b32 s20, s20, 29
	s_add_i32 s20, s24, s20
	s_ashr_i32 s21, s20, 3
	s_and_b32 s20, s20, -8
	s_sub_i32 s20, s24, s20
	s_cmp_lt_i32 s20, 0
	s_cselect_b32 s22, s38, 0xa0
	s_mul_i32 s20, s22, s20
	s_add_i32 s20, s20, s21
	s_ashr_i32 s21, s20, 31
	s_lshr_b32 s21, s21, 27
	s_add_i32 s21, s20, s21
	s_ashr_i32 s22, s21, 5
	s_lshl_b32 s22, s22, 2
	s_sub_i32 s23, 0xa0, s22
	s_min_i32 s23, s23, 4
	s_abs_i32 s24, s23
	v_cvt_f32_u32_e32 v2, s24
	s_sub_i32 s26, 0, s24
	s_andn2_b32 s21, s21, 31
	s_sub_i32 s21, s20, s21
	v_rcp_iflag_f32_e32 v2, v2
	s_abs_i32 s20, s21
	s_xor_b32 s25, s21, s23
	s_ashr_i32 s25, s25, 31
	v_mul_f32_e32 v2, 0x4f7ffffe, v2
	v_cvt_u32_f32_e32 v2, v2
	s_nop 0
	v_readfirstlane_b32 s27, v2
	s_mul_i32 s26, s26, s27
	s_mul_hi_u32 s26, s27, s26
	s_add_i32 s27, s27, s26
	s_mul_hi_u32 s26, s20, s27
	s_mul_i32 s27, s26, s24
	s_sub_i32 s20, s20, s27
	s_add_i32 s98, s26, 1
	s_sub_i32 s27, s20, s24
	s_cmp_ge_u32 s20, s24
	s_cselect_b32 s26, s98, s26
	s_cselect_b32 s20, s27, s20
	s_add_i32 s27, s26, 1
	s_cmp_ge_u32 s20, s24
	s_cselect_b32 s20, s27, s26
	s_xor_b32 s20, s20, s25
	s_sub_i32 s20, s20, s25
	s_mul_i32 s23, s20, s23
	s_sub_i32 s21, s21, s23
	s_add_i32 s22, s21, s22
.LBB0_2258:
	s_ashr_i32 s23, s22, 31
	s_lshl_b64 s[24:25], s[22:23], 21
	s_add_u32 s24, s86, s24
	s_addc_u32 s25, s87, s25
	s_and_b64 s[26:27], s[4:5], exec
	s_cselect_b32 s23, s25, s101
	s_cselect_b32 s53, s24, s100
	s_ashr_i32 s21, s20, 31
	s_lshl_b64 s[26:27], s[20:21], 21
	s_add_u32 s26, s88, s26
	s_addc_u32 s27, s89, s27
	s_and_b64 s[98:99], s[4:5], exec
	s_cselect_b32 s21, s27, s59
	s_cselect_b32 s54, s26, s58
	s_mov_b32 s57, -2
	s_waitcnt vmcnt(8)
	s_waitcnt lgkmcnt(0)
	s_barrier
	s_setprio 1
	s_waitcnt lgkmcnt(0)
	v_mfma_f32_16x16x32_bf16 v[126:129], v[152:155], v[184:187], 0
	v_mfma_f32_16x16x32_bf16 v[122:125], v[160:163], v[184:187], 0
	v_mfma_f32_16x16x32_bf16 v[118:121], v[152:155], v[192:195], 0
	v_mfma_f32_16x16x32_bf16 v[114:117], v[160:163], v[192:195], 0
	v_mfma_f32_16x16x32_bf16 v[102:105], v[152:155], v[200:203], 0
	v_mfma_f32_16x16x32_bf16 v[98:101], v[160:163], v[200:203], 0
	v_mfma_f32_16x16x32_bf16 v[86:89], v[152:155], v[210:213], 0
	v_mfma_f32_16x16x32_bf16 v[82:85], v[160:163], v[210:213], 0
	v_mfma_f32_16x16x32_bf16 v[126:129], v[156:159], v[188:191], v[126:129]
	v_mfma_f32_16x16x32_bf16 v[122:125], v[164:167], v[188:191], v[122:125]
	v_mfma_f32_16x16x32_bf16 v[118:121], v[156:159], v[196:199], v[118:121]
	v_mfma_f32_16x16x32_bf16 v[114:117], v[164:167], v[196:199], v[114:117]
	v_mfma_f32_16x16x32_bf16 v[102:105], v[156:159], v[204:207], v[102:105]
	v_mfma_f32_16x16x32_bf16 v[98:101], v[164:167], v[204:207], v[98:101]
	v_mfma_f32_16x16x32_bf16 v[86:89], v[156:159], v[214:217], v[86:89]
	v_mfma_f32_16x16x32_bf16 v[82:85], v[164:167], v[214:217], v[82:85]
	s_setprio 0
	s_setprio 1
	v_mfma_f32_16x16x32_bf16 v[110:113], v[168:171], v[184:187], 0
	v_mfma_f32_16x16x32_bf16 v[106:109], v[176:179], v[184:187], 0
	v_mfma_f32_16x16x32_bf16 v[94:97], v[168:171], v[192:195], 0
	v_mfma_f32_16x16x32_bf16 v[90:93], v[176:179], v[192:195], 0
	v_mfma_f32_16x16x32_bf16 v[78:81], v[168:171], v[200:203], 0
	v_mfma_f32_16x16x32_bf16 v[74:77], v[176:179], v[200:203], 0
	v_mfma_f32_16x16x32_bf16 v[70:73], v[168:171], v[210:213], 0
	v_mfma_f32_16x16x32_bf16 v[66:69], v[176:179], v[210:213], 0
	v_mfma_f32_16x16x32_bf16 v[110:113], v[172:175], v[188:191], v[110:113]
	v_mfma_f32_16x16x32_bf16 v[106:109], v[180:183], v[188:191], v[106:109]
	v_mfma_f32_16x16x32_bf16 v[94:97], v[172:175], v[196:199], v[94:97]
	v_mfma_f32_16x16x32_bf16 v[90:93], v[180:183], v[196:199], v[90:93]
	v_mfma_f32_16x16x32_bf16 v[78:81], v[172:175], v[204:207], v[78:81]
	v_mfma_f32_16x16x32_bf16 v[74:77], v[180:183], v[204:207], v[74:77]
	v_mfma_f32_16x16x32_bf16 v[70:73], v[172:175], v[214:217], v[70:73]
	v_mfma_f32_16x16x32_bf16 v[66:69], v[180:183], v[214:217], v[66:69]
	s_setprio 0
	s_barrier
; #define PG8_STAGE(bufoff, gbase, voff) do { _Pragma("unroll") for (int _i = 0; _i < 2; ++_i) \
;         __builtin_amdgcn_global_load_lds((const unsigned*)((const char*)(gbase) + (voff)[_i]), (PG8_LAS unsigned*)(lds + (bufoff) + ldsw + _i * 8192), 16, 0, 0); } while (0)
; #define PG8_LDA(dst, b, h) do { _Pragma("unroll") for (int m = 0; m < 4; ++m) _Pragma("unroll") for (int k = 0; k < 2; ++k) dst[m][k] = *(const PG8_LAS bf16x8*)(lds + PG8_SA(b, h) + aoff + m * 2048 + k * 1024); } while (0)
; #define PG8_LDB(dst, b, h) do { _Pragma("unroll") for (int n = 0; n < 2; ++n) _Pragma("unroll") for (int k = 0; k < 2; ++k) dst[n][k] = *(const PG8_LAS bf16x8*)(lds + PG8_SB(b, h) + boff + n * 2048 + k * 1024); } while (0)
; #define PG8_MMA(ai, bj, At, Bt) do { __builtin_amdgcn_s_setprio(1); _Pragma("unroll") for (int m = 0; m < 4; ++m) _Pragma("unroll") for (int n = 0; n < 2; ++n) _Pragma("unroll") for (int k = 0; k < 2; ++k) \
;         acc[ai][bj][m][n] = __builtin_amdgcn_mfma_f32_16x16x32_bf16(Bt[n][k], At[m][k], acc[ai][bj][m][n], 0, 0, 0); __builtin_amdgcn_s_setprio(0); } while (0)
; #define PG8_WAIT_V(n) asm volatile("s_waitcnt vmcnt(" #n ")" ::: "memory")
; #define PG8_WAIT_L(n) asm volatile("s_waitcnt lgkmcnt(" #n ")" ::: "memory")
; #define PG8_BAR __builtin_amdgcn_s_barrier()
; #define PG8_SCHED __builtin_amdgcn_sched_barrier(0)
; template <class Epi, class Sched, bool ALIGN_EPI = false, bool SP2 = false>
; __device__ __forceinline__ void gemm_phase(PG8_LAS unsigned char* lds, const Gemm g, const Sched& S, const Epi& E) {
;     ...
;             PG8_LDA(At, 0, 1); PG8_STAGE(PG8_SB(0, 0), b2, voffB); PG8_STAGE(PG8_SB(0, 1), b2 + hstepB, voffB); PG8_STAGE(PG8_SA(0, 0), a2, voffA);
;             PG8_WAIT_V(8); PG8_WAIT_L(0); PG8_BAR; PG8_MMA(1, 0, At, B0); PG8_MMA(1, 1, At, B1); PG8_BAR; PG8_SCHED;
;             PG8_LDB(B0, 1, 0); PG8_LDB(B1, 1, 1); PG8_SCHED; PG8_LDA(At, 1, 0); PG8_STAGE(PG8_SA(0, 1), a2 + hstepA, voffA);
;             PG8_WAIT_V(8); PG8_WAIT_L(0); PG8_BAR; PG8_MMA(0, 0, At, B0); PG8_MMA(0, 1, At, B1); PG8_BAR; PG8_SCHED;
	s_add_i32 s58, s46, s36
	v_lshl_add_u64 v[218:219], s[30:31], 0, v[134:135]
	s_mov_b32 m0, s58
	ds_read_b128 v[184:187], v150 offset:16384
	ds_read_b128 v[188:191], v150 offset:17408
	ds_read_b128 v[192:195], v150 offset:18432
	ds_read_b128 v[196:199], v150 offset:19456
	ds_read_b128 v[200:203], v150 offset:20480
	ds_read_b128 v[204:207], v150 offset:21504
	ds_read_b128 v[210:213], v150 offset:22528
	ds_read_b128 v[214:217], v150 offset:23552
	global_load_lds_dwordx4 v[218:219], off
	s_add_i32 m0, s58, 0x2000
	s_add_u32 s58, s30, 0x100000
	v_lshl_add_u64 v[220:221], s[30:31], 0, v[130:131]
	s_addc_u32 s59, s31, 0
	s_add_i32 s60, s47, s36
	global_load_lds_dwordx4 v[220:221], off
	v_lshl_add_u64 v[222:223], s[58:59], 0, v[134:135]
	s_mov_b32 m0, s60
	v_lshl_add_u64 v[224:225], s[34:35], 0, v[132:133]
	global_load_lds_dwordx4 v[222:223], off
	v_lshl_add_u64 v[222:223], s[58:59], 0, v[130:131]
	s_add_i32 m0, s60, 0x2000
	s_nop 0
	global_load_lds_dwordx4 v[222:223], off
	v_lshl_add_u64 v[222:223], s[34:35], 0, v[136:137]
	s_mov_b32 m0, s19
	s_nop 0
	global_load_lds_dwordx4 v[222:223], off
	s_mov_b32 m0, s39
	s_nop 0
	global_load_lds_dwordx4 v[224:225], off
	s_waitcnt vmcnt(8)
	s_waitcnt lgkmcnt(0)
	s_barrier
	s_setprio 1
	s_waitcnt lgkmcnt(0)
	v_mfma_f32_16x16x32_bf16 v[62:65], v[152:155], v[184:187], 0
	v_mfma_f32_16x16x32_bf16 v[58:61], v[160:163], v[184:187], 0
	v_mfma_f32_16x16x32_bf16 v[54:57], v[152:155], v[192:195], 0
	v_mfma_f32_16x16x32_bf16 v[50:53], v[160:163], v[192:195], 0
	v_mfma_f32_16x16x32_bf16 v[38:41], v[152:155], v[200:203], 0
	v_mfma_f32_16x16x32_bf16 v[34:37], v[160:163], v[200:203], 0
	v_mfma_f32_16x16x32_bf16 v[22:25], v[152:155], v[210:213], 0
	v_mfma_f32_16x16x32_bf16 v[18:21], v[160:163], v[210:213], 0
	v_mfma_f32_16x16x32_bf16 v[62:65], v[156:159], v[188:191], v[62:65]
	v_mfma_f32_16x16x32_bf16 v[58:61], v[164:167], v[188:191], v[58:61]
	v_mfma_f32_16x16x32_bf16 v[54:57], v[156:159], v[196:199], v[54:57]
	v_mfma_f32_16x16x32_bf16 v[50:53], v[164:167], v[196:199], v[50:53]
	v_mfma_f32_16x16x32_bf16 v[38:41], v[156:159], v[204:207], v[38:41]
	v_mfma_f32_16x16x32_bf16 v[34:37], v[164:167], v[204:207], v[34:37]
	v_mfma_f32_16x16x32_bf16 v[22:25], v[156:159], v[214:217], v[22:25]
	v_mfma_f32_16x16x32_bf16 v[18:21], v[164:167], v[214:217], v[18:21]
	s_setprio 0
	s_setprio 1
	v_mfma_f32_16x16x32_bf16 v[46:49], v[168:171], v[184:187], 0
	v_mfma_f32_16x16x32_bf16 v[42:45], v[176:179], v[184:187], 0
	v_mfma_f32_16x16x32_bf16 v[30:33], v[168:171], v[192:195], 0
	v_mfma_f32_16x16x32_bf16 v[26:29], v[176:179], v[192:195], 0
	v_mfma_f32_16x16x32_bf16 v[14:17], v[168:171], v[200:203], 0
	v_mfma_f32_16x16x32_bf16 v[10:13], v[176:179], v[200:203], 0
	v_mfma_f32_16x16x32_bf16 v[6:9], v[168:171], v[210:213], 0
	v_mfma_f32_16x16x32_bf16 v[2:5], v[176:179], v[210:213], 0
	v_mfma_f32_16x16x32_bf16 v[46:49], v[172:175], v[188:191], v[46:49]
	v_mfma_f32_16x16x32_bf16 v[42:45], v[180:183], v[188:191], v[42:45]
	v_mfma_f32_16x16x32_bf16 v[30:33], v[172:175], v[196:199], v[30:33]
	v_mfma_f32_16x16x32_bf16 v[26:29], v[180:183], v[196:199], v[26:29]
	v_mfma_f32_16x16x32_bf16 v[14:17], v[172:175], v[204:207], v[14:17]
	v_mfma_f32_16x16x32_bf16 v[10:13], v[180:183], v[204:207], v[10:13]
	v_mfma_f32_16x16x32_bf16 v[6:9], v[172:175], v[214:217], v[6:9]
	v_mfma_f32_16x16x32_bf16 v[2:5], v[180:183], v[214:217], v[2:5]
	s_setprio 0
	s_barrier
	s_add_i32 s58, 0, 0x18000
	v_add_u32_e32 v151, s58, v146
	s_add_i32 s59, 0, 0x1c000
	ds_read_b128 v[152:155], v151
	ds_read_b128 v[156:159], v151 offset:1024
	ds_read_b128 v[160:163], v151 offset:2048
	ds_read_b128 v[164:167], v151 offset:3072
	v_add_u32_e32 v151, s59, v146
	ds_read_b128 v[168:171], v151
	ds_read_b128 v[172:175], v151 offset:1024
	ds_read_b128 v[176:179], v151 offset:2048
	ds_read_b128 v[180:183], v151 offset:3072
	s_add_u32 s34, s34, 0x100000
	s_addc_u32 s35, s35, 0
	s_mov_b32 m0, s40
	v_lshl_add_u64 v[226:227], s[34:35], 0, v[136:137]
	ds_read_b128 v[184:187], v150 offset:32768
	ds_read_b128 v[188:191], v150 offset:33792
	ds_read_b128 v[192:195], v150 offset:34816
	ds_read_b128 v[196:199], v150 offset:35840
	ds_read_b128 v[200:203], v150 offset:36864
	ds_read_b128 v[204:207], v150 offset:37888
	ds_read_b128 v[210:213], v150 offset:38912
	ds_read_b128 v[214:217], v150 offset:39936
	global_load_lds_dwordx4 v[226:227], off
	v_lshl_add_u64 v[226:227], s[34:35], 0, v[132:133]
	s_mov_b32 m0, s41
	s_nop 0
	global_load_lds_dwordx4 v[226:227], off
	s_waitcnt vmcnt(8)
	s_waitcnt lgkmcnt(0)
	s_barrier
; #define PG8_STAGE(bufoff, gbase, voff) do { _Pragma("unroll") for (int _i = 0; _i < 2; ++_i) \
;         __builtin_amdgcn_global_load_lds((const unsigned*)((const char*)(gbase) + (voff)[_i]), (PG8_LAS unsigned*)(lds + (bufoff) + ldsw + _i * 8192), 16, 0, 0); } while (0)
; #define PG8_LDA(dst, b, h) do { _Pragma("unroll") for (int m = 0; m < 4; ++m) _Pragma("unroll") for (int k = 0; k < 2; ++k) dst[m][k] = *(const PG8_LAS bf16x8*)(lds + PG8_SA(b, h) + aoff + m * 2048 + k * 1024); } while (0)
; #define PG8_MMA(ai, bj, At, Bt) do { __builtin_amdgcn_s_setprio(1); _Pragma("unroll") for (int m = 0; m < 4; ++m) _Pragma("unroll") for (int n = 0; n < 2; ++n) _Pragma("unroll") for (int k = 0; k < 2; ++k) \
;         acc[ai][bj][m][n] = __builtin_amdgcn_mfma_f32_16x16x32_bf16(Bt[n][k], At[m][k], acc[ai][bj][m][n], 0, 0, 0); __builtin_amdgcn_s_setprio(0); } while (0)
; #define PG8_WAIT_V(n) asm volatile("s_waitcnt vmcnt(" #n ")" ::: "memory")
; #define PG8_WAIT_L(n) asm volatile("s_waitcnt lgkmcnt(" #n ")" ::: "memory")
; #define PG8_BAR __builtin_amdgcn_s_barrier()
; #define PG8_SCHED __builtin_amdgcn_sched_barrier(0)
; template <class Epi, class Sched, bool ALIGN_EPI = false, bool SP2 = false>
; __device__ __forceinline__ void gemm_phase(PG8_LAS unsigned char* lds, const Gemm g, const Sched& S, const Epi& E) {
;     ...
;         for (int t = 0; t < nt; t += 2) {
;     ...
;             PG8_WAIT_V(8); PG8_WAIT_L(0); PG8_BAR; PG8_MMA(0, 0, At, B0); PG8_MMA(0, 1, At, B1); PG8_BAR; PG8_SCHED;
;             PG8_LDA(At, 1, 1); PG8_STAGE(PG8_SB(1, 0), b3, voffB); PG8_STAGE(PG8_SB(1, 1), b3 + hstepB, voffB); PG8_STAGE(PG8_SA(1, 0), a3, voffA);
;             PG8_WAIT_V(8); PG8_WAIT_L(0); PG8_BAR; PG8_MMA(1, 0, At, B0); PG8_MMA(1, 1, At, B1); PG8_BAR; PG8_SCHED;
	s_setprio 1
	s_waitcnt lgkmcnt(0)
	v_mfma_f32_16x16x32_bf16 v[126:129], v[152:155], v[184:187], v[126:129]
	v_mfma_f32_16x16x32_bf16 v[122:125], v[160:163], v[184:187], v[122:125]
	v_mfma_f32_16x16x32_bf16 v[118:121], v[152:155], v[192:195], v[118:121]
	v_mfma_f32_16x16x32_bf16 v[114:117], v[160:163], v[192:195], v[114:117]
	v_mfma_f32_16x16x32_bf16 v[102:105], v[152:155], v[200:203], v[102:105]
	v_mfma_f32_16x16x32_bf16 v[98:101], v[160:163], v[200:203], v[98:101]
	v_mfma_f32_16x16x32_bf16 v[86:89], v[152:155], v[210:213], v[86:89]
	v_mfma_f32_16x16x32_bf16 v[82:85], v[160:163], v[210:213], v[82:85]
	v_mfma_f32_16x16x32_bf16 v[126:129], v[156:159], v[188:191], v[126:129]
	v_mfma_f32_16x16x32_bf16 v[122:125], v[164:167], v[188:191], v[122:125]
	v_mfma_f32_16x16x32_bf16 v[118:121], v[156:159], v[196:199], v[118:121]
	v_mfma_f32_16x16x32_bf16 v[114:117], v[164:167], v[196:199], v[114:117]
	v_mfma_f32_16x16x32_bf16 v[102:105], v[156:159], v[204:207], v[102:105]
	v_mfma_f32_16x16x32_bf16 v[98:101], v[164:167], v[204:207], v[98:101]
	v_mfma_f32_16x16x32_bf16 v[86:89], v[156:159], v[214:217], v[86:89]
	v_mfma_f32_16x16x32_bf16 v[82:85], v[164:167], v[214:217], v[82:85]
	s_setprio 0
	s_setprio 1
	v_mfma_f32_16x16x32_bf16 v[110:113], v[168:171], v[184:187], v[110:113]
	v_mfma_f32_16x16x32_bf16 v[106:109], v[176:179], v[184:187], v[106:109]
	v_mfma_f32_16x16x32_bf16 v[94:97], v[168:171], v[192:195], v[94:97]
	v_mfma_f32_16x16x32_bf16 v[90:93], v[176:179], v[192:195], v[90:93]
	v_mfma_f32_16x16x32_bf16 v[78:81], v[168:171], v[200:203], v[78:81]
	v_mfma_f32_16x16x32_bf16 v[74:77], v[176:179], v[200:203], v[74:77]
	v_mfma_f32_16x16x32_bf16 v[70:73], v[168:171], v[210:213], v[70:73]
	v_mfma_f32_16x16x32_bf16 v[66:69], v[176:179], v[210:213], v[66:69]
	v_mfma_f32_16x16x32_bf16 v[110:113], v[172:175], v[188:191], v[110:113]
	v_mfma_f32_16x16x32_bf16 v[106:109], v[180:183], v[188:191], v[106:109]
	v_mfma_f32_16x16x32_bf16 v[94:97], v[172:175], v[196:199], v[94:97]
	v_mfma_f32_16x16x32_bf16 v[90:93], v[180:183], v[196:199], v[90:93]
	v_mfma_f32_16x16x32_bf16 v[78:81], v[172:175], v[204:207], v[78:81]
	v_mfma_f32_16x16x32_bf16 v[74:77], v[180:183], v[204:207], v[74:77]
	v_mfma_f32_16x16x32_bf16 v[70:73], v[172:175], v[214:217], v[70:73]
	v_mfma_f32_16x16x32_bf16 v[66:69], v[180:183], v[214:217], v[66:69]
	s_setprio 0
	s_barrier
	s_add_i32 s34, s58, s36
	v_lshl_add_u64 v[218:219], v[218:219], 0, s[6:7]
	s_mov_b32 m0, s34
	ds_read_b128 v[184:187], v150 offset:49152
	ds_read_b128 v[188:191], v150 offset:50176
	ds_read_b128 v[192:195], v150 offset:51200
	ds_read_b128 v[196:199], v150 offset:52224
	ds_read_b128 v[200:203], v150 offset:53248
	ds_read_b128 v[204:207], v150 offset:54272
	ds_read_b128 v[210:213], v150 offset:55296
	ds_read_b128 v[214:217], v150 offset:56320
	global_load_lds_dwordx4 v[218:219], off
	s_add_i32 m0, s34, 0x2000
	s_add_u32 s30, s30, 0x100080
	v_lshl_add_u64 v[218:219], v[220:221], 0, s[6:7]
	s_addc_u32 s31, s31, 0
	s_add_i32 s34, s59, s36
	global_load_lds_dwordx4 v[218:219], off
	v_lshl_add_u64 v[218:219], s[30:31], 0, v[134:135]
	s_mov_b32 m0, s34
	s_nop 0
	global_load_lds_dwordx4 v[218:219], off
	v_lshl_add_u64 v[218:219], s[30:31], 0, v[130:131]
	s_add_i32 m0, s34, 0x2000
	s_nop 0
	global_load_lds_dwordx4 v[218:219], off
	v_lshl_add_u64 v[218:219], v[222:223], 0, s[6:7]
	s_mov_b32 m0, s43
	s_nop 0
	global_load_lds_dwordx4 v[218:219], off
	v_lshl_add_u64 v[218:219], v[224:225], 0, s[6:7]
	s_mov_b32 m0, s44
	s_nop 0
	global_load_lds_dwordx4 v[218:219], off
	s_waitcnt vmcnt(8)
	s_waitcnt lgkmcnt(0)
	s_barrier
	s_setprio 1
	s_waitcnt lgkmcnt(0)
	v_mfma_f32_16x16x32_bf16 v[62:65], v[152:155], v[184:187], v[62:65]
	v_mfma_f32_16x16x32_bf16 v[58:61], v[160:163], v[184:187], v[58:61]
	v_mfma_f32_16x16x32_bf16 v[54:57], v[152:155], v[192:195], v[54:57]
	v_mfma_f32_16x16x32_bf16 v[50:53], v[160:163], v[192:195], v[50:53]
	v_mfma_f32_16x16x32_bf16 v[38:41], v[152:155], v[200:203], v[38:41]
	v_mfma_f32_16x16x32_bf16 v[34:37], v[160:163], v[200:203], v[34:37]
	v_mfma_f32_16x16x32_bf16 v[22:25], v[152:155], v[210:213], v[22:25]
	v_mfma_f32_16x16x32_bf16 v[18:21], v[160:163], v[210:213], v[18:21]
	v_mfma_f32_16x16x32_bf16 v[62:65], v[156:159], v[188:191], v[62:65]
	v_mfma_f32_16x16x32_bf16 v[58:61], v[164:167], v[188:191], v[58:61]
	v_mfma_f32_16x16x32_bf16 v[54:57], v[156:159], v[196:199], v[54:57]
	v_mfma_f32_16x16x32_bf16 v[50:53], v[164:167], v[196:199], v[50:53]
	v_mfma_f32_16x16x32_bf16 v[38:41], v[156:159], v[204:207], v[38:41]
	v_mfma_f32_16x16x32_bf16 v[34:37], v[164:167], v[204:207], v[34:37]
	v_mfma_f32_16x16x32_bf16 v[22:25], v[156:159], v[214:217], v[22:25]
	v_mfma_f32_16x16x32_bf16 v[18:21], v[164:167], v[214:217], v[18:21]
	s_setprio 0
	s_setprio 1
	v_mfma_f32_16x16x32_bf16 v[46:49], v[168:171], v[184:187], v[46:49]
	v_mfma_f32_16x16x32_bf16 v[42:45], v[176:179], v[184:187], v[42:45]
	v_mfma_f32_16x16x32_bf16 v[30:33], v[168:171], v[192:195], v[30:33]
	v_mfma_f32_16x16x32_bf16 v[26:29], v[176:179], v[192:195], v[26:29]
	v_mfma_f32_16x16x32_bf16 v[14:17], v[168:171], v[200:203], v[14:17]
	v_mfma_f32_16x16x32_bf16 v[10:13], v[176:179], v[200:203], v[10:13]
	v_mfma_f32_16x16x32_bf16 v[6:9], v[168:171], v[210:213], v[6:9]
	v_mfma_f32_16x16x32_bf16 v[2:5], v[176:179], v[210:213], v[2:5]
	v_mfma_f32_16x16x32_bf16 v[46:49], v[172:175], v[188:191], v[46:49]
	v_mfma_f32_16x16x32_bf16 v[42:45], v[180:183], v[188:191], v[42:45]
	v_mfma_f32_16x16x32_bf16 v[30:33], v[172:175], v[196:199], v[30:33]
	v_mfma_f32_16x16x32_bf16 v[26:29], v[180:183], v[196:199], v[26:29]
	v_mfma_f32_16x16x32_bf16 v[14:17], v[172:175], v[204:207], v[14:17]
	v_mfma_f32_16x16x32_bf16 v[10:13], v[180:183], v[204:207], v[10:13]
	v_mfma_f32_16x16x32_bf16 v[6:9], v[172:175], v[214:217], v[6:9]
	v_mfma_f32_16x16x32_bf16 v[2:5], v[180:183], v[214:217], v[2:5]
	s_setprio 0
	s_barrier
	s_add_i32 s57, s57, 2
	s_add_u32 s28, s28, 0x100
	s_addc_u32 s29, s29, 0
	s_add_u32 s55, s55, 0x100
	s_addc_u32 s56, s56, 0
	s_cmp_gt_u32 s57, 61
	s_cbranch_scc1 .Lpeel_exit_23
	.p2align 6

; #define PG8_STAGE(bufoff, gbase, voff) do { _Pragma("unroll") for (int _i = 0; _i < 2; ++_i) \
;         __builtin_amdgcn_global_load_lds((const unsigned*)((const char*)(gbase) + (voff)[_i]), (PG8_LAS unsigned*)(lds + (bufoff) + ldsw + _i * 8192), 16, 0, 0); } while (0)
; #define PG8_LDA(dst, b, h) do { _Pragma("unroll") for (int m = 0; m < 4; ++m) _Pragma("unroll") for (int k = 0; k < 2; ++k) dst[m][k] = *(const PG8_LAS bf16x8*)(lds + PG8_SA(b, h) + aoff + m * 2048 + k * 1024); } while (0)
; #define PG8_LDB(dst, b, h) do { _Pragma("unroll") for (int n = 0; n < 2; ++n) _Pragma("unroll") for (int k = 0; k < 2; ++k) dst[n][k] = *(const PG8_LAS bf16x8*)(lds + PG8_SB(b, h) + boff + n * 2048 + k * 1024); } while (0)
; #define PG8_MMA(ai, bj, At, Bt) do { __builtin_amdgcn_s_setprio(1); _Pragma("unroll") for (int m = 0; m < 4; ++m) _Pragma("unroll") for (int n = 0; n < 2; ++n) _Pragma("unroll") for (int k = 0; k < 2; ++k) \
;         acc[ai][bj][m][n] = __builtin_amdgcn_mfma_f32_16x16x32_bf16(Bt[n][k], At[m][k], acc[ai][bj][m][n], 0, 0, 0); __builtin_amdgcn_s_setprio(0); } while (0)
; #define PG8_WAIT_V(n) asm volatile("s_waitcnt vmcnt(" #n ")" ::: "memory")
; #define PG8_WAIT_L(n) asm volatile("s_waitcnt lgkmcnt(" #n ")" ::: "memory")
; #define PG8_BAR __builtin_amdgcn_s_barrier()
; #define PG8_SCHED __builtin_amdgcn_sched_barrier(0)
;     __host__ __device__ bool next(int i, Unit& u) const {
;         const long L = (long)i * G + c; if (L >= nwg) return false;
;         int wgid = (int)L; { const int q = nwg / NXCD, r = nwg % NXCD, xcd = wgid % NXCD, off = wgid / NXCD; wgid = (xcd < r ? xcd * (q + 1) : r * (q + 1) + (xcd - r) * q) + off; }
;         const int nig = WGM * nN, gid = wgid / nig, fm = gid * WGM, gsz = (nM - fm) < WGM ? (nM - fm) : WGM;
;         u.pm = fm + ((wgid % nig) % gsz); u.pn = (wgid % nig) / gsz; return true;
; template <class Epi, class Sched, bool ALIGN_EPI = false, bool SP2 = false>
; __device__ __forceinline__ void gemm_phase(PG8_LAS unsigned char* lds, const Gemm g, const Sched& S, const Epi& E) {
;     ...
;             PG8_LDB(B0, 0, 0); PG8_LDB(B1, 0, 1); PG8_SCHED; PG8_LDA(At, 0, 0); PG8_STAGE(PG8_SA(1, 1), a1 + hstepA, voffA);
;             PG8_WAIT_V(8); PG8_WAIT_L(0); PG8_BAR; PG8_MMA(0, 0, At, B0); PG8_MMA(0, 1, At, B1); PG8_BAR; PG8_SCHED;
.LBB0_2384:
	s_mov_b32 s100, s20
	s_mov_b32 s101, s21
	s_mov_b32 s47, s22
	s_mov_b32 s48, s23
	s_add_u32 s20, s20, 0x80080
	s_addc_u32 s21, s21, 0
	s_add_u32 s44, s22, 0x100
	s_addc_u32 s45, s23, 0
	ds_read_b128 v[154:157], v150
	ds_read_b128 v[158:161], v150 offset:1024
	ds_read_b128 v[162:165], v150 offset:2048
	ds_read_b128 v[166:169], v150 offset:3072
	ds_read_b128 v[170:173], v151
	ds_read_b128 v[174:177], v151 offset:1024
	ds_read_b128 v[178:181], v151 offset:2048
	ds_read_b128 v[182:185], v151 offset:3072
	s_add_u32 s22, s20, 0xfff80080
	s_addc_u32 s23, s21, -1
	s_mov_b32 s25, s23
	s_mov_b32 s24, s22
	s_mov_b32 s23, s45
	s_mov_b32 s22, s44
	v_lshl_add_u64 v[146:147], s[20:21], 0, v[138:139]
	s_add_i32 m0, s19, 0xc000
	ds_read_b128 v[186:189], v152
	ds_read_b128 v[190:193], v152 offset:1024
	ds_read_b128 v[194:197], v152 offset:2048
	ds_read_b128 v[198:201], v152 offset:3072
	ds_read_b128 v[202:205], v152 offset:4096
	ds_read_b128 v[210:213], v152 offset:5120
	ds_read_b128 v[214:217], v152 offset:6144
	ds_read_b128 v[218:221], v152 offset:7168
	global_load_lds_dwordx4 v[146:147], off
	v_lshl_add_u64 v[146:147], s[20:21], 0, v[140:141]
	s_add_i32 m0, s19, 0xe000
	s_nop 0
	global_load_lds_dwordx4 v[146:147], off
	s_add_i32 s34, s34, 1
	s_mul_i32 s4, s34, s37
	s_mul_hi_u32 s5, s34, s26
	s_add_i32 s5, s5, s4
	s_mul_i32 s4, s34, s26
	s_add_u32 s14, s4, s70
	s_addc_u32 s15, s5, s28
	v_cmp_gt_i64_e32 vcc, s[14:15], v[144:145]
	v_cmp_lt_i64_e64 s[4:5], s[14:15], v[142:143]
	s_cbranch_vccnz .LBB0_2386
	s_ashr_i32 s10, s14, 31
	s_lshr_b32 s10, s10, 29
	s_add_i32 s10, s14, s10
	s_ashr_i32 s11, s10, 3
	s_and_b32 s10, s10, -8
	s_sub_i32 s10, s14, s10
	s_cmp_lt_i32 s10, 0
	s_cselect_b32 s12, s29, 0x370
	s_mul_i32 s10, s12, s10
	s_add_i32 s10, s10, s11
	s_mul_hi_i32 s11, s10, 0x2e8ba2e9
	s_lshr_b32 s12, s11, 31
	s_ashr_i32 s11, s11, 5
	s_add_i32 s11, s11, s12
	s_lshl_b32 s12, s11, 2
	s_sub_i32 s13, 0xa0, s12
	s_min_i32 s13, s13, 4
	s_abs_i32 s14, s13
	v_cvt_f32_u32_e32 v2, s14
	s_sub_i32 s16, 0, s14
	s_mulk_i32 s11, 0xb0
	s_sub_i32 s11, s10, s11
	v_rcp_iflag_f32_e32 v2, v2
	s_abs_i32 s10, s11
	s_xor_b32 s15, s11, s13
	s_ashr_i32 s15, s15, 31
	v_mul_f32_e32 v2, 0x4f7ffffe, v2
	v_cvt_u32_f32_e32 v2, v2
	s_nop 0
	v_readfirstlane_b32 s17, v2
	s_mul_i32 s16, s16, s17
	s_mul_hi_u32 s16, s17, s16
	s_add_i32 s17, s17, s16
	s_mul_hi_u32 s16, s10, s17
	s_mul_i32 s17, s16, s14
	s_sub_i32 s10, s10, s17
	s_add_i32 s98, s16, 1
	s_sub_i32 s17, s10, s14
	s_cmp_ge_u32 s10, s14
	s_cselect_b32 s16, s98, s16
	s_cselect_b32 s10, s17, s10
	s_add_i32 s17, s16, 1
	s_cmp_ge_u32 s10, s14
	s_cselect_b32 s10, s17, s16
	s_xor_b32 s10, s10, s15
	s_sub_i32 s10, s10, s15
	s_mul_i32 s13, s10, s13
	s_sub_i32 s11, s11, s13
	s_add_i32 s12, s11, s12
.LBB0_2386:
	s_ashr_i32 s13, s12, 31
	s_lshl_b64 s[14:15], s[12:13], 20
	s_add_u32 s14, s86, s14
	s_addc_u32 s15, s87, s15
	s_and_b64 s[16:17], s[4:5], exec
	s_cselect_b32 s13, s15, s101
	s_cselect_b32 s42, s14, s100
	s_ashr_i32 s11, s10, 31
	s_lshl_b64 s[16:17], s[10:11], 20
	v_readlane_b32 s98, v254, 0
	v_readlane_b32 s99, v254, 1
	s_add_u32 s16, s98, s16
	s_addc_u32 s17, s99, s17
	s_and_b64 s[98:99], s[4:5], exec
	s_cselect_b32 s11, s17, s48
	s_cselect_b32 s43, s16, s47
	s_mov_b32 s46, -2
	s_waitcnt vmcnt(8)
	s_waitcnt lgkmcnt(0)
	s_barrier
	s_setprio 1
	s_waitcnt lgkmcnt(0)
	v_mfma_f32_16x16x32_bf16 v[126:129], v[154:157], v[186:189], 0
	v_mfma_f32_16x16x32_bf16 v[122:125], v[162:165], v[186:189], 0
	v_mfma_f32_16x16x32_bf16 v[110:113], v[154:157], v[194:197], 0
	v_mfma_f32_16x16x32_bf16 v[106:109], v[162:165], v[194:197], 0
	v_mfma_f32_16x16x32_bf16 v[94:97], v[154:157], v[202:205], 0
	v_mfma_f32_16x16x32_bf16 v[90:93], v[162:165], v[202:205], 0
	v_mfma_f32_16x16x32_bf16 v[78:81], v[154:157], v[214:217], 0
	v_mfma_f32_16x16x32_bf16 v[74:77], v[162:165], v[214:217], 0
	v_mfma_f32_16x16x32_bf16 v[126:129], v[158:161], v[190:193], v[126:129]
	v_mfma_f32_16x16x32_bf16 v[122:125], v[166:169], v[190:193], v[122:125]
	v_mfma_f32_16x16x32_bf16 v[110:113], v[158:161], v[198:201], v[110:113]
	v_mfma_f32_16x16x32_bf16 v[106:109], v[166:169], v[198:201], v[106:109]
	v_mfma_f32_16x16x32_bf16 v[94:97], v[158:161], v[210:213], v[94:97]
	v_mfma_f32_16x16x32_bf16 v[90:93], v[166:169], v[210:213], v[90:93]
	v_mfma_f32_16x16x32_bf16 v[78:81], v[158:161], v[218:221], v[78:81]
	v_mfma_f32_16x16x32_bf16 v[74:77], v[166:169], v[218:221], v[74:77]
	s_setprio 0
	s_setprio 1
	v_mfma_f32_16x16x32_bf16 v[118:121], v[170:173], v[186:189], 0
	v_mfma_f32_16x16x32_bf16 v[114:117], v[178:181], v[186:189], 0
	v_mfma_f32_16x16x32_bf16 v[102:105], v[170:173], v[194:197], 0
	v_mfma_f32_16x16x32_bf16 v[98:101], v[178:181], v[194:197], 0
	v_mfma_f32_16x16x32_bf16 v[86:89], v[170:173], v[202:205], 0
	v_mfma_f32_16x16x32_bf16 v[82:85], v[178:181], v[202:205], 0
	v_mfma_f32_16x16x32_bf16 v[70:73], v[170:173], v[214:217], 0
	v_mfma_f32_16x16x32_bf16 v[66:69], v[178:181], v[214:217], 0
	v_mfma_f32_16x16x32_bf16 v[118:121], v[174:177], v[190:193], v[118:121]
	v_mfma_f32_16x16x32_bf16 v[114:117], v[182:185], v[190:193], v[114:117]
	v_mfma_f32_16x16x32_bf16 v[102:105], v[174:177], v[198:201], v[102:105]
	v_mfma_f32_16x16x32_bf16 v[98:101], v[182:185], v[198:201], v[98:101]
	v_mfma_f32_16x16x32_bf16 v[86:89], v[174:177], v[210:213], v[86:89]
	v_mfma_f32_16x16x32_bf16 v[82:85], v[182:185], v[210:213], v[82:85]
	v_mfma_f32_16x16x32_bf16 v[70:73], v[174:177], v[218:221], v[70:73]
	v_mfma_f32_16x16x32_bf16 v[66:69], v[182:185], v[218:221], v[66:69]
	s_setprio 0
	s_barrier
; #define PG8_STAGE(bufoff, gbase, voff) do { _Pragma("unroll") for (int _i = 0; _i < 2; ++_i) \
;         __builtin_amdgcn_global_load_lds((const unsigned*)((const char*)(gbase) + (voff)[_i]), (PG8_LAS unsigned*)(lds + (bufoff) + ldsw + _i * 8192), 16, 0, 0); } while (0)
; #define PG8_LDA(dst, b, h) do { _Pragma("unroll") for (int m = 0; m < 4; ++m) _Pragma("unroll") for (int k = 0; k < 2; ++k) dst[m][k] = *(const PG8_LAS bf16x8*)(lds + PG8_SA(b, h) + aoff + m * 2048 + k * 1024); } while (0)
; #define PG8_LDB(dst, b, h) do { _Pragma("unroll") for (int n = 0; n < 2; ++n) _Pragma("unroll") for (int k = 0; k < 2; ++k) dst[n][k] = *(const PG8_LAS bf16x8*)(lds + PG8_SB(b, h) + boff + n * 2048 + k * 1024); } while (0)
; #define PG8_MMA(ai, bj, At, Bt) do { __builtin_amdgcn_s_setprio(1); _Pragma("unroll") for (int m = 0; m < 4; ++m) _Pragma("unroll") for (int n = 0; n < 2; ++n) _Pragma("unroll") for (int k = 0; k < 2; ++k) \
;         acc[ai][bj][m][n] = __builtin_amdgcn_mfma_f32_16x16x32_bf16(Bt[n][k], At[m][k], acc[ai][bj][m][n], 0, 0, 0); __builtin_amdgcn_s_setprio(0); } while (0)
; #define PG8_WAIT_V(n) asm volatile("s_waitcnt vmcnt(" #n ")" ::: "memory")
; #define PG8_WAIT_L(n) asm volatile("s_waitcnt lgkmcnt(" #n ")" ::: "memory")
; #define PG8_BAR __builtin_amdgcn_s_barrier()
; #define PG8_SCHED __builtin_amdgcn_sched_barrier(0)
; template <class Epi, class Sched, bool ALIGN_EPI = false, bool SP2 = false>
; __device__ __forceinline__ void gemm_phase(PG8_LAS unsigned char* lds, const Gemm g, const Sched& S, const Epi& E) {
;     ...
;             PG8_LDA(At, 0, 1); PG8_STAGE(PG8_SB(0, 0), b2, voffB); PG8_STAGE(PG8_SB(0, 1), b2 + hstepB, voffB); PG8_STAGE(PG8_SA(0, 0), a2, voffA);
;             PG8_WAIT_V(8); PG8_WAIT_L(0); PG8_BAR; PG8_MMA(1, 0, At, B0); PG8_MMA(1, 1, At, B1); PG8_BAR; PG8_SCHED;
;             PG8_LDB(B0, 1, 0); PG8_LDB(B1, 1, 1); PG8_SCHED; PG8_LDA(At, 1, 0); PG8_STAGE(PG8_SA(0, 1), a2 + hstepA, voffA);
;             PG8_WAIT_V(8); PG8_WAIT_L(0); PG8_BAR; PG8_MMA(0, 0, At, B0); PG8_MMA(0, 1, At, B1); PG8_BAR; PG8_SCHED;
	s_add_i32 s47, s38, s27
	v_lshl_add_u64 v[146:147], s[22:23], 0, v[134:135]
	s_mov_b32 m0, s47
	ds_read_b128 v[186:189], v152 offset:16384
	ds_read_b128 v[190:193], v152 offset:17408
	ds_read_b128 v[194:197], v152 offset:18432
	ds_read_b128 v[198:201], v152 offset:19456
	ds_read_b128 v[202:205], v152 offset:20480
	ds_read_b128 v[210:213], v152 offset:21504
	ds_read_b128 v[214:217], v152 offset:22528
	ds_read_b128 v[218:221], v152 offset:23552
	global_load_lds_dwordx4 v[146:147], off
	s_add_i32 m0, s47, 0x2000
	s_add_u32 s48, s22, 0x80000
	v_lshl_add_u64 v[206:207], s[22:23], 0, v[130:131]
	s_addc_u32 s49, s23, 0
	s_add_i32 s47, s39, s27
	global_load_lds_dwordx4 v[206:207], off
	v_lshl_add_u64 v[222:223], s[48:49], 0, v[134:135]
	s_mov_b32 m0, s47
	v_lshl_add_u64 v[224:225], s[24:25], 0, v[132:133]
	global_load_lds_dwordx4 v[222:223], off
	v_lshl_add_u64 v[222:223], s[48:49], 0, v[130:131]
	s_add_i32 m0, s47, 0x2000
	s_nop 0
	global_load_lds_dwordx4 v[222:223], off
	v_lshl_add_u64 v[222:223], s[24:25], 0, v[136:137]
	s_mov_b32 m0, s19
	s_nop 0
	global_load_lds_dwordx4 v[222:223], off
	s_mov_b32 m0, s30
	s_nop 0
	global_load_lds_dwordx4 v[224:225], off
	s_waitcnt vmcnt(8)
	s_waitcnt lgkmcnt(0)
	s_barrier
	s_setprio 1
	s_waitcnt lgkmcnt(0)
	v_mfma_f32_16x16x32_bf16 v[62:65], v[154:157], v[186:189], 0
	v_mfma_f32_16x16x32_bf16 v[58:61], v[162:165], v[186:189], 0
	v_mfma_f32_16x16x32_bf16 v[46:49], v[154:157], v[194:197], 0
	v_mfma_f32_16x16x32_bf16 v[42:45], v[162:165], v[194:197], 0
	v_mfma_f32_16x16x32_bf16 v[30:33], v[154:157], v[202:205], 0
	v_mfma_f32_16x16x32_bf16 v[26:29], v[162:165], v[202:205], 0
	v_mfma_f32_16x16x32_bf16 v[14:17], v[154:157], v[214:217], 0
	v_mfma_f32_16x16x32_bf16 v[10:13], v[162:165], v[214:217], 0
	v_mfma_f32_16x16x32_bf16 v[62:65], v[158:161], v[190:193], v[62:65]
	v_mfma_f32_16x16x32_bf16 v[58:61], v[166:169], v[190:193], v[58:61]
	v_mfma_f32_16x16x32_bf16 v[46:49], v[158:161], v[198:201], v[46:49]
	v_mfma_f32_16x16x32_bf16 v[42:45], v[166:169], v[198:201], v[42:45]
	v_mfma_f32_16x16x32_bf16 v[30:33], v[158:161], v[210:213], v[30:33]
	v_mfma_f32_16x16x32_bf16 v[26:29], v[166:169], v[210:213], v[26:29]
	v_mfma_f32_16x16x32_bf16 v[14:17], v[158:161], v[218:221], v[14:17]
	v_mfma_f32_16x16x32_bf16 v[10:13], v[166:169], v[218:221], v[10:13]
	s_setprio 0
	s_setprio 1
	v_mfma_f32_16x16x32_bf16 v[54:57], v[170:173], v[186:189], 0
	v_mfma_f32_16x16x32_bf16 v[50:53], v[178:181], v[186:189], 0
	v_mfma_f32_16x16x32_bf16 v[38:41], v[170:173], v[194:197], 0
	v_mfma_f32_16x16x32_bf16 v[34:37], v[178:181], v[194:197], 0
	v_mfma_f32_16x16x32_bf16 v[22:25], v[170:173], v[202:205], 0
	v_mfma_f32_16x16x32_bf16 v[18:21], v[178:181], v[202:205], 0
	v_mfma_f32_16x16x32_bf16 v[6:9], v[170:173], v[214:217], 0
	v_mfma_f32_16x16x32_bf16 v[2:5], v[178:181], v[214:217], 0
	v_mfma_f32_16x16x32_bf16 v[54:57], v[174:177], v[190:193], v[54:57]
	v_mfma_f32_16x16x32_bf16 v[50:53], v[182:185], v[190:193], v[50:53]
	v_mfma_f32_16x16x32_bf16 v[38:41], v[174:177], v[198:201], v[38:41]
	v_mfma_f32_16x16x32_bf16 v[34:37], v[182:185], v[198:201], v[34:37]
	v_mfma_f32_16x16x32_bf16 v[22:25], v[174:177], v[210:213], v[22:25]
	v_mfma_f32_16x16x32_bf16 v[18:21], v[182:185], v[210:213], v[18:21]
	v_mfma_f32_16x16x32_bf16 v[6:9], v[174:177], v[218:221], v[6:9]
	v_mfma_f32_16x16x32_bf16 v[2:5], v[182:185], v[218:221], v[2:5]
	s_setprio 0
	s_barrier
	s_add_i32 s47, 0, 0x18000
	v_add_u32_e32 v153, s47, v148
	s_add_i32 s48, 0, 0x1c000
	ds_read_b128 v[154:157], v153
	ds_read_b128 v[158:161], v153 offset:1024
	ds_read_b128 v[162:165], v153 offset:2048
	ds_read_b128 v[166:169], v153 offset:3072
	v_add_u32_e32 v153, s48, v148
	ds_read_b128 v[170:173], v153
	ds_read_b128 v[174:177], v153 offset:1024
	ds_read_b128 v[178:181], v153 offset:2048
	ds_read_b128 v[182:185], v153 offset:3072
	s_add_u32 s24, s24, 0x80000
	s_addc_u32 s25, s25, 0
	s_mov_b32 m0, s31
	v_lshl_add_u64 v[226:227], s[24:25], 0, v[136:137]
	ds_read_b128 v[186:189], v152 offset:32768
	ds_read_b128 v[190:193], v152 offset:33792
	ds_read_b128 v[194:197], v152 offset:34816
	ds_read_b128 v[198:201], v152 offset:35840
	ds_read_b128 v[202:205], v152 offset:36864
	ds_read_b128 v[210:213], v152 offset:37888
	ds_read_b128 v[214:217], v152 offset:38912
	ds_read_b128 v[218:221], v152 offset:39936
	global_load_lds_dwordx4 v[226:227], off
	v_lshl_add_u64 v[226:227], s[24:25], 0, v[132:133]
	s_mov_b32 m0, s33
	s_nop 0
	global_load_lds_dwordx4 v[226:227], off
	s_waitcnt vmcnt(8)
	s_waitcnt lgkmcnt(0)
	s_barrier
; #define PG8_STAGE(bufoff, gbase, voff) do { _Pragma("unroll") for (int _i = 0; _i < 2; ++_i) \
;         __builtin_amdgcn_global_load_lds((const unsigned*)((const char*)(gbase) + (voff)[_i]), (PG8_LAS unsigned*)(lds + (bufoff) + ldsw + _i * 8192), 16, 0, 0); } while (0)
; #define PG8_LDA(dst, b, h) do { _Pragma("unroll") for (int m = 0; m < 4; ++m) _Pragma("unroll") for (int k = 0; k < 2; ++k) dst[m][k] = *(const PG8_LAS bf16x8*)(lds + PG8_SA(b, h) + aoff + m * 2048 + k * 1024); } while (0)
; #define PG8_MMA(ai, bj, At, Bt) do { __builtin_amdgcn_s_setprio(1); _Pragma("unroll") for (int m = 0; m < 4; ++m) _Pragma("unroll") for (int n = 0; n < 2; ++n) _Pragma("unroll") for (int k = 0; k < 2; ++k) \
;         acc[ai][bj][m][n] = __builtin_amdgcn_mfma_f32_16x16x32_bf16(Bt[n][k], At[m][k], acc[ai][bj][m][n], 0, 0, 0); __builtin_amdgcn_s_setprio(0); } while (0)
; #define PG8_WAIT_V(n) asm volatile("s_waitcnt vmcnt(" #n ")" ::: "memory")
; #define PG8_WAIT_L(n) asm volatile("s_waitcnt lgkmcnt(" #n ")" ::: "memory")
; #define PG8_BAR __builtin_amdgcn_s_barrier()
; #define PG8_SCHED __builtin_amdgcn_sched_barrier(0)
; template <class Epi, class Sched, bool ALIGN_EPI = false, bool SP2 = false>
; __device__ __forceinline__ void gemm_phase(PG8_LAS unsigned char* lds, const Gemm g, const Sched& S, const Epi& E) {
;     ...
;         for (int t = 0; t < nt; t += 2) {
;     ...
;             PG8_WAIT_V(8); PG8_WAIT_L(0); PG8_BAR; PG8_MMA(0, 0, At, B0); PG8_MMA(0, 1, At, B1); PG8_BAR; PG8_SCHED;
;             PG8_LDA(At, 1, 1); PG8_STAGE(PG8_SB(1, 0), b3, voffB); PG8_STAGE(PG8_SB(1, 1), b3 + hstepB, voffB); PG8_STAGE(PG8_SA(1, 0), a3, voffA);
;             PG8_WAIT_V(8); PG8_WAIT_L(0); PG8_BAR; PG8_MMA(1, 0, At, B0); PG8_MMA(1, 1, At, B1); PG8_BAR; PG8_SCHED;
	s_setprio 1
	s_waitcnt lgkmcnt(0)
	v_mfma_f32_16x16x32_bf16 v[126:129], v[154:157], v[186:189], v[126:129]
	v_mfma_f32_16x16x32_bf16 v[122:125], v[162:165], v[186:189], v[122:125]
	v_mfma_f32_16x16x32_bf16 v[110:113], v[154:157], v[194:197], v[110:113]
	v_mfma_f32_16x16x32_bf16 v[106:109], v[162:165], v[194:197], v[106:109]
	v_mfma_f32_16x16x32_bf16 v[94:97], v[154:157], v[202:205], v[94:97]
	v_mfma_f32_16x16x32_bf16 v[90:93], v[162:165], v[202:205], v[90:93]
	v_mfma_f32_16x16x32_bf16 v[78:81], v[154:157], v[214:217], v[78:81]
	v_mfma_f32_16x16x32_bf16 v[74:77], v[162:165], v[214:217], v[74:77]
	v_mfma_f32_16x16x32_bf16 v[126:129], v[158:161], v[190:193], v[126:129]
	v_mfma_f32_16x16x32_bf16 v[122:125], v[166:169], v[190:193], v[122:125]
	v_mfma_f32_16x16x32_bf16 v[110:113], v[158:161], v[198:201], v[110:113]
	v_mfma_f32_16x16x32_bf16 v[106:109], v[166:169], v[198:201], v[106:109]
	v_mfma_f32_16x16x32_bf16 v[94:97], v[158:161], v[210:213], v[94:97]
	v_mfma_f32_16x16x32_bf16 v[90:93], v[166:169], v[210:213], v[90:93]
	v_mfma_f32_16x16x32_bf16 v[78:81], v[158:161], v[218:221], v[78:81]
	v_mfma_f32_16x16x32_bf16 v[74:77], v[166:169], v[218:221], v[74:77]
	s_setprio 0
	s_setprio 1
	v_mfma_f32_16x16x32_bf16 v[118:121], v[170:173], v[186:189], v[118:121]
	v_mfma_f32_16x16x32_bf16 v[114:117], v[178:181], v[186:189], v[114:117]
	v_mfma_f32_16x16x32_bf16 v[102:105], v[170:173], v[194:197], v[102:105]
	v_mfma_f32_16x16x32_bf16 v[98:101], v[178:181], v[194:197], v[98:101]
	v_mfma_f32_16x16x32_bf16 v[86:89], v[170:173], v[202:205], v[86:89]
	v_mfma_f32_16x16x32_bf16 v[82:85], v[178:181], v[202:205], v[82:85]
	v_mfma_f32_16x16x32_bf16 v[70:73], v[170:173], v[214:217], v[70:73]
	v_mfma_f32_16x16x32_bf16 v[66:69], v[178:181], v[214:217], v[66:69]
	v_mfma_f32_16x16x32_bf16 v[118:121], v[174:177], v[190:193], v[118:121]
	v_mfma_f32_16x16x32_bf16 v[114:117], v[182:185], v[190:193], v[114:117]
	v_mfma_f32_16x16x32_bf16 v[102:105], v[174:177], v[198:201], v[102:105]
	v_mfma_f32_16x16x32_bf16 v[98:101], v[182:185], v[198:201], v[98:101]
	v_mfma_f32_16x16x32_bf16 v[86:89], v[174:177], v[210:213], v[86:89]
	v_mfma_f32_16x16x32_bf16 v[82:85], v[182:185], v[210:213], v[82:85]
	v_mfma_f32_16x16x32_bf16 v[70:73], v[174:177], v[218:221], v[70:73]
	v_mfma_f32_16x16x32_bf16 v[66:69], v[182:185], v[218:221], v[66:69]
	s_setprio 0
	s_barrier
	s_add_i32 s24, s47, s27
	v_lshl_add_u64 v[146:147], v[146:147], 0, s[2:3]
	s_mov_b32 m0, s24
	ds_read_b128 v[186:189], v152 offset:49152
	ds_read_b128 v[190:193], v152 offset:50176
	ds_read_b128 v[194:197], v152 offset:51200
	ds_read_b128 v[198:201], v152 offset:52224
	ds_read_b128 v[202:205], v152 offset:53248
	ds_read_b128 v[210:213], v152 offset:54272
	ds_read_b128 v[214:217], v152 offset:55296
	ds_read_b128 v[218:221], v152 offset:56320
	global_load_lds_dwordx4 v[146:147], off
	s_add_i32 m0, s24, 0x2000
	s_add_u32 s22, s22, 0x80080
	v_lshl_add_u64 v[146:147], v[206:207], 0, s[2:3]
	s_addc_u32 s23, s23, 0
	s_add_i32 s24, s48, s27
	global_load_lds_dwordx4 v[146:147], off
	v_lshl_add_u64 v[146:147], s[22:23], 0, v[134:135]
	s_mov_b32 m0, s24
	s_nop 0
	global_load_lds_dwordx4 v[146:147], off
	v_lshl_add_u64 v[146:147], s[22:23], 0, v[130:131]
	s_add_i32 m0, s24, 0x2000
	s_nop 0
	global_load_lds_dwordx4 v[146:147], off
	v_lshl_add_u64 v[146:147], v[222:223], 0, s[2:3]
	s_mov_b32 m0, s35
	s_nop 0
	global_load_lds_dwordx4 v[146:147], off
	v_lshl_add_u64 v[146:147], v[224:225], 0, s[2:3]
	s_mov_b32 m0, s36
	s_nop 0
	global_load_lds_dwordx4 v[146:147], off
	s_waitcnt vmcnt(8)
	s_waitcnt lgkmcnt(0)
	s_barrier
	s_setprio 1
	s_waitcnt lgkmcnt(0)
	v_mfma_f32_16x16x32_bf16 v[62:65], v[154:157], v[186:189], v[62:65]
	v_mfma_f32_16x16x32_bf16 v[58:61], v[162:165], v[186:189], v[58:61]
	v_mfma_f32_16x16x32_bf16 v[46:49], v[154:157], v[194:197], v[46:49]
	v_mfma_f32_16x16x32_bf16 v[42:45], v[162:165], v[194:197], v[42:45]
	v_mfma_f32_16x16x32_bf16 v[30:33], v[154:157], v[202:205], v[30:33]
	v_mfma_f32_16x16x32_bf16 v[26:29], v[162:165], v[202:205], v[26:29]
	v_mfma_f32_16x16x32_bf16 v[14:17], v[154:157], v[214:217], v[14:17]
	v_mfma_f32_16x16x32_bf16 v[10:13], v[162:165], v[214:217], v[10:13]
	v_mfma_f32_16x16x32_bf16 v[62:65], v[158:161], v[190:193], v[62:65]
	v_mfma_f32_16x16x32_bf16 v[58:61], v[166:169], v[190:193], v[58:61]
	v_mfma_f32_16x16x32_bf16 v[46:49], v[158:161], v[198:201], v[46:49]
	v_mfma_f32_16x16x32_bf16 v[42:45], v[166:169], v[198:201], v[42:45]
	v_mfma_f32_16x16x32_bf16 v[30:33], v[158:161], v[210:213], v[30:33]
	v_mfma_f32_16x16x32_bf16 v[26:29], v[166:169], v[210:213], v[26:29]
	v_mfma_f32_16x16x32_bf16 v[14:17], v[158:161], v[218:221], v[14:17]
	v_mfma_f32_16x16x32_bf16 v[10:13], v[166:169], v[218:221], v[10:13]
	s_setprio 0
	s_setprio 1
	v_mfma_f32_16x16x32_bf16 v[54:57], v[170:173], v[186:189], v[54:57]
	v_mfma_f32_16x16x32_bf16 v[50:53], v[178:181], v[186:189], v[50:53]
	v_mfma_f32_16x16x32_bf16 v[38:41], v[170:173], v[194:197], v[38:41]
	v_mfma_f32_16x16x32_bf16 v[34:37], v[178:181], v[194:197], v[34:37]
	v_mfma_f32_16x16x32_bf16 v[22:25], v[170:173], v[202:205], v[22:25]
	v_mfma_f32_16x16x32_bf16 v[18:21], v[178:181], v[202:205], v[18:21]
	v_mfma_f32_16x16x32_bf16 v[6:9], v[170:173], v[214:217], v[6:9]
	v_mfma_f32_16x16x32_bf16 v[2:5], v[178:181], v[214:217], v[2:5]
	v_mfma_f32_16x16x32_bf16 v[54:57], v[174:177], v[190:193], v[54:57]
	v_mfma_f32_16x16x32_bf16 v[50:53], v[182:185], v[190:193], v[50:53]
	v_mfma_f32_16x16x32_bf16 v[38:41], v[174:177], v[198:201], v[38:41]
	v_mfma_f32_16x16x32_bf16 v[34:37], v[182:185], v[198:201], v[34:37]
	v_mfma_f32_16x16x32_bf16 v[22:25], v[174:177], v[210:213], v[22:25]
	v_mfma_f32_16x16x32_bf16 v[18:21], v[182:185], v[210:213], v[18:21]
	v_mfma_f32_16x16x32_bf16 v[6:9], v[174:177], v[218:221], v[6:9]
	v_mfma_f32_16x16x32_bf16 v[2:5], v[182:185], v[218:221], v[2:5]
	s_setprio 0
	s_barrier
	s_add_i32 s46, s46, 2
	s_add_u32 s20, s20, 0x100
	s_addc_u32 s21, s21, 0
	s_add_u32 s44, s44, 0x100
	s_addc_u32 s45, s45, 0
	s_cmp_gt_u32 s46, 29
	s_cbranch_scc1 .Lpeel_exit_25
	.p2align 6

; #define PG8_STAGE(bufoff, gbase, voff) do { _Pragma("unroll") for (int _i = 0; _i < 2; ++_i) \
;         __builtin_amdgcn_global_load_lds((const unsigned*)((const char*)(gbase) + (voff)[_i]), (PG8_LAS unsigned*)(lds + (bufoff) + ldsw + _i * 8192), 16, 0, 0); } while (0)
; #define PG8_LDA(dst, b, h) do { _Pragma("unroll") for (int m = 0; m < 4; ++m) _Pragma("unroll") for (int k = 0; k < 2; ++k) dst[m][k] = *(const PG8_LAS bf16x8*)(lds + PG8_SA(b, h) + aoff + m * 2048 + k * 1024); } while (0)
; #define PG8_LDB(dst, b, h) do { _Pragma("unroll") for (int n = 0; n < 2; ++n) _Pragma("unroll") for (int k = 0; k < 2; ++k) dst[n][k] = *(const PG8_LAS bf16x8*)(lds + PG8_SB(b, h) + boff + n * 2048 + k * 1024); } while (0)
; #define PG8_MMA(ai, bj, At, Bt) do { __builtin_amdgcn_s_setprio(1); _Pragma("unroll") for (int m = 0; m < 4; ++m) _Pragma("unroll") for (int n = 0; n < 2; ++n) _Pragma("unroll") for (int k = 0; k < 2; ++k) \
;         acc[ai][bj][m][n] = __builtin_amdgcn_mfma_f32_16x16x32_bf16(Bt[n][k], At[m][k], acc[ai][bj][m][n], 0, 0, 0); __builtin_amdgcn_s_setprio(0); } while (0)
; #define PG8_WAIT_V(n) asm volatile("s_waitcnt vmcnt(" #n ")" ::: "memory")
; #define PG8_WAIT_L(n) asm volatile("s_waitcnt lgkmcnt(" #n ")" ::: "memory")
; #define PG8_BAR __builtin_amdgcn_s_barrier()
; #define PG8_SCHED __builtin_amdgcn_sched_barrier(0)
;     __host__ __device__ bool next(int i, Unit& u) const {
;         const long L = (long)i * G + c; if (L >= nwg) return false;
;         int wgid = (int)L; { const int q = nwg / NXCD, r = nwg % NXCD, xcd = wgid % NXCD, off = wgid / NXCD; wgid = (xcd < r ? xcd * (q + 1) : r * (q + 1) + (xcd - r) * q) + off; }
;         const int nig = WGM * nN, gid = wgid / nig, fm = gid * WGM, gsz = (nM - fm) < WGM ? (nM - fm) : WGM;
;         u.pm = fm + ((wgid % nig) % gsz); u.pn = (wgid % nig) / gsz; return true;
; template <class Epi, class Sched, bool ALIGN_EPI = false, bool SP2 = false>
; __device__ __forceinline__ void gemm_phase(PG8_LAS unsigned char* lds, const Gemm g, const Sched& S, const Epi& E) {
;     ...
;             PG8_LDB(B0, 0, 0); PG8_LDB(B1, 0, 1); PG8_SCHED; PG8_LDA(At, 0, 0); PG8_STAGE(PG8_SA(1, 1), a1 + hstepA, voffA);
;             PG8_WAIT_V(8); PG8_WAIT_L(0); PG8_BAR; PG8_MMA(0, 0, At, B0); PG8_MMA(0, 1, At, B1); PG8_BAR; PG8_SCHED;
.LBB0_2612:
	s_mov_b32 s100, s22
	s_mov_b32 s101, s23
	s_mov_b32 s49, s24
	s_mov_b32 s50, s25
	s_add_u32 s22, s22, 0x80080
	s_addc_u32 s23, s23, 0
	s_add_u32 s46, s24, 0x100
	s_addc_u32 s47, s25, 0
	ds_read_b128 v[130:133], v166
	ds_read_b128 v[134:137], v166 offset:1024
	ds_read_b128 v[138:141], v166 offset:2048
	ds_read_b128 v[142:145], v166 offset:3072
	ds_read_b128 v[170:173], v167
	ds_read_b128 v[174:177], v167 offset:1024
	ds_read_b128 v[178:181], v167 offset:2048
	ds_read_b128 v[182:185], v167 offset:3072
	s_add_u32 s24, s22, 0xfff80080
	s_addc_u32 s25, s23, -1
	s_mov_b32 s27, s25
	s_mov_b32 s26, s24
	s_mov_b32 s25, s47
	s_mov_b32 s24, s46
	v_lshl_add_u64 v[162:163], s[22:23], 0, v[154:155]
	s_add_i32 m0, s21, 0xc000
	ds_read_b128 v[186:189], v168
	ds_read_b128 v[190:193], v168 offset:1024
	ds_read_b128 v[194:197], v168 offset:2048
	ds_read_b128 v[198:201], v168 offset:3072
	ds_read_b128 v[202:205], v168 offset:4096
	ds_read_b128 v[210:213], v168 offset:5120
	ds_read_b128 v[214:217], v168 offset:6144
	ds_read_b128 v[218:221], v168 offset:7168
	global_load_lds_dwordx4 v[162:163], off
	v_lshl_add_u64 v[162:163], s[22:23], 0, v[156:157]
	s_add_i32 m0, s21, 0xe000
	s_nop 0
	global_load_lds_dwordx4 v[162:163], off
	s_add_i32 s36, s36, 1
	s_mul_i32 s4, s36, s39
	s_mul_hi_u32 s5, s36, s28
	s_add_i32 s5, s5, s4
	s_mul_i32 s4, s36, s28
	s_add_u32 s16, s4, s70
	s_addc_u32 s17, s5, s30
	v_cmp_gt_i64_e32 vcc, s[16:17], v[160:161]
	v_cmp_lt_i64_e64 s[4:5], s[16:17], v[158:159]
	s_cbranch_vccnz .LBB0_2614
	s_ashr_i32 s12, s16, 31
	s_lshr_b32 s12, s12, 29
	s_add_i32 s12, s16, s12
	s_ashr_i32 s13, s12, 3
	s_and_b32 s12, s12, -8
	s_sub_i32 s12, s16, s12
	s_cmp_lt_i32 s12, 0
	s_cselect_b32 s14, s31, 0x1e0
	s_mul_i32 s12, s14, s12
	s_add_i32 s12, s12, s13
	s_mul_hi_i32 s13, s12, 0x2aaaaaab
	s_lshr_b32 s14, s13, 31
	s_ashr_i32 s13, s13, 4
	s_add_i32 s13, s13, s14
	s_lshl_b32 s14, s13, 2
	s_sub_i32 s15, 0xa0, s14
	s_min_i32 s15, s15, 4
	s_abs_i32 s16, s15
	v_cvt_f32_u32_e32 v2, s16
	s_sub_i32 s18, 0, s16
	s_mulk_i32 s13, 0x60
	s_sub_i32 s13, s12, s13
	v_rcp_iflag_f32_e32 v2, v2
	s_abs_i32 s12, s13
	s_xor_b32 s17, s13, s15
	s_ashr_i32 s17, s17, 31
	v_mul_f32_e32 v2, 0x4f7ffffe, v2
	v_cvt_u32_f32_e32 v2, v2
	s_nop 0
	v_readfirstlane_b32 s19, v2
	s_mul_i32 s18, s18, s19
	s_mul_hi_u32 s18, s19, s18
	s_add_i32 s19, s19, s18
	s_mul_hi_u32 s18, s12, s19
	s_mul_i32 s19, s18, s16
	s_sub_i32 s12, s12, s19
	s_add_i32 s98, s18, 1
	s_sub_i32 s19, s12, s16
	s_cmp_ge_u32 s12, s16
	s_cselect_b32 s18, s98, s18
	s_cselect_b32 s12, s19, s12
	s_add_i32 s19, s18, 1
	s_cmp_ge_u32 s12, s16
	s_cselect_b32 s12, s19, s18
	s_xor_b32 s12, s12, s17
	s_sub_i32 s12, s12, s17
	s_mul_i32 s15, s12, s15
	s_sub_i32 s13, s13, s15
	s_add_i32 s14, s13, s14
.LBB0_2614:
	s_ashr_i32 s15, s14, 31
	s_lshl_b64 s[16:17], s[14:15], 20
	s_add_u32 s16, s86, s16
	s_addc_u32 s17, s87, s17
	s_and_b64 s[18:19], s[4:5], exec
	s_cselect_b32 s15, s17, s101
	s_cselect_b32 s44, s16, s100
	s_ashr_i32 s13, s12, 31
	s_lshl_b64 s[18:19], s[12:13], 20
	s_add_u32 s18, s62, s18
	s_addc_u32 s19, s63, s19
	s_and_b64 s[98:99], s[4:5], exec
	s_cselect_b32 s13, s19, s50
	s_cselect_b32 s45, s18, s49
	s_mov_b32 s48, -2
	s_waitcnt vmcnt(8)
	s_waitcnt lgkmcnt(0)
	s_barrier
	s_setprio 1
	s_waitcnt lgkmcnt(0)
	v_mfma_f32_16x16x32_bf16 v[126:129], v[130:133], v[186:189], 0
	v_mfma_f32_16x16x32_bf16 v[122:125], v[138:141], v[186:189], 0
	v_mfma_f32_16x16x32_bf16 v[118:121], v[130:133], v[194:197], 0
	v_mfma_f32_16x16x32_bf16 v[114:117], v[138:141], v[194:197], 0
	v_mfma_f32_16x16x32_bf16 v[110:113], v[130:133], v[202:205], 0
	v_mfma_f32_16x16x32_bf16 v[102:105], v[138:141], v[202:205], 0
	v_mfma_f32_16x16x32_bf16 v[94:97], v[130:133], v[214:217], 0
	v_mfma_f32_16x16x32_bf16 v[86:89], v[138:141], v[214:217], 0
	v_mfma_f32_16x16x32_bf16 v[126:129], v[134:137], v[190:193], v[126:129]
	v_mfma_f32_16x16x32_bf16 v[122:125], v[142:145], v[190:193], v[122:125]
	v_mfma_f32_16x16x32_bf16 v[118:121], v[134:137], v[198:201], v[118:121]
	v_mfma_f32_16x16x32_bf16 v[114:117], v[142:145], v[198:201], v[114:117]
	v_mfma_f32_16x16x32_bf16 v[110:113], v[134:137], v[210:213], v[110:113]
	v_mfma_f32_16x16x32_bf16 v[102:105], v[142:145], v[210:213], v[102:105]
	v_mfma_f32_16x16x32_bf16 v[94:97], v[134:137], v[218:221], v[94:97]
	v_mfma_f32_16x16x32_bf16 v[86:89], v[142:145], v[218:221], v[86:89]
	s_setprio 0
	s_setprio 1
	v_mfma_f32_16x16x32_bf16 v[106:109], v[170:173], v[186:189], 0
	v_mfma_f32_16x16x32_bf16 v[98:101], v[178:181], v[186:189], 0
	v_mfma_f32_16x16x32_bf16 v[90:93], v[170:173], v[194:197], 0
	v_mfma_f32_16x16x32_bf16 v[82:85], v[178:181], v[194:197], 0
	v_mfma_f32_16x16x32_bf16 v[78:81], v[170:173], v[202:205], 0
	v_mfma_f32_16x16x32_bf16 v[74:77], v[178:181], v[202:205], 0
	v_mfma_f32_16x16x32_bf16 v[70:73], v[170:173], v[214:217], 0
	v_mfma_f32_16x16x32_bf16 v[66:69], v[178:181], v[214:217], 0
	v_mfma_f32_16x16x32_bf16 v[106:109], v[174:177], v[190:193], v[106:109]
	v_mfma_f32_16x16x32_bf16 v[98:101], v[182:185], v[190:193], v[98:101]
	v_mfma_f32_16x16x32_bf16 v[90:93], v[174:177], v[198:201], v[90:93]
	v_mfma_f32_16x16x32_bf16 v[82:85], v[182:185], v[198:201], v[82:85]
	v_mfma_f32_16x16x32_bf16 v[78:81], v[174:177], v[210:213], v[78:81]
	v_mfma_f32_16x16x32_bf16 v[74:77], v[182:185], v[210:213], v[74:77]
	v_mfma_f32_16x16x32_bf16 v[70:73], v[174:177], v[218:221], v[70:73]
	v_mfma_f32_16x16x32_bf16 v[66:69], v[182:185], v[218:221], v[66:69]
	s_setprio 0
	s_barrier
; #define PG8_STAGE(bufoff, gbase, voff) do { _Pragma("unroll") for (int _i = 0; _i < 2; ++_i) \
;         __builtin_amdgcn_global_load_lds((const unsigned*)((const char*)(gbase) + (voff)[_i]), (PG8_LAS unsigned*)(lds + (bufoff) + ldsw + _i * 8192), 16, 0, 0); } while (0)
; #define PG8_LDA(dst, b, h) do { _Pragma("unroll") for (int m = 0; m < 4; ++m) _Pragma("unroll") for (int k = 0; k < 2; ++k) dst[m][k] = *(const PG8_LAS bf16x8*)(lds + PG8_SA(b, h) + aoff + m * 2048 + k * 1024); } while (0)
; #define PG8_LDB(dst, b, h) do { _Pragma("unroll") for (int n = 0; n < 2; ++n) _Pragma("unroll") for (int k = 0; k < 2; ++k) dst[n][k] = *(const PG8_LAS bf16x8*)(lds + PG8_SB(b, h) + boff + n * 2048 + k * 1024); } while (0)
; #define PG8_MMA(ai, bj, At, Bt) do { __builtin_amdgcn_s_setprio(1); _Pragma("unroll") for (int m = 0; m < 4; ++m) _Pragma("unroll") for (int n = 0; n < 2; ++n) _Pragma("unroll") for (int k = 0; k < 2; ++k) \
;         acc[ai][bj][m][n] = __builtin_amdgcn_mfma_f32_16x16x32_bf16(Bt[n][k], At[m][k], acc[ai][bj][m][n], 0, 0, 0); __builtin_amdgcn_s_setprio(0); } while (0)
; #define PG8_WAIT_V(n) asm volatile("s_waitcnt vmcnt(" #n ")" ::: "memory")
; #define PG8_WAIT_L(n) asm volatile("s_waitcnt lgkmcnt(" #n ")" ::: "memory")
; #define PG8_BAR __builtin_amdgcn_s_barrier()
; #define PG8_SCHED __builtin_amdgcn_sched_barrier(0)
; template <class Epi, class Sched, bool ALIGN_EPI = false, bool SP2 = false>
; __device__ __forceinline__ void gemm_phase(PG8_LAS unsigned char* lds, const Gemm g, const Sched& S, const Epi& E) {
;     ...
;             PG8_LDA(At, 0, 1); PG8_STAGE(PG8_SB(0, 0), b2, voffB); PG8_STAGE(PG8_SB(0, 1), b2 + hstepB, voffB); PG8_STAGE(PG8_SA(0, 0), a2, voffA);
;             PG8_WAIT_V(8); PG8_WAIT_L(0); PG8_BAR; PG8_MMA(1, 0, At, B0); PG8_MMA(1, 1, At, B1); PG8_BAR; PG8_SCHED;
;             PG8_LDB(B0, 1, 0); PG8_LDB(B1, 1, 1); PG8_SCHED; PG8_LDA(At, 1, 0); PG8_STAGE(PG8_SA(0, 1), a2 + hstepA, voffA);
;             PG8_WAIT_V(8); PG8_WAIT_L(0); PG8_BAR; PG8_MMA(0, 0, At, B0); PG8_MMA(0, 1, At, B1); PG8_BAR; PG8_SCHED;
	s_add_i32 s49, s40, s29
	v_lshl_add_u64 v[162:163], s[24:25], 0, v[150:151]
	s_mov_b32 m0, s49
	ds_read_b128 v[186:189], v168 offset:16384
	ds_read_b128 v[190:193], v168 offset:17408
	ds_read_b128 v[194:197], v168 offset:18432
	ds_read_b128 v[198:201], v168 offset:19456
	ds_read_b128 v[202:205], v168 offset:20480
	ds_read_b128 v[210:213], v168 offset:21504
	ds_read_b128 v[214:217], v168 offset:22528
	ds_read_b128 v[218:221], v168 offset:23552
	global_load_lds_dwordx4 v[162:163], off
	s_add_i32 m0, s49, 0x2000
	s_add_u32 s50, s24, 0x80000
	v_lshl_add_u64 v[206:207], s[24:25], 0, v[146:147]
	s_addc_u32 s51, s25, 0
	s_add_i32 s49, s41, s29
	global_load_lds_dwordx4 v[206:207], off
	v_lshl_add_u64 v[222:223], s[50:51], 0, v[150:151]
	s_mov_b32 m0, s49
	v_lshl_add_u64 v[224:225], s[26:27], 0, v[148:149]
	global_load_lds_dwordx4 v[222:223], off
	v_lshl_add_u64 v[222:223], s[50:51], 0, v[146:147]
	s_add_i32 m0, s49, 0x2000
	s_nop 0
	global_load_lds_dwordx4 v[222:223], off
	v_lshl_add_u64 v[222:223], s[26:27], 0, v[152:153]
	s_mov_b32 m0, s21
	s_nop 0
	global_load_lds_dwordx4 v[222:223], off
	s_mov_b32 m0, s33
	s_nop 0
	global_load_lds_dwordx4 v[224:225], off
	s_waitcnt vmcnt(8)
	s_waitcnt lgkmcnt(0)
	s_barrier
	s_setprio 1
	s_waitcnt lgkmcnt(0)
	v_mfma_f32_16x16x32_bf16 v[62:65], v[130:133], v[186:189], 0
	v_mfma_f32_16x16x32_bf16 v[58:61], v[138:141], v[186:189], 0
	v_mfma_f32_16x16x32_bf16 v[54:57], v[130:133], v[194:197], 0
	v_mfma_f32_16x16x32_bf16 v[46:49], v[138:141], v[194:197], 0
	v_mfma_f32_16x16x32_bf16 v[38:41], v[130:133], v[202:205], 0
	v_mfma_f32_16x16x32_bf16 v[30:33], v[138:141], v[202:205], 0
	v_mfma_f32_16x16x32_bf16 v[22:25], v[130:133], v[214:217], 0
	v_mfma_f32_16x16x32_bf16 v[14:17], v[138:141], v[214:217], 0
	v_mfma_f32_16x16x32_bf16 v[62:65], v[134:137], v[190:193], v[62:65]
	v_mfma_f32_16x16x32_bf16 v[58:61], v[142:145], v[190:193], v[58:61]
	v_mfma_f32_16x16x32_bf16 v[54:57], v[134:137], v[198:201], v[54:57]
	v_mfma_f32_16x16x32_bf16 v[46:49], v[142:145], v[198:201], v[46:49]
	v_mfma_f32_16x16x32_bf16 v[38:41], v[134:137], v[210:213], v[38:41]
	v_mfma_f32_16x16x32_bf16 v[30:33], v[142:145], v[210:213], v[30:33]
	v_mfma_f32_16x16x32_bf16 v[22:25], v[134:137], v[218:221], v[22:25]
	v_mfma_f32_16x16x32_bf16 v[14:17], v[142:145], v[218:221], v[14:17]
	s_setprio 0
	s_setprio 1
	v_mfma_f32_16x16x32_bf16 v[50:53], v[170:173], v[186:189], 0
	v_mfma_f32_16x16x32_bf16 v[42:45], v[178:181], v[186:189], 0
	v_mfma_f32_16x16x32_bf16 v[34:37], v[170:173], v[194:197], 0
	v_mfma_f32_16x16x32_bf16 v[26:29], v[178:181], v[194:197], 0
	v_mfma_f32_16x16x32_bf16 v[18:21], v[170:173], v[202:205], 0
	v_mfma_f32_16x16x32_bf16 v[10:13], v[178:181], v[202:205], 0
	v_mfma_f32_16x16x32_bf16 v[6:9], v[170:173], v[214:217], 0
	v_mfma_f32_16x16x32_bf16 v[2:5], v[178:181], v[214:217], 0
	v_mfma_f32_16x16x32_bf16 v[50:53], v[174:177], v[190:193], v[50:53]
	v_mfma_f32_16x16x32_bf16 v[42:45], v[182:185], v[190:193], v[42:45]
	v_mfma_f32_16x16x32_bf16 v[34:37], v[174:177], v[198:201], v[34:37]
	v_mfma_f32_16x16x32_bf16 v[26:29], v[182:185], v[198:201], v[26:29]
	v_mfma_f32_16x16x32_bf16 v[18:21], v[174:177], v[210:213], v[18:21]
	v_mfma_f32_16x16x32_bf16 v[10:13], v[182:185], v[210:213], v[10:13]
	v_mfma_f32_16x16x32_bf16 v[6:9], v[174:177], v[218:221], v[6:9]
	v_mfma_f32_16x16x32_bf16 v[2:5], v[182:185], v[218:221], v[2:5]
	s_setprio 0
	s_barrier
	s_add_i32 s49, 0, 0x18000
	s_add_i32 s50, 0, 0x1c000
	v_add_u32_e32 v142, s49, v164
	v_add_u32_e32 v169, s50, v164
	ds_read_b128 v[130:133], v142
	ds_read_b128 v[134:137], v142 offset:1024
	ds_read_b128 v[138:141], v142 offset:2048
	ds_read_b128 v[142:145], v142 offset:3072
	ds_read_b128 v[170:173], v169
	ds_read_b128 v[174:177], v169 offset:1024
	ds_read_b128 v[178:181], v169 offset:2048
	ds_read_b128 v[182:185], v169 offset:3072
	s_add_u32 s26, s26, 0x80000
	s_addc_u32 s27, s27, 0
	s_mov_b32 m0, s34
	v_lshl_add_u64 v[226:227], s[26:27], 0, v[152:153]
	ds_read_b128 v[186:189], v168 offset:32768
	ds_read_b128 v[190:193], v168 offset:33792
	ds_read_b128 v[194:197], v168 offset:34816
	ds_read_b128 v[198:201], v168 offset:35840
	ds_read_b128 v[202:205], v168 offset:36864
	ds_read_b128 v[210:213], v168 offset:37888
	ds_read_b128 v[214:217], v168 offset:38912
	ds_read_b128 v[218:221], v168 offset:39936
	global_load_lds_dwordx4 v[226:227], off
	v_lshl_add_u64 v[226:227], s[26:27], 0, v[148:149]
	s_mov_b32 m0, s35
	s_nop 0
	global_load_lds_dwordx4 v[226:227], off
	s_waitcnt vmcnt(8)
	s_waitcnt lgkmcnt(0)
	s_barrier
; #define PG8_STAGE(bufoff, gbase, voff) do { _Pragma("unroll") for (int _i = 0; _i < 2; ++_i) \
;         __builtin_amdgcn_global_load_lds((const unsigned*)((const char*)(gbase) + (voff)[_i]), (PG8_LAS unsigned*)(lds + (bufoff) + ldsw + _i * 8192), 16, 0, 0); } while (0)
; #define PG8_LDA(dst, b, h) do { _Pragma("unroll") for (int m = 0; m < 4; ++m) _Pragma("unroll") for (int k = 0; k < 2; ++k) dst[m][k] = *(const PG8_LAS bf16x8*)(lds + PG8_SA(b, h) + aoff + m * 2048 + k * 1024); } while (0)
; #define PG8_MMA(ai, bj, At, Bt) do { __builtin_amdgcn_s_setprio(1); _Pragma("unroll") for (int m = 0; m < 4; ++m) _Pragma("unroll") for (int n = 0; n < 2; ++n) _Pragma("unroll") for (int k = 0; k < 2; ++k) \
;         acc[ai][bj][m][n] = __builtin_amdgcn_mfma_f32_16x16x32_bf16(Bt[n][k], At[m][k], acc[ai][bj][m][n], 0, 0, 0); __builtin_amdgcn_s_setprio(0); } while (0)
; #define PG8_WAIT_V(n) asm volatile("s_waitcnt vmcnt(" #n ")" ::: "memory")
; #define PG8_WAIT_L(n) asm volatile("s_waitcnt lgkmcnt(" #n ")" ::: "memory")
; #define PG8_BAR __builtin_amdgcn_s_barrier()
; #define PG8_SCHED __builtin_amdgcn_sched_barrier(0)
; template <class Epi, class Sched, bool ALIGN_EPI = false, bool SP2 = false>
; __device__ __forceinline__ void gemm_phase(PG8_LAS unsigned char* lds, const Gemm g, const Sched& S, const Epi& E) {
;     ...
;         for (int t = 0; t < nt; t += 2) {
;     ...
;             PG8_WAIT_V(8); PG8_WAIT_L(0); PG8_BAR; PG8_MMA(0, 0, At, B0); PG8_MMA(0, 1, At, B1); PG8_BAR; PG8_SCHED;
;             PG8_LDA(At, 1, 1); PG8_STAGE(PG8_SB(1, 0), b3, voffB); PG8_STAGE(PG8_SB(1, 1), b3 + hstepB, voffB); PG8_STAGE(PG8_SA(1, 0), a3, voffA);
;             PG8_WAIT_V(8); PG8_WAIT_L(0); PG8_BAR; PG8_MMA(1, 0, At, B0); PG8_MMA(1, 1, At, B1); PG8_BAR; PG8_SCHED;
	s_setprio 1
	s_waitcnt lgkmcnt(0)
	v_mfma_f32_16x16x32_bf16 v[126:129], v[130:133], v[186:189], v[126:129]
	v_mfma_f32_16x16x32_bf16 v[122:125], v[138:141], v[186:189], v[122:125]
	v_mfma_f32_16x16x32_bf16 v[118:121], v[130:133], v[194:197], v[118:121]
	v_mfma_f32_16x16x32_bf16 v[114:117], v[138:141], v[194:197], v[114:117]
	v_mfma_f32_16x16x32_bf16 v[110:113], v[130:133], v[202:205], v[110:113]
	v_mfma_f32_16x16x32_bf16 v[102:105], v[138:141], v[202:205], v[102:105]
	v_mfma_f32_16x16x32_bf16 v[94:97], v[130:133], v[214:217], v[94:97]
	v_mfma_f32_16x16x32_bf16 v[86:89], v[138:141], v[214:217], v[86:89]
	v_mfma_f32_16x16x32_bf16 v[126:129], v[134:137], v[190:193], v[126:129]
	v_mfma_f32_16x16x32_bf16 v[122:125], v[142:145], v[190:193], v[122:125]
	v_mfma_f32_16x16x32_bf16 v[118:121], v[134:137], v[198:201], v[118:121]
	v_mfma_f32_16x16x32_bf16 v[114:117], v[142:145], v[198:201], v[114:117]
	v_mfma_f32_16x16x32_bf16 v[110:113], v[134:137], v[210:213], v[110:113]
	v_mfma_f32_16x16x32_bf16 v[102:105], v[142:145], v[210:213], v[102:105]
	v_mfma_f32_16x16x32_bf16 v[94:97], v[134:137], v[218:221], v[94:97]
	v_mfma_f32_16x16x32_bf16 v[86:89], v[142:145], v[218:221], v[86:89]
	s_setprio 0
	s_setprio 1
	v_mfma_f32_16x16x32_bf16 v[106:109], v[170:173], v[186:189], v[106:109]
	v_mfma_f32_16x16x32_bf16 v[98:101], v[178:181], v[186:189], v[98:101]
	v_mfma_f32_16x16x32_bf16 v[90:93], v[170:173], v[194:197], v[90:93]
	v_mfma_f32_16x16x32_bf16 v[82:85], v[178:181], v[194:197], v[82:85]
	v_mfma_f32_16x16x32_bf16 v[78:81], v[170:173], v[202:205], v[78:81]
	v_mfma_f32_16x16x32_bf16 v[74:77], v[178:181], v[202:205], v[74:77]
	v_mfma_f32_16x16x32_bf16 v[70:73], v[170:173], v[214:217], v[70:73]
	v_mfma_f32_16x16x32_bf16 v[66:69], v[178:181], v[214:217], v[66:69]
	v_mfma_f32_16x16x32_bf16 v[106:109], v[174:177], v[190:193], v[106:109]
	v_mfma_f32_16x16x32_bf16 v[98:101], v[182:185], v[190:193], v[98:101]
	v_mfma_f32_16x16x32_bf16 v[90:93], v[174:177], v[198:201], v[90:93]
	v_mfma_f32_16x16x32_bf16 v[82:85], v[182:185], v[198:201], v[82:85]
	v_mfma_f32_16x16x32_bf16 v[78:81], v[174:177], v[210:213], v[78:81]
	v_mfma_f32_16x16x32_bf16 v[74:77], v[182:185], v[210:213], v[74:77]
	v_mfma_f32_16x16x32_bf16 v[70:73], v[174:177], v[218:221], v[70:73]
	v_mfma_f32_16x16x32_bf16 v[66:69], v[182:185], v[218:221], v[66:69]
	s_setprio 0
	s_barrier
	s_add_i32 s26, s49, s29
	v_lshl_add_u64 v[162:163], v[162:163], 0, s[8:9]
	s_mov_b32 m0, s26
	ds_read_b128 v[186:189], v168 offset:49152
	ds_read_b128 v[190:193], v168 offset:50176
	ds_read_b128 v[194:197], v168 offset:51200
	ds_read_b128 v[198:201], v168 offset:52224
	ds_read_b128 v[202:205], v168 offset:53248
	ds_read_b128 v[210:213], v168 offset:54272
	ds_read_b128 v[214:217], v168 offset:55296
	ds_read_b128 v[218:221], v168 offset:56320
	global_load_lds_dwordx4 v[162:163], off
	s_add_i32 m0, s26, 0x2000
	s_add_u32 s24, s24, 0x80080
	v_lshl_add_u64 v[162:163], v[206:207], 0, s[8:9]
	s_addc_u32 s25, s25, 0
	s_add_i32 s26, s50, s29
	global_load_lds_dwordx4 v[162:163], off
	v_lshl_add_u64 v[162:163], s[24:25], 0, v[150:151]
	s_mov_b32 m0, s26
	s_nop 0
	global_load_lds_dwordx4 v[162:163], off
	v_lshl_add_u64 v[162:163], s[24:25], 0, v[146:147]
	s_add_i32 m0, s26, 0x2000
	s_nop 0
	global_load_lds_dwordx4 v[162:163], off
	v_lshl_add_u64 v[162:163], v[222:223], 0, s[8:9]
	s_mov_b32 m0, s37
	s_nop 0
	global_load_lds_dwordx4 v[162:163], off
	v_lshl_add_u64 v[162:163], v[224:225], 0, s[8:9]
	s_mov_b32 m0, s38
	s_nop 0
	global_load_lds_dwordx4 v[162:163], off
	s_waitcnt vmcnt(8)
	s_waitcnt lgkmcnt(0)
	s_barrier
	s_setprio 1
	s_waitcnt lgkmcnt(0)
	v_mfma_f32_16x16x32_bf16 v[62:65], v[130:133], v[186:189], v[62:65]
	v_mfma_f32_16x16x32_bf16 v[58:61], v[138:141], v[186:189], v[58:61]
	v_mfma_f32_16x16x32_bf16 v[54:57], v[130:133], v[194:197], v[54:57]
	v_mfma_f32_16x16x32_bf16 v[46:49], v[138:141], v[194:197], v[46:49]
	v_mfma_f32_16x16x32_bf16 v[38:41], v[130:133], v[202:205], v[38:41]
	v_mfma_f32_16x16x32_bf16 v[30:33], v[138:141], v[202:205], v[30:33]
	v_mfma_f32_16x16x32_bf16 v[22:25], v[130:133], v[214:217], v[22:25]
	v_mfma_f32_16x16x32_bf16 v[14:17], v[138:141], v[214:217], v[14:17]
	v_mfma_f32_16x16x32_bf16 v[62:65], v[134:137], v[190:193], v[62:65]
	v_mfma_f32_16x16x32_bf16 v[58:61], v[142:145], v[190:193], v[58:61]
	v_mfma_f32_16x16x32_bf16 v[54:57], v[134:137], v[198:201], v[54:57]
	v_mfma_f32_16x16x32_bf16 v[46:49], v[142:145], v[198:201], v[46:49]
	v_mfma_f32_16x16x32_bf16 v[38:41], v[134:137], v[210:213], v[38:41]
	v_mfma_f32_16x16x32_bf16 v[30:33], v[142:145], v[210:213], v[30:33]
	v_mfma_f32_16x16x32_bf16 v[22:25], v[134:137], v[218:221], v[22:25]
	v_mfma_f32_16x16x32_bf16 v[14:17], v[142:145], v[218:221], v[14:17]
	s_setprio 0
	s_setprio 1
	v_mfma_f32_16x16x32_bf16 v[50:53], v[170:173], v[186:189], v[50:53]
	v_mfma_f32_16x16x32_bf16 v[42:45], v[178:181], v[186:189], v[42:45]
	v_mfma_f32_16x16x32_bf16 v[34:37], v[170:173], v[194:197], v[34:37]
	v_mfma_f32_16x16x32_bf16 v[26:29], v[178:181], v[194:197], v[26:29]
	v_mfma_f32_16x16x32_bf16 v[18:21], v[170:173], v[202:205], v[18:21]
	v_mfma_f32_16x16x32_bf16 v[10:13], v[178:181], v[202:205], v[10:13]
	v_mfma_f32_16x16x32_bf16 v[6:9], v[170:173], v[214:217], v[6:9]
	v_mfma_f32_16x16x32_bf16 v[2:5], v[178:181], v[214:217], v[2:5]
	v_mfma_f32_16x16x32_bf16 v[50:53], v[174:177], v[190:193], v[50:53]
	v_mfma_f32_16x16x32_bf16 v[42:45], v[182:185], v[190:193], v[42:45]
	v_mfma_f32_16x16x32_bf16 v[34:37], v[174:177], v[198:201], v[34:37]
	v_mfma_f32_16x16x32_bf16 v[26:29], v[182:185], v[198:201], v[26:29]
	v_mfma_f32_16x16x32_bf16 v[18:21], v[174:177], v[210:213], v[18:21]
	v_mfma_f32_16x16x32_bf16 v[10:13], v[182:185], v[210:213], v[10:13]
	v_mfma_f32_16x16x32_bf16 v[6:9], v[174:177], v[218:221], v[6:9]
	v_mfma_f32_16x16x32_bf16 v[2:5], v[182:185], v[218:221], v[2:5]
	s_setprio 0
	s_barrier
	s_add_i32 s48, s48, 2
	s_add_u32 s22, s22, 0x100
	s_addc_u32 s23, s23, 0
	s_add_u32 s46, s46, 0x100
	s_addc_u32 s47, s47, 0
	s_cmp_gt_u32 s48, 29
	s_cbranch_scc1 .Lpeel_exit_28
	.p2align 6

; #define PG8_STAGE(bufoff, gbase, voff) do { _Pragma("unroll") for (int _i = 0; _i < 2; ++_i) \
;         __builtin_amdgcn_global_load_lds((const unsigned*)((const char*)(gbase) + (voff)[_i]), (PG8_LAS unsigned*)(lds + (bufoff) + ldsw + _i * 8192), 16, 0, 0); } while (0)
; #define PG8_LDA(dst, b, h) do { _Pragma("unroll") for (int m = 0; m < 4; ++m) _Pragma("unroll") for (int k = 0; k < 2; ++k) dst[m][k] = *(const PG8_LAS bf16x8*)(lds + PG8_SA(b, h) + aoff + m * 2048 + k * 1024); } while (0)
; #define PG8_LDB(dst, b, h) do { _Pragma("unroll") for (int n = 0; n < 2; ++n) _Pragma("unroll") for (int k = 0; k < 2; ++k) dst[n][k] = *(const PG8_LAS bf16x8*)(lds + PG8_SB(b, h) + boff + n * 2048 + k * 1024); } while (0)
; #define PG8_MMA(ai, bj, At, Bt) do { __builtin_amdgcn_s_setprio(1); _Pragma("unroll") for (int m = 0; m < 4; ++m) _Pragma("unroll") for (int n = 0; n < 2; ++n) _Pragma("unroll") for (int k = 0; k < 2; ++k) \
;         acc[ai][bj][m][n] = __builtin_amdgcn_mfma_f32_16x16x32_bf16(Bt[n][k], At[m][k], acc[ai][bj][m][n], 0, 0, 0); __builtin_amdgcn_s_setprio(0); } while (0)
; #define PG8_WAIT_V(n) asm volatile("s_waitcnt vmcnt(" #n ")" ::: "memory")
; #define PG8_WAIT_L(n) asm volatile("s_waitcnt lgkmcnt(" #n ")" ::: "memory")
; #define PG8_BAR __builtin_amdgcn_s_barrier()
; #define PG8_SCHED __builtin_amdgcn_sched_barrier(0)
;     __host__ __device__ bool next(int i, Unit& u) const {
;         const long L = (long)i * G + c; if (L >= nwg) return false;
;         int wgid = (int)L; { const int q = nwg / NXCD, r = nwg % NXCD, xcd = wgid % NXCD, off = wgid / NXCD; wgid = (xcd < r ? xcd * (q + 1) : r * (q + 1) + (xcd - r) * q) + off; }
;         const int nig = WGM * nN, gid = wgid / nig, fm = gid * WGM, gsz = (nM - fm) < WGM ? (nM - fm) : WGM;
;         u.pm = fm + ((wgid % nig) % gsz); u.pn = (wgid % nig) / gsz; return true;
; template <class Epi, class Sched, bool ALIGN_EPI = false, bool SP2 = false>
; __device__ __forceinline__ void gemm_phase(PG8_LAS unsigned char* lds, const Gemm g, const Sched& S, const Epi& E) {
;     ...
;             PG8_LDB(B0, 0, 0); PG8_LDB(B1, 0, 1); PG8_SCHED; PG8_LDA(At, 0, 0); PG8_STAGE(PG8_SA(1, 1), a1 + hstepA, voffA);
;             PG8_WAIT_V(8); PG8_WAIT_L(0); PG8_BAR; PG8_MMA(0, 0, At, B0); PG8_MMA(0, 1, At, B1); PG8_BAR; PG8_SCHED;
.LBB0_3369:
	s_mov_b32 s100, s30
	s_mov_b32 s101, s31
	s_mov_b32 s60, s34
	s_mov_b32 s61, s35
	s_add_u32 s30, s30, 0x80080
	s_addc_u32 s31, s31, 0
	s_add_u32 s57, s34, 0x100
	s_addc_u32 s58, s35, 0
	ds_read_b128 v[130:133], v164
	ds_read_b128 v[134:137], v164 offset:1024
	ds_read_b128 v[138:141], v164 offset:2048
	ds_read_b128 v[142:145], v164 offset:3072
	ds_read_b128 v[168:171], v165
	ds_read_b128 v[172:175], v165 offset:1024
	ds_read_b128 v[176:179], v165 offset:2048
	ds_read_b128 v[180:183], v165 offset:3072
	s_add_u32 s34, s30, 0xfff80080
	s_addc_u32 s35, s31, -1
	s_mov_b32 s37, s35
	s_mov_b32 s36, s34
	s_mov_b32 s35, s58
	s_mov_b32 s34, s57
	v_lshl_add_u64 v[218:219], s[30:31], 0, v[154:155]
	s_add_i32 m0, s29, 0xc000
	ds_read_b128 v[184:187], v166
	ds_read_b128 v[188:191], v166 offset:1024
	ds_read_b128 v[192:195], v166 offset:2048
	ds_read_b128 v[196:199], v166 offset:3072
	ds_read_b128 v[200:203], v166 offset:4096
	ds_read_b128 v[204:207], v166 offset:5120
	ds_read_b128 v[210:213], v166 offset:6144
	ds_read_b128 v[214:217], v166 offset:7168
	global_load_lds_dwordx4 v[218:219], off
	v_lshl_add_u64 v[218:219], s[30:31], 0, v[156:157]
	s_add_i32 m0, s29, 0xe000
	s_nop 0
	global_load_lds_dwordx4 v[218:219], off
	s_add_i32 s44, s44, 1
	s_mul_i32 s4, s44, s47
	s_mul_hi_u32 s5, s44, s33
	s_add_i32 s5, s5, s4
	s_mul_i32 s4, s44, s33
	s_add_u32 s24, s4, s70
	s_addc_u32 s25, s5, s39
	v_cmp_gt_i64_e32 vcc, s[24:25], v[160:161]
	v_cmp_lt_i64_e64 s[4:5], s[24:25], v[158:159]
	s_cbranch_vccnz .LBB0_3371
	s_ashr_i32 s20, s24, 31
	s_lshr_b32 s20, s20, 29
	s_add_i32 s20, s24, s20
	s_ashr_i32 s21, s20, 3
	s_and_b32 s20, s20, -8
	s_sub_i32 s20, s24, s20
	s_cmp_lt_i32 s20, 0
	s_cselect_b32 s22, s40, 0xa0
	s_mul_i32 s20, s22, s20
	s_add_i32 s20, s20, s21
	s_ashr_i32 s21, s20, 31
	s_lshr_b32 s21, s21, 27
	s_add_i32 s21, s20, s21
	s_ashr_i32 s22, s21, 5
	s_lshl_b32 s22, s22, 2
	s_sub_i32 s23, 0xa0, s22
	s_min_i32 s23, s23, 4
	s_abs_i32 s24, s23
	v_cvt_f32_u32_e32 v2, s24
	s_sub_i32 s26, 0, s24
	s_andn2_b32 s21, s21, 31
	s_sub_i32 s21, s20, s21
	v_rcp_iflag_f32_e32 v2, v2
	s_abs_i32 s20, s21
	s_xor_b32 s25, s21, s23
	s_ashr_i32 s25, s25, 31
	v_mul_f32_e32 v2, 0x4f7ffffe, v2
	v_cvt_u32_f32_e32 v2, v2
	s_nop 0
	v_readfirstlane_b32 s27, v2
	s_mul_i32 s26, s26, s27
	s_mul_hi_u32 s26, s27, s26
	s_add_i32 s27, s27, s26
	s_mul_hi_u32 s26, s20, s27
	s_mul_i32 s27, s26, s24
	s_sub_i32 s20, s20, s27
	s_add_i32 s98, s26, 1
	s_sub_i32 s27, s20, s24
	s_cmp_ge_u32 s20, s24
	s_cselect_b32 s26, s98, s26
	s_cselect_b32 s20, s27, s20
	s_add_i32 s27, s26, 1
	s_cmp_ge_u32 s20, s24
	s_cselect_b32 s20, s27, s26
	s_xor_b32 s20, s20, s25
	s_sub_i32 s20, s20, s25
	s_mul_i32 s23, s20, s23
	s_sub_i32 s21, s21, s23
	s_add_i32 s22, s21, s22
.LBB0_3371:
	s_ashr_i32 s23, s22, 31
	s_lshl_b64 s[24:25], s[22:23], 20
	s_add_u32 s24, s86, s24
	s_addc_u32 s25, s87, s25
	s_and_b64 s[26:27], s[4:5], exec
	s_cselect_b32 s23, s25, s101
	s_cselect_b32 s55, s24, s100
	s_ashr_i32 s21, s20, 31
	s_lshl_b64 s[26:27], s[20:21], 20
	s_add_u32 s26, s88, s26
	s_addc_u32 s27, s89, s27
	s_and_b64 s[98:99], s[4:5], exec
	s_cselect_b32 s21, s27, s61
	s_cselect_b32 s56, s26, s60
	s_mov_b32 s59, -2
	s_waitcnt vmcnt(8)
	s_waitcnt lgkmcnt(0)
	s_barrier
	s_setprio 1
	s_waitcnt lgkmcnt(0)
	v_mfma_f32_16x16x32_bf16 v[126:129], v[130:133], v[184:187], 0
	v_mfma_f32_16x16x32_bf16 v[122:125], v[138:141], v[184:187], 0
	v_mfma_f32_16x16x32_bf16 v[118:121], v[130:133], v[192:195], 0
	v_mfma_f32_16x16x32_bf16 v[114:117], v[138:141], v[192:195], 0
	v_mfma_f32_16x16x32_bf16 v[110:113], v[130:133], v[200:203], 0
	v_mfma_f32_16x16x32_bf16 v[102:105], v[138:141], v[200:203], 0
	v_mfma_f32_16x16x32_bf16 v[94:97], v[130:133], v[210:213], 0
	v_mfma_f32_16x16x32_bf16 v[86:89], v[138:141], v[210:213], 0
	v_mfma_f32_16x16x32_bf16 v[126:129], v[134:137], v[188:191], v[126:129]
	v_mfma_f32_16x16x32_bf16 v[122:125], v[142:145], v[188:191], v[122:125]
	v_mfma_f32_16x16x32_bf16 v[118:121], v[134:137], v[196:199], v[118:121]
	v_mfma_f32_16x16x32_bf16 v[114:117], v[142:145], v[196:199], v[114:117]
	v_mfma_f32_16x16x32_bf16 v[110:113], v[134:137], v[204:207], v[110:113]
	v_mfma_f32_16x16x32_bf16 v[102:105], v[142:145], v[204:207], v[102:105]
	v_mfma_f32_16x16x32_bf16 v[94:97], v[134:137], v[214:217], v[94:97]
	v_mfma_f32_16x16x32_bf16 v[86:89], v[142:145], v[214:217], v[86:89]
	s_setprio 0
	s_setprio 1
	v_mfma_f32_16x16x32_bf16 v[106:109], v[168:171], v[184:187], 0
	v_mfma_f32_16x16x32_bf16 v[98:101], v[176:179], v[184:187], 0
	v_mfma_f32_16x16x32_bf16 v[90:93], v[168:171], v[192:195], 0
	v_mfma_f32_16x16x32_bf16 v[82:85], v[176:179], v[192:195], 0
	v_mfma_f32_16x16x32_bf16 v[78:81], v[168:171], v[200:203], 0
	v_mfma_f32_16x16x32_bf16 v[74:77], v[176:179], v[200:203], 0
	v_mfma_f32_16x16x32_bf16 v[70:73], v[168:171], v[210:213], 0
	v_mfma_f32_16x16x32_bf16 v[66:69], v[176:179], v[210:213], 0
	v_mfma_f32_16x16x32_bf16 v[106:109], v[172:175], v[188:191], v[106:109]
	v_mfma_f32_16x16x32_bf16 v[98:101], v[180:183], v[188:191], v[98:101]
	v_mfma_f32_16x16x32_bf16 v[90:93], v[172:175], v[196:199], v[90:93]
	v_mfma_f32_16x16x32_bf16 v[82:85], v[180:183], v[196:199], v[82:85]
	v_mfma_f32_16x16x32_bf16 v[78:81], v[172:175], v[204:207], v[78:81]
	v_mfma_f32_16x16x32_bf16 v[74:77], v[180:183], v[204:207], v[74:77]
	v_mfma_f32_16x16x32_bf16 v[70:73], v[172:175], v[214:217], v[70:73]
	v_mfma_f32_16x16x32_bf16 v[66:69], v[180:183], v[214:217], v[66:69]
	s_setprio 0
	s_barrier
; #define PG8_STAGE(bufoff, gbase, voff) do { _Pragma("unroll") for (int _i = 0; _i < 2; ++_i) \
;         __builtin_amdgcn_global_load_lds((const unsigned*)((const char*)(gbase) + (voff)[_i]), (PG8_LAS unsigned*)(lds + (bufoff) + ldsw + _i * 8192), 16, 0, 0); } while (0)
; #define PG8_LDA(dst, b, h) do { _Pragma("unroll") for (int m = 0; m < 4; ++m) _Pragma("unroll") for (int k = 0; k < 2; ++k) dst[m][k] = *(const PG8_LAS bf16x8*)(lds + PG8_SA(b, h) + aoff + m * 2048 + k * 1024); } while (0)
; #define PG8_LDB(dst, b, h) do { _Pragma("unroll") for (int n = 0; n < 2; ++n) _Pragma("unroll") for (int k = 0; k < 2; ++k) dst[n][k] = *(const PG8_LAS bf16x8*)(lds + PG8_SB(b, h) + boff + n * 2048 + k * 1024); } while (0)
; #define PG8_MMA(ai, bj, At, Bt) do { __builtin_amdgcn_s_setprio(1); _Pragma("unroll") for (int m = 0; m < 4; ++m) _Pragma("unroll") for (int n = 0; n < 2; ++n) _Pragma("unroll") for (int k = 0; k < 2; ++k) \
;         acc[ai][bj][m][n] = __builtin_amdgcn_mfma_f32_16x16x32_bf16(Bt[n][k], At[m][k], acc[ai][bj][m][n], 0, 0, 0); __builtin_amdgcn_s_setprio(0); } while (0)
; #define PG8_WAIT_V(n) asm volatile("s_waitcnt vmcnt(" #n ")" ::: "memory")
; #define PG8_WAIT_L(n) asm volatile("s_waitcnt lgkmcnt(" #n ")" ::: "memory")
; #define PG8_BAR __builtin_amdgcn_s_barrier()
; #define PG8_SCHED __builtin_amdgcn_sched_barrier(0)
; template <class Epi, class Sched, bool ALIGN_EPI = false, bool SP2 = false>
; __device__ __forceinline__ void gemm_phase(PG8_LAS unsigned char* lds, const Gemm g, const Sched& S, const Epi& E) {
;     ...
;             PG8_LDA(At, 0, 1); PG8_STAGE(PG8_SB(0, 0), b2, voffB); PG8_STAGE(PG8_SB(0, 1), b2 + hstepB, voffB); PG8_STAGE(PG8_SA(0, 0), a2, voffA);
;             PG8_WAIT_V(8); PG8_WAIT_L(0); PG8_BAR; PG8_MMA(1, 0, At, B0); PG8_MMA(1, 1, At, B1); PG8_BAR; PG8_SCHED;
;             PG8_LDB(B0, 1, 0); PG8_LDB(B1, 1, 1); PG8_SCHED; PG8_LDA(At, 1, 0); PG8_STAGE(PG8_SA(0, 1), a2 + hstepA, voffA);
;             PG8_WAIT_V(8); PG8_WAIT_L(0); PG8_BAR; PG8_MMA(0, 0, At, B0); PG8_MMA(0, 1, At, B1); PG8_BAR; PG8_SCHED;
	s_add_i32 s60, s48, s38
	v_lshl_add_u64 v[218:219], s[34:35], 0, v[150:151]
	s_mov_b32 m0, s60
	ds_read_b128 v[184:187], v166 offset:16384
	ds_read_b128 v[188:191], v166 offset:17408
	ds_read_b128 v[192:195], v166 offset:18432
	ds_read_b128 v[196:199], v166 offset:19456
	ds_read_b128 v[200:203], v166 offset:20480
	ds_read_b128 v[204:207], v166 offset:21504
	ds_read_b128 v[210:213], v166 offset:22528
	ds_read_b128 v[214:217], v166 offset:23552
	global_load_lds_dwordx4 v[218:219], off
	s_add_i32 m0, s60, 0x2000
	s_add_u32 s60, s34, 0x80000
	v_lshl_add_u64 v[220:221], s[34:35], 0, v[146:147]
	s_addc_u32 s61, s35, 0
	s_add_i32 s62, s49, s38
	global_load_lds_dwordx4 v[220:221], off
	v_lshl_add_u64 v[222:223], s[60:61], 0, v[150:151]
	s_mov_b32 m0, s62
	v_lshl_add_u64 v[224:225], s[36:37], 0, v[148:149]
	global_load_lds_dwordx4 v[222:223], off
	v_lshl_add_u64 v[222:223], s[60:61], 0, v[146:147]
	s_add_i32 m0, s62, 0x2000
	s_nop 0
	global_load_lds_dwordx4 v[222:223], off
	v_lshl_add_u64 v[222:223], s[36:37], 0, v[152:153]
	s_mov_b32 m0, s29
	s_nop 0
	global_load_lds_dwordx4 v[222:223], off
	s_mov_b32 m0, s41
	s_nop 0
	global_load_lds_dwordx4 v[224:225], off
	s_waitcnt vmcnt(8)
	s_waitcnt lgkmcnt(0)
	s_barrier
	s_setprio 1
	s_waitcnt lgkmcnt(0)
	v_mfma_f32_16x16x32_bf16 v[62:65], v[130:133], v[184:187], 0
	v_mfma_f32_16x16x32_bf16 v[58:61], v[138:141], v[184:187], 0
	v_mfma_f32_16x16x32_bf16 v[54:57], v[130:133], v[192:195], 0
	v_mfma_f32_16x16x32_bf16 v[46:49], v[138:141], v[192:195], 0
	v_mfma_f32_16x16x32_bf16 v[38:41], v[130:133], v[200:203], 0
	v_mfma_f32_16x16x32_bf16 v[30:33], v[138:141], v[200:203], 0
	v_mfma_f32_16x16x32_bf16 v[22:25], v[130:133], v[210:213], 0
	v_mfma_f32_16x16x32_bf16 v[14:17], v[138:141], v[210:213], 0
	v_mfma_f32_16x16x32_bf16 v[62:65], v[134:137], v[188:191], v[62:65]
	v_mfma_f32_16x16x32_bf16 v[58:61], v[142:145], v[188:191], v[58:61]
	v_mfma_f32_16x16x32_bf16 v[54:57], v[134:137], v[196:199], v[54:57]
	v_mfma_f32_16x16x32_bf16 v[46:49], v[142:145], v[196:199], v[46:49]
	v_mfma_f32_16x16x32_bf16 v[38:41], v[134:137], v[204:207], v[38:41]
	v_mfma_f32_16x16x32_bf16 v[30:33], v[142:145], v[204:207], v[30:33]
	v_mfma_f32_16x16x32_bf16 v[22:25], v[134:137], v[214:217], v[22:25]
	v_mfma_f32_16x16x32_bf16 v[14:17], v[142:145], v[214:217], v[14:17]
	s_setprio 0
	s_setprio 1
	v_mfma_f32_16x16x32_bf16 v[50:53], v[168:171], v[184:187], 0
	v_mfma_f32_16x16x32_bf16 v[42:45], v[176:179], v[184:187], 0
	v_mfma_f32_16x16x32_bf16 v[34:37], v[168:171], v[192:195], 0
	v_mfma_f32_16x16x32_bf16 v[26:29], v[176:179], v[192:195], 0
	v_mfma_f32_16x16x32_bf16 v[18:21], v[168:171], v[200:203], 0
	v_mfma_f32_16x16x32_bf16 v[10:13], v[176:179], v[200:203], 0
	v_mfma_f32_16x16x32_bf16 v[6:9], v[168:171], v[210:213], 0
	v_mfma_f32_16x16x32_bf16 v[2:5], v[176:179], v[210:213], 0
	v_mfma_f32_16x16x32_bf16 v[50:53], v[172:175], v[188:191], v[50:53]
	v_mfma_f32_16x16x32_bf16 v[42:45], v[180:183], v[188:191], v[42:45]
	v_mfma_f32_16x16x32_bf16 v[34:37], v[172:175], v[196:199], v[34:37]
	v_mfma_f32_16x16x32_bf16 v[26:29], v[180:183], v[196:199], v[26:29]
	v_mfma_f32_16x16x32_bf16 v[18:21], v[172:175], v[204:207], v[18:21]
	v_mfma_f32_16x16x32_bf16 v[10:13], v[180:183], v[204:207], v[10:13]
	v_mfma_f32_16x16x32_bf16 v[6:9], v[172:175], v[214:217], v[6:9]
	v_mfma_f32_16x16x32_bf16 v[2:5], v[180:183], v[214:217], v[2:5]
	s_setprio 0
	s_barrier
	s_add_i32 s60, 0, 0x18000
	s_add_i32 s61, 0, 0x1c000
	v_add_u32_e32 v142, s60, v162
	v_add_u32_e32 v167, s61, v162
	ds_read_b128 v[130:133], v142
	ds_read_b128 v[134:137], v142 offset:1024
	ds_read_b128 v[138:141], v142 offset:2048
	ds_read_b128 v[142:145], v142 offset:3072
	ds_read_b128 v[168:171], v167
	ds_read_b128 v[172:175], v167 offset:1024
	ds_read_b128 v[176:179], v167 offset:2048
	ds_read_b128 v[180:183], v167 offset:3072
	s_add_u32 s36, s36, 0x80000
	s_addc_u32 s37, s37, 0
	s_mov_b32 m0, s42
	v_lshl_add_u64 v[226:227], s[36:37], 0, v[152:153]
	ds_read_b128 v[184:187], v166 offset:32768
	ds_read_b128 v[188:191], v166 offset:33792
	ds_read_b128 v[192:195], v166 offset:34816
	ds_read_b128 v[196:199], v166 offset:35840
	ds_read_b128 v[200:203], v166 offset:36864
	ds_read_b128 v[204:207], v166 offset:37888
	ds_read_b128 v[210:213], v166 offset:38912
	ds_read_b128 v[214:217], v166 offset:39936
	global_load_lds_dwordx4 v[226:227], off
	v_lshl_add_u64 v[226:227], s[36:37], 0, v[148:149]
	s_mov_b32 m0, s43
	s_nop 0
	global_load_lds_dwordx4 v[226:227], off
	s_waitcnt vmcnt(8)
	s_waitcnt lgkmcnt(0)
	s_barrier
; #define PG8_STAGE(bufoff, gbase, voff) do { _Pragma("unroll") for (int _i = 0; _i < 2; ++_i) \
;         __builtin_amdgcn_global_load_lds((const unsigned*)((const char*)(gbase) + (voff)[_i]), (PG8_LAS unsigned*)(lds + (bufoff) + ldsw + _i * 8192), 16, 0, 0); } while (0)
; #define PG8_LDA(dst, b, h) do { _Pragma("unroll") for (int m = 0; m < 4; ++m) _Pragma("unroll") for (int k = 0; k < 2; ++k) dst[m][k] = *(const PG8_LAS bf16x8*)(lds + PG8_SA(b, h) + aoff + m * 2048 + k * 1024); } while (0)
; #define PG8_MMA(ai, bj, At, Bt) do { __builtin_amdgcn_s_setprio(1); _Pragma("unroll") for (int m = 0; m < 4; ++m) _Pragma("unroll") for (int n = 0; n < 2; ++n) _Pragma("unroll") for (int k = 0; k < 2; ++k) \
;         acc[ai][bj][m][n] = __builtin_amdgcn_mfma_f32_16x16x32_bf16(Bt[n][k], At[m][k], acc[ai][bj][m][n], 0, 0, 0); __builtin_amdgcn_s_setprio(0); } while (0)
; #define PG8_WAIT_V(n) asm volatile("s_waitcnt vmcnt(" #n ")" ::: "memory")
; #define PG8_WAIT_L(n) asm volatile("s_waitcnt lgkmcnt(" #n ")" ::: "memory")
; #define PG8_BAR __builtin_amdgcn_s_barrier()
; #define PG8_SCHED __builtin_amdgcn_sched_barrier(0)
; template <class Epi, class Sched, bool ALIGN_EPI = false, bool SP2 = false>
; __device__ __forceinline__ void gemm_phase(PG8_LAS unsigned char* lds, const Gemm g, const Sched& S, const Epi& E) {
;     ...
;         for (int t = 0; t < nt; t += 2) {
;     ...
;             PG8_WAIT_V(8); PG8_WAIT_L(0); PG8_BAR; PG8_MMA(0, 0, At, B0); PG8_MMA(0, 1, At, B1); PG8_BAR; PG8_SCHED;
;             PG8_LDA(At, 1, 1); PG8_STAGE(PG8_SB(1, 0), b3, voffB); PG8_STAGE(PG8_SB(1, 1), b3 + hstepB, voffB); PG8_STAGE(PG8_SA(1, 0), a3, voffA);
;             PG8_WAIT_V(8); PG8_WAIT_L(0); PG8_BAR; PG8_MMA(1, 0, At, B0); PG8_MMA(1, 1, At, B1); PG8_BAR; PG8_SCHED;
	s_setprio 1
	s_waitcnt lgkmcnt(0)
	v_mfma_f32_16x16x32_bf16 v[126:129], v[130:133], v[184:187], v[126:129]
	v_mfma_f32_16x16x32_bf16 v[122:125], v[138:141], v[184:187], v[122:125]
	v_mfma_f32_16x16x32_bf16 v[118:121], v[130:133], v[192:195], v[118:121]
	v_mfma_f32_16x16x32_bf16 v[114:117], v[138:141], v[192:195], v[114:117]
	v_mfma_f32_16x16x32_bf16 v[110:113], v[130:133], v[200:203], v[110:113]
	v_mfma_f32_16x16x32_bf16 v[102:105], v[138:141], v[200:203], v[102:105]
	v_mfma_f32_16x16x32_bf16 v[94:97], v[130:133], v[210:213], v[94:97]
	v_mfma_f32_16x16x32_bf16 v[86:89], v[138:141], v[210:213], v[86:89]
	v_mfma_f32_16x16x32_bf16 v[126:129], v[134:137], v[188:191], v[126:129]
	v_mfma_f32_16x16x32_bf16 v[122:125], v[142:145], v[188:191], v[122:125]
	v_mfma_f32_16x16x32_bf16 v[118:121], v[134:137], v[196:199], v[118:121]
	v_mfma_f32_16x16x32_bf16 v[114:117], v[142:145], v[196:199], v[114:117]
	v_mfma_f32_16x16x32_bf16 v[110:113], v[134:137], v[204:207], v[110:113]
	v_mfma_f32_16x16x32_bf16 v[102:105], v[142:145], v[204:207], v[102:105]
	v_mfma_f32_16x16x32_bf16 v[94:97], v[134:137], v[214:217], v[94:97]
	v_mfma_f32_16x16x32_bf16 v[86:89], v[142:145], v[214:217], v[86:89]
	s_setprio 0
	s_setprio 1
	v_mfma_f32_16x16x32_bf16 v[106:109], v[168:171], v[184:187], v[106:109]
	v_mfma_f32_16x16x32_bf16 v[98:101], v[176:179], v[184:187], v[98:101]
	v_mfma_f32_16x16x32_bf16 v[90:93], v[168:171], v[192:195], v[90:93]
	v_mfma_f32_16x16x32_bf16 v[82:85], v[176:179], v[192:195], v[82:85]
	v_mfma_f32_16x16x32_bf16 v[78:81], v[168:171], v[200:203], v[78:81]
	v_mfma_f32_16x16x32_bf16 v[74:77], v[176:179], v[200:203], v[74:77]
	v_mfma_f32_16x16x32_bf16 v[70:73], v[168:171], v[210:213], v[70:73]
	v_mfma_f32_16x16x32_bf16 v[66:69], v[176:179], v[210:213], v[66:69]
	v_mfma_f32_16x16x32_bf16 v[106:109], v[172:175], v[188:191], v[106:109]
	v_mfma_f32_16x16x32_bf16 v[98:101], v[180:183], v[188:191], v[98:101]
	v_mfma_f32_16x16x32_bf16 v[90:93], v[172:175], v[196:199], v[90:93]
	v_mfma_f32_16x16x32_bf16 v[82:85], v[180:183], v[196:199], v[82:85]
	v_mfma_f32_16x16x32_bf16 v[78:81], v[172:175], v[204:207], v[78:81]
	v_mfma_f32_16x16x32_bf16 v[74:77], v[180:183], v[204:207], v[74:77]
	v_mfma_f32_16x16x32_bf16 v[70:73], v[172:175], v[214:217], v[70:73]
	v_mfma_f32_16x16x32_bf16 v[66:69], v[180:183], v[214:217], v[66:69]
	s_setprio 0
	s_barrier
	s_add_i32 s36, s60, s38
	v_lshl_add_u64 v[218:219], v[218:219], 0, s[10:11]
	s_mov_b32 m0, s36
	ds_read_b128 v[184:187], v166 offset:49152
	ds_read_b128 v[188:191], v166 offset:50176
	ds_read_b128 v[192:195], v166 offset:51200
	ds_read_b128 v[196:199], v166 offset:52224
	ds_read_b128 v[200:203], v166 offset:53248
	ds_read_b128 v[204:207], v166 offset:54272
	ds_read_b128 v[210:213], v166 offset:55296
	ds_read_b128 v[214:217], v166 offset:56320
	global_load_lds_dwordx4 v[218:219], off
	s_add_i32 m0, s36, 0x2000
	s_add_u32 s34, s34, 0x80080
	v_lshl_add_u64 v[218:219], v[220:221], 0, s[10:11]
	s_addc_u32 s35, s35, 0
	s_add_i32 s36, s61, s38
	global_load_lds_dwordx4 v[218:219], off
	v_lshl_add_u64 v[218:219], s[34:35], 0, v[150:151]
	s_mov_b32 m0, s36
	s_nop 0
	global_load_lds_dwordx4 v[218:219], off
	v_lshl_add_u64 v[218:219], s[34:35], 0, v[146:147]
	s_add_i32 m0, s36, 0x2000
	s_nop 0
	global_load_lds_dwordx4 v[218:219], off
	v_lshl_add_u64 v[218:219], v[222:223], 0, s[10:11]
	s_mov_b32 m0, s45
	s_nop 0
	global_load_lds_dwordx4 v[218:219], off
	v_lshl_add_u64 v[218:219], v[224:225], 0, s[10:11]
	s_mov_b32 m0, s46
	s_nop 0
	global_load_lds_dwordx4 v[218:219], off
	s_waitcnt vmcnt(8)
	s_waitcnt lgkmcnt(0)
	s_barrier
	s_setprio 1
	s_waitcnt lgkmcnt(0)
	v_mfma_f32_16x16x32_bf16 v[62:65], v[130:133], v[184:187], v[62:65]
	v_mfma_f32_16x16x32_bf16 v[58:61], v[138:141], v[184:187], v[58:61]
	v_mfma_f32_16x16x32_bf16 v[54:57], v[130:133], v[192:195], v[54:57]
	v_mfma_f32_16x16x32_bf16 v[46:49], v[138:141], v[192:195], v[46:49]
	v_mfma_f32_16x16x32_bf16 v[38:41], v[130:133], v[200:203], v[38:41]
	v_mfma_f32_16x16x32_bf16 v[30:33], v[138:141], v[200:203], v[30:33]
	v_mfma_f32_16x16x32_bf16 v[22:25], v[130:133], v[210:213], v[22:25]
	v_mfma_f32_16x16x32_bf16 v[14:17], v[138:141], v[210:213], v[14:17]
	v_mfma_f32_16x16x32_bf16 v[62:65], v[134:137], v[188:191], v[62:65]
	v_mfma_f32_16x16x32_bf16 v[58:61], v[142:145], v[188:191], v[58:61]
	v_mfma_f32_16x16x32_bf16 v[54:57], v[134:137], v[196:199], v[54:57]
	v_mfma_f32_16x16x32_bf16 v[46:49], v[142:145], v[196:199], v[46:49]
	v_mfma_f32_16x16x32_bf16 v[38:41], v[134:137], v[204:207], v[38:41]
	v_mfma_f32_16x16x32_bf16 v[30:33], v[142:145], v[204:207], v[30:33]
	v_mfma_f32_16x16x32_bf16 v[22:25], v[134:137], v[214:217], v[22:25]
	v_mfma_f32_16x16x32_bf16 v[14:17], v[142:145], v[214:217], v[14:17]
	s_setprio 0
	s_setprio 1
	v_mfma_f32_16x16x32_bf16 v[50:53], v[168:171], v[184:187], v[50:53]
	v_mfma_f32_16x16x32_bf16 v[42:45], v[176:179], v[184:187], v[42:45]
	v_mfma_f32_16x16x32_bf16 v[34:37], v[168:171], v[192:195], v[34:37]
	v_mfma_f32_16x16x32_bf16 v[26:29], v[176:179], v[192:195], v[26:29]
	v_mfma_f32_16x16x32_bf16 v[18:21], v[168:171], v[200:203], v[18:21]
	v_mfma_f32_16x16x32_bf16 v[10:13], v[176:179], v[200:203], v[10:13]
	v_mfma_f32_16x16x32_bf16 v[6:9], v[168:171], v[210:213], v[6:9]
	v_mfma_f32_16x16x32_bf16 v[2:5], v[176:179], v[210:213], v[2:5]
	v_mfma_f32_16x16x32_bf16 v[50:53], v[172:175], v[188:191], v[50:53]
	v_mfma_f32_16x16x32_bf16 v[42:45], v[180:183], v[188:191], v[42:45]
	v_mfma_f32_16x16x32_bf16 v[34:37], v[172:175], v[196:199], v[34:37]
	v_mfma_f32_16x16x32_bf16 v[26:29], v[180:183], v[196:199], v[26:29]
	v_mfma_f32_16x16x32_bf16 v[18:21], v[172:175], v[204:207], v[18:21]
	v_mfma_f32_16x16x32_bf16 v[10:13], v[180:183], v[204:207], v[10:13]
	v_mfma_f32_16x16x32_bf16 v[6:9], v[172:175], v[214:217], v[6:9]
	v_mfma_f32_16x16x32_bf16 v[2:5], v[180:183], v[214:217], v[2:5]
	s_setprio 0
	s_barrier
	s_add_i32 s59, s59, 2
	s_add_u32 s30, s30, 0x100
	s_addc_u32 s31, s31, 0
	s_add_u32 s57, s57, 0x100
	s_addc_u32 s58, s58, 0
	s_cmp_gt_u32 s59, 29
	s_cbranch_scc1 .Lpeel_exit_32
	.p2align 6

; #define PG8_STAGE(bufoff, gbase, voff) do { _Pragma("unroll") for (int _i = 0; _i < 2; ++_i) \
;         __builtin_amdgcn_global_load_lds((const unsigned*)((const char*)(gbase) + (voff)[_i]), (PG8_LAS unsigned*)(lds + (bufoff) + ldsw + _i * 8192), 16, 0, 0); } while (0)
; #define PG8_LDA(dst, b, h) do { _Pragma("unroll") for (int m = 0; m < 4; ++m) _Pragma("unroll") for (int k = 0; k < 2; ++k) dst[m][k] = *(const PG8_LAS bf16x8*)(lds + PG8_SA(b, h) + aoff + m * 2048 + k * 1024); } while (0)
; #define PG8_LDB(dst, b, h) do { _Pragma("unroll") for (int n = 0; n < 2; ++n) _Pragma("unroll") for (int k = 0; k < 2; ++k) dst[n][k] = *(const PG8_LAS bf16x8*)(lds + PG8_SB(b, h) + boff + n * 2048 + k * 1024); } while (0)
; #define PG8_MMA(ai, bj, At, Bt) do { __builtin_amdgcn_s_setprio(1); _Pragma("unroll") for (int m = 0; m < 4; ++m) _Pragma("unroll") for (int n = 0; n < 2; ++n) _Pragma("unroll") for (int k = 0; k < 2; ++k) \
;         acc[ai][bj][m][n] = __builtin_amdgcn_mfma_f32_16x16x32_bf16(Bt[n][k], At[m][k], acc[ai][bj][m][n], 0, 0, 0); __builtin_amdgcn_s_setprio(0); } while (0)
; #define PG8_WAIT_V(n) asm volatile("s_waitcnt vmcnt(" #n ")" ::: "memory")
; #define PG8_WAIT_L(n) asm volatile("s_waitcnt lgkmcnt(" #n ")" ::: "memory")
; #define PG8_BAR __builtin_amdgcn_s_barrier()
; #define PG8_SCHED __builtin_amdgcn_sched_barrier(0)
;     __host__ __device__ bool next(int i, Unit& u) const {
;         const long L = (long)i * G + c; if (L >= nwg) return false;
;         int wgid = (int)L; { const int q = nwg / NXCD, r = nwg % NXCD, xcd = wgid % NXCD, off = wgid / NXCD; wgid = (xcd < r ? xcd * (q + 1) : r * (q + 1) + (xcd - r) * q) + off; }
;         const int nig = WGM * nN, gid = wgid / nig, fm = gid * WGM, gsz = (nM - fm) < WGM ? (nM - fm) : WGM;
;         u.pm = fm + ((wgid % nig) % gsz); u.pn = (wgid % nig) / gsz; return true;
; template <class Epi, class Sched, bool ALIGN_EPI = false, bool SP2 = false>
; __device__ __forceinline__ void gemm_phase(PG8_LAS unsigned char* lds, const Gemm g, const Sched& S, const Epi& E) {
;     ...
;             PG8_LDB(B0, 0, 0); PG8_LDB(B1, 0, 1); PG8_SCHED; PG8_LDA(At, 0, 0); PG8_STAGE(PG8_SA(1, 1), a1 + hstepA, voffA);
;             PG8_WAIT_V(8); PG8_WAIT_L(0); PG8_BAR; PG8_MMA(0, 0, At, B0); PG8_MMA(0, 1, At, B1); PG8_BAR; PG8_SCHED;
.LBB0_3497:
	s_mov_b32 s100, s20
	s_mov_b32 s101, s21
	s_mov_b32 s49, s22
	s_mov_b32 s50, s23
	s_add_u32 s20, s20, 0x80080
	s_addc_u32 s21, s21, 0
	s_add_u32 s46, s22, 0x100
	s_addc_u32 s47, s23, 0
	ds_read_b128 v[154:157], v150
	ds_read_b128 v[158:161], v150 offset:1024
	ds_read_b128 v[162:165], v150 offset:2048
	ds_read_b128 v[166:169], v150 offset:3072
	ds_read_b128 v[170:173], v151
	ds_read_b128 v[174:177], v151 offset:1024
	ds_read_b128 v[178:181], v151 offset:2048
	ds_read_b128 v[182:185], v151 offset:3072
	s_add_u32 s22, s20, 0xfff80080
	s_addc_u32 s23, s21, -1
	s_mov_b32 s25, s23
	s_mov_b32 s24, s22
	s_mov_b32 s23, s47
	s_mov_b32 s22, s46
	v_lshl_add_u64 v[146:147], s[20:21], 0, v[138:139]
	s_add_i32 m0, s19, 0xc000
	ds_read_b128 v[186:189], v152
	ds_read_b128 v[190:193], v152 offset:1024
	ds_read_b128 v[194:197], v152 offset:2048
	ds_read_b128 v[198:201], v152 offset:3072
	ds_read_b128 v[202:205], v152 offset:4096
	ds_read_b128 v[210:213], v152 offset:5120
	ds_read_b128 v[214:217], v152 offset:6144
	ds_read_b128 v[218:221], v152 offset:7168
	global_load_lds_dwordx4 v[146:147], off
	v_lshl_add_u64 v[146:147], s[20:21], 0, v[140:141]
	s_add_i32 m0, s19, 0xe000
	s_nop 0
	global_load_lds_dwordx4 v[146:147], off
	s_add_i32 s36, s36, 1
	s_mul_i32 s4, s36, s39
	s_mul_hi_u32 s5, s36, s26
	s_add_i32 s5, s5, s4
	s_mul_i32 s4, s36, s26
	s_add_u32 s14, s4, s70
	s_addc_u32 s15, s5, s30
	v_cmp_gt_i64_e32 vcc, s[14:15], v[144:145]
	v_cmp_lt_i64_e64 s[4:5], s[14:15], v[142:143]
	s_cbranch_vccnz .LBB0_3499
	s_ashr_i32 s10, s14, 31
	s_lshr_b32 s10, s10, 29
	s_add_i32 s10, s14, s10
	s_ashr_i32 s11, s10, 3
	s_and_b32 s10, s10, -8
	s_sub_i32 s10, s14, s10
	s_cmp_lt_i32 s10, 0
	s_cselect_b32 s12, s31, 0x370
	s_mul_i32 s10, s12, s10
	s_add_i32 s10, s10, s11
	s_mul_hi_i32 s11, s10, 0x2e8ba2e9
	s_lshr_b32 s12, s11, 31
	s_ashr_i32 s11, s11, 5
	s_add_i32 s11, s11, s12
	s_lshl_b32 s12, s11, 2
	s_sub_i32 s13, 0xa0, s12
	s_min_i32 s13, s13, 4
	s_abs_i32 s14, s13
	v_cvt_f32_u32_e32 v2, s14
	s_sub_i32 s16, 0, s14
	s_mulk_i32 s11, 0xb0
	s_sub_i32 s11, s10, s11
	v_rcp_iflag_f32_e32 v2, v2
	s_abs_i32 s10, s11
	s_xor_b32 s15, s11, s13
	s_ashr_i32 s15, s15, 31
	v_mul_f32_e32 v2, 0x4f7ffffe, v2
	v_cvt_u32_f32_e32 v2, v2
	s_nop 0
	v_readfirstlane_b32 s17, v2
	s_mul_i32 s16, s16, s17
	s_mul_hi_u32 s16, s17, s16
	s_add_i32 s17, s17, s16
	s_mul_hi_u32 s16, s10, s17
	s_mul_i32 s17, s16, s14
	s_sub_i32 s10, s10, s17
	s_add_i32 s98, s16, 1
	s_sub_i32 s17, s10, s14
	s_cmp_ge_u32 s10, s14
	s_cselect_b32 s16, s98, s16
	s_cselect_b32 s10, s17, s10
	s_add_i32 s17, s16, 1
	s_cmp_ge_u32 s10, s14
	s_cselect_b32 s10, s17, s16
	s_xor_b32 s10, s10, s15
	s_sub_i32 s10, s10, s15
	s_mul_i32 s13, s10, s13
	s_sub_i32 s11, s11, s13
	s_add_i32 s12, s11, s12
.LBB0_3499:
	s_ashr_i32 s13, s12, 31
	s_lshl_b64 s[14:15], s[12:13], 20
	s_add_u32 s14, s86, s14
	s_addc_u32 s15, s87, s15
	s_and_b64 s[16:17], s[4:5], exec
	s_cselect_b32 s13, s15, s101
	s_cselect_b32 s44, s14, s100
	s_ashr_i32 s11, s10, 31
	s_lshl_b64 s[16:17], s[10:11], 20
	s_add_u32 s16, s27, s16
	s_addc_u32 s17, s28, s17
	s_and_b64 s[98:99], s[4:5], exec
	s_cselect_b32 s11, s17, s50
	s_cselect_b32 s45, s16, s49
	s_mov_b32 s48, -2
	s_waitcnt vmcnt(8)
	s_waitcnt lgkmcnt(0)
	s_barrier
	s_setprio 1
	s_waitcnt lgkmcnt(0)
	v_mfma_f32_16x16x32_bf16 v[126:129], v[154:157], v[186:189], 0
	v_mfma_f32_16x16x32_bf16 v[122:125], v[162:165], v[186:189], 0
	v_mfma_f32_16x16x32_bf16 v[110:113], v[154:157], v[194:197], 0
	v_mfma_f32_16x16x32_bf16 v[106:109], v[162:165], v[194:197], 0
	v_mfma_f32_16x16x32_bf16 v[94:97], v[154:157], v[202:205], 0
	v_mfma_f32_16x16x32_bf16 v[90:93], v[162:165], v[202:205], 0
	v_mfma_f32_16x16x32_bf16 v[78:81], v[154:157], v[214:217], 0
	v_mfma_f32_16x16x32_bf16 v[74:77], v[162:165], v[214:217], 0
	v_mfma_f32_16x16x32_bf16 v[126:129], v[158:161], v[190:193], v[126:129]
	v_mfma_f32_16x16x32_bf16 v[122:125], v[166:169], v[190:193], v[122:125]
	v_mfma_f32_16x16x32_bf16 v[110:113], v[158:161], v[198:201], v[110:113]
	v_mfma_f32_16x16x32_bf16 v[106:109], v[166:169], v[198:201], v[106:109]
	v_mfma_f32_16x16x32_bf16 v[94:97], v[158:161], v[210:213], v[94:97]
	v_mfma_f32_16x16x32_bf16 v[90:93], v[166:169], v[210:213], v[90:93]
	v_mfma_f32_16x16x32_bf16 v[78:81], v[158:161], v[218:221], v[78:81]
	v_mfma_f32_16x16x32_bf16 v[74:77], v[166:169], v[218:221], v[74:77]
	s_setprio 0
	s_setprio 1
	v_mfma_f32_16x16x32_bf16 v[118:121], v[170:173], v[186:189], 0
	v_mfma_f32_16x16x32_bf16 v[114:117], v[178:181], v[186:189], 0
	v_mfma_f32_16x16x32_bf16 v[102:105], v[170:173], v[194:197], 0
	v_mfma_f32_16x16x32_bf16 v[98:101], v[178:181], v[194:197], 0
	v_mfma_f32_16x16x32_bf16 v[86:89], v[170:173], v[202:205], 0
	v_mfma_f32_16x16x32_bf16 v[82:85], v[178:181], v[202:205], 0
	v_mfma_f32_16x16x32_bf16 v[70:73], v[170:173], v[214:217], 0
	v_mfma_f32_16x16x32_bf16 v[66:69], v[178:181], v[214:217], 0
	v_mfma_f32_16x16x32_bf16 v[118:121], v[174:177], v[190:193], v[118:121]
	v_mfma_f32_16x16x32_bf16 v[114:117], v[182:185], v[190:193], v[114:117]
	v_mfma_f32_16x16x32_bf16 v[102:105], v[174:177], v[198:201], v[102:105]
	v_mfma_f32_16x16x32_bf16 v[98:101], v[182:185], v[198:201], v[98:101]
	v_mfma_f32_16x16x32_bf16 v[86:89], v[174:177], v[210:213], v[86:89]
	v_mfma_f32_16x16x32_bf16 v[82:85], v[182:185], v[210:213], v[82:85]
	v_mfma_f32_16x16x32_bf16 v[70:73], v[174:177], v[218:221], v[70:73]
	v_mfma_f32_16x16x32_bf16 v[66:69], v[182:185], v[218:221], v[66:69]
	s_setprio 0
	s_barrier
; #define PG8_STAGE(bufoff, gbase, voff) do { _Pragma("unroll") for (int _i = 0; _i < 2; ++_i) \
;         __builtin_amdgcn_global_load_lds((const unsigned*)((const char*)(gbase) + (voff)[_i]), (PG8_LAS unsigned*)(lds + (bufoff) + ldsw + _i * 8192), 16, 0, 0); } while (0)
; #define PG8_LDA(dst, b, h) do { _Pragma("unroll") for (int m = 0; m < 4; ++m) _Pragma("unroll") for (int k = 0; k < 2; ++k) dst[m][k] = *(const PG8_LAS bf16x8*)(lds + PG8_SA(b, h) + aoff + m * 2048 + k * 1024); } while (0)
; #define PG8_LDB(dst, b, h) do { _Pragma("unroll") for (int n = 0; n < 2; ++n) _Pragma("unroll") for (int k = 0; k < 2; ++k) dst[n][k] = *(const PG8_LAS bf16x8*)(lds + PG8_SB(b, h) + boff + n * 2048 + k * 1024); } while (0)
; #define PG8_MMA(ai, bj, At, Bt) do { __builtin_amdgcn_s_setprio(1); _Pragma("unroll") for (int m = 0; m < 4; ++m) _Pragma("unroll") for (int n = 0; n < 2; ++n) _Pragma("unroll") for (int k = 0; k < 2; ++k) \
;         acc[ai][bj][m][n] = __builtin_amdgcn_mfma_f32_16x16x32_bf16(Bt[n][k], At[m][k], acc[ai][bj][m][n], 0, 0, 0); __builtin_amdgcn_s_setprio(0); } while (0)
; #define PG8_WAIT_V(n) asm volatile("s_waitcnt vmcnt(" #n ")" ::: "memory")
; #define PG8_WAIT_L(n) asm volatile("s_waitcnt lgkmcnt(" #n ")" ::: "memory")
; #define PG8_BAR __builtin_amdgcn_s_barrier()
; #define PG8_SCHED __builtin_amdgcn_sched_barrier(0)
; template <class Epi, class Sched, bool ALIGN_EPI = false, bool SP2 = false>
; __device__ __forceinline__ void gemm_phase(PG8_LAS unsigned char* lds, const Gemm g, const Sched& S, const Epi& E) {
;     ...
;             PG8_LDA(At, 0, 1); PG8_STAGE(PG8_SB(0, 0), b2, voffB); PG8_STAGE(PG8_SB(0, 1), b2 + hstepB, voffB); PG8_STAGE(PG8_SA(0, 0), a2, voffA);
;             PG8_WAIT_V(8); PG8_WAIT_L(0); PG8_BAR; PG8_MMA(1, 0, At, B0); PG8_MMA(1, 1, At, B1); PG8_BAR; PG8_SCHED;
;             PG8_LDB(B0, 1, 0); PG8_LDB(B1, 1, 1); PG8_SCHED; PG8_LDA(At, 1, 0); PG8_STAGE(PG8_SA(0, 1), a2 + hstepA, voffA);
;             PG8_WAIT_V(8); PG8_WAIT_L(0); PG8_BAR; PG8_MMA(0, 0, At, B0); PG8_MMA(0, 1, At, B1); PG8_BAR; PG8_SCHED;
	s_add_i32 s49, s40, s29
	v_lshl_add_u64 v[146:147], s[22:23], 0, v[134:135]
	s_mov_b32 m0, s49
	ds_read_b128 v[186:189], v152 offset:16384
	ds_read_b128 v[190:193], v152 offset:17408
	ds_read_b128 v[194:197], v152 offset:18432
	ds_read_b128 v[198:201], v152 offset:19456
	ds_read_b128 v[202:205], v152 offset:20480
	ds_read_b128 v[210:213], v152 offset:21504
	ds_read_b128 v[214:217], v152 offset:22528
	ds_read_b128 v[218:221], v152 offset:23552
	global_load_lds_dwordx4 v[146:147], off
	s_add_i32 m0, s49, 0x2000
	s_add_u32 s50, s22, 0x80000
	v_lshl_add_u64 v[206:207], s[22:23], 0, v[130:131]
	s_addc_u32 s51, s23, 0
	s_add_i32 s49, s41, s29
	global_load_lds_dwordx4 v[206:207], off
	v_lshl_add_u64 v[222:223], s[50:51], 0, v[134:135]
	s_mov_b32 m0, s49
	v_lshl_add_u64 v[224:225], s[24:25], 0, v[132:133]
	global_load_lds_dwordx4 v[222:223], off
	v_lshl_add_u64 v[222:223], s[50:51], 0, v[130:131]
	s_add_i32 m0, s49, 0x2000
	s_nop 0
	global_load_lds_dwordx4 v[222:223], off
	v_lshl_add_u64 v[222:223], s[24:25], 0, v[136:137]
	s_mov_b32 m0, s19
	s_nop 0
	global_load_lds_dwordx4 v[222:223], off
	s_mov_b32 m0, s33
	s_nop 0
	global_load_lds_dwordx4 v[224:225], off
	s_waitcnt vmcnt(8)
	s_waitcnt lgkmcnt(0)
	s_barrier
	s_setprio 1
	s_waitcnt lgkmcnt(0)
	v_mfma_f32_16x16x32_bf16 v[62:65], v[154:157], v[186:189], 0
	v_mfma_f32_16x16x32_bf16 v[58:61], v[162:165], v[186:189], 0
	v_mfma_f32_16x16x32_bf16 v[46:49], v[154:157], v[194:197], 0
	v_mfma_f32_16x16x32_bf16 v[42:45], v[162:165], v[194:197], 0
	v_mfma_f32_16x16x32_bf16 v[30:33], v[154:157], v[202:205], 0
	v_mfma_f32_16x16x32_bf16 v[26:29], v[162:165], v[202:205], 0
	v_mfma_f32_16x16x32_bf16 v[14:17], v[154:157], v[214:217], 0
	v_mfma_f32_16x16x32_bf16 v[10:13], v[162:165], v[214:217], 0
	v_mfma_f32_16x16x32_bf16 v[62:65], v[158:161], v[190:193], v[62:65]
	v_mfma_f32_16x16x32_bf16 v[58:61], v[166:169], v[190:193], v[58:61]
	v_mfma_f32_16x16x32_bf16 v[46:49], v[158:161], v[198:201], v[46:49]
	v_mfma_f32_16x16x32_bf16 v[42:45], v[166:169], v[198:201], v[42:45]
	v_mfma_f32_16x16x32_bf16 v[30:33], v[158:161], v[210:213], v[30:33]
	v_mfma_f32_16x16x32_bf16 v[26:29], v[166:169], v[210:213], v[26:29]
	v_mfma_f32_16x16x32_bf16 v[14:17], v[158:161], v[218:221], v[14:17]
	v_mfma_f32_16x16x32_bf16 v[10:13], v[166:169], v[218:221], v[10:13]
	s_setprio 0
	s_setprio 1
	v_mfma_f32_16x16x32_bf16 v[54:57], v[170:173], v[186:189], 0
	v_mfma_f32_16x16x32_bf16 v[50:53], v[178:181], v[186:189], 0
	v_mfma_f32_16x16x32_bf16 v[38:41], v[170:173], v[194:197], 0
	v_mfma_f32_16x16x32_bf16 v[34:37], v[178:181], v[194:197], 0
	v_mfma_f32_16x16x32_bf16 v[22:25], v[170:173], v[202:205], 0
	v_mfma_f32_16x16x32_bf16 v[18:21], v[178:181], v[202:205], 0
	v_mfma_f32_16x16x32_bf16 v[6:9], v[170:173], v[214:217], 0
	v_mfma_f32_16x16x32_bf16 v[2:5], v[178:181], v[214:217], 0
	v_mfma_f32_16x16x32_bf16 v[54:57], v[174:177], v[190:193], v[54:57]
	v_mfma_f32_16x16x32_bf16 v[50:53], v[182:185], v[190:193], v[50:53]
	v_mfma_f32_16x16x32_bf16 v[38:41], v[174:177], v[198:201], v[38:41]
	v_mfma_f32_16x16x32_bf16 v[34:37], v[182:185], v[198:201], v[34:37]
	v_mfma_f32_16x16x32_bf16 v[22:25], v[174:177], v[210:213], v[22:25]
	v_mfma_f32_16x16x32_bf16 v[18:21], v[182:185], v[210:213], v[18:21]
	v_mfma_f32_16x16x32_bf16 v[6:9], v[174:177], v[218:221], v[6:9]
	v_mfma_f32_16x16x32_bf16 v[2:5], v[182:185], v[218:221], v[2:5]
	s_setprio 0
	s_barrier
	s_add_i32 s49, 0, 0x18000
	v_add_u32_e32 v153, s49, v148
	s_add_i32 s50, 0, 0x1c000
	ds_read_b128 v[154:157], v153
	ds_read_b128 v[158:161], v153 offset:1024
	ds_read_b128 v[162:165], v153 offset:2048
	ds_read_b128 v[166:169], v153 offset:3072
	v_add_u32_e32 v153, s50, v148
	ds_read_b128 v[170:173], v153
	ds_read_b128 v[174:177], v153 offset:1024
	ds_read_b128 v[178:181], v153 offset:2048
	ds_read_b128 v[182:185], v153 offset:3072
	s_add_u32 s24, s24, 0x80000
	s_addc_u32 s25, s25, 0
	s_mov_b32 m0, s34
	v_lshl_add_u64 v[226:227], s[24:25], 0, v[136:137]
	ds_read_b128 v[186:189], v152 offset:32768
	ds_read_b128 v[190:193], v152 offset:33792
	ds_read_b128 v[194:197], v152 offset:34816
	ds_read_b128 v[198:201], v152 offset:35840
	ds_read_b128 v[202:205], v152 offset:36864
	ds_read_b128 v[210:213], v152 offset:37888
	ds_read_b128 v[214:217], v152 offset:38912
	ds_read_b128 v[218:221], v152 offset:39936
	global_load_lds_dwordx4 v[226:227], off
	v_lshl_add_u64 v[226:227], s[24:25], 0, v[132:133]
	s_mov_b32 m0, s35
	s_nop 0
	global_load_lds_dwordx4 v[226:227], off
	s_waitcnt vmcnt(8)
	s_waitcnt lgkmcnt(0)
	s_barrier
; #define PG8_STAGE(bufoff, gbase, voff) do { _Pragma("unroll") for (int _i = 0; _i < 2; ++_i) \
;         __builtin_amdgcn_global_load_lds((const unsigned*)((const char*)(gbase) + (voff)[_i]), (PG8_LAS unsigned*)(lds + (bufoff) + ldsw + _i * 8192), 16, 0, 0); } while (0)
; #define PG8_LDA(dst, b, h) do { _Pragma("unroll") for (int m = 0; m < 4; ++m) _Pragma("unroll") for (int k = 0; k < 2; ++k) dst[m][k] = *(const PG8_LAS bf16x8*)(lds + PG8_SA(b, h) + aoff + m * 2048 + k * 1024); } while (0)
; #define PG8_MMA(ai, bj, At, Bt) do { __builtin_amdgcn_s_setprio(1); _Pragma("unroll") for (int m = 0; m < 4; ++m) _Pragma("unroll") for (int n = 0; n < 2; ++n) _Pragma("unroll") for (int k = 0; k < 2; ++k) \
;         acc[ai][bj][m][n] = __builtin_amdgcn_mfma_f32_16x16x32_bf16(Bt[n][k], At[m][k], acc[ai][bj][m][n], 0, 0, 0); __builtin_amdgcn_s_setprio(0); } while (0)
; #define PG8_WAIT_V(n) asm volatile("s_waitcnt vmcnt(" #n ")" ::: "memory")
; #define PG8_WAIT_L(n) asm volatile("s_waitcnt lgkmcnt(" #n ")" ::: "memory")
; #define PG8_BAR __builtin_amdgcn_s_barrier()
; #define PG8_SCHED __builtin_amdgcn_sched_barrier(0)
; template <class Epi, class Sched, bool ALIGN_EPI = false, bool SP2 = false>
; __device__ __forceinline__ void gemm_phase(PG8_LAS unsigned char* lds, const Gemm g, const Sched& S, const Epi& E) {
;     ...
;         for (int t = 0; t < nt; t += 2) {
;     ...
;             PG8_WAIT_V(8); PG8_WAIT_L(0); PG8_BAR; PG8_MMA(0, 0, At, B0); PG8_MMA(0, 1, At, B1); PG8_BAR; PG8_SCHED;
;             PG8_LDA(At, 1, 1); PG8_STAGE(PG8_SB(1, 0), b3, voffB); PG8_STAGE(PG8_SB(1, 1), b3 + hstepB, voffB); PG8_STAGE(PG8_SA(1, 0), a3, voffA);
;             PG8_WAIT_V(8); PG8_WAIT_L(0); PG8_BAR; PG8_MMA(1, 0, At, B0); PG8_MMA(1, 1, At, B1); PG8_BAR; PG8_SCHED;
	s_setprio 1
	s_waitcnt lgkmcnt(0)
	v_mfma_f32_16x16x32_bf16 v[126:129], v[154:157], v[186:189], v[126:129]
	v_mfma_f32_16x16x32_bf16 v[122:125], v[162:165], v[186:189], v[122:125]
	v_mfma_f32_16x16x32_bf16 v[110:113], v[154:157], v[194:197], v[110:113]
	v_mfma_f32_16x16x32_bf16 v[106:109], v[162:165], v[194:197], v[106:109]
	v_mfma_f32_16x16x32_bf16 v[94:97], v[154:157], v[202:205], v[94:97]
	v_mfma_f32_16x16x32_bf16 v[90:93], v[162:165], v[202:205], v[90:93]
	v_mfma_f32_16x16x32_bf16 v[78:81], v[154:157], v[214:217], v[78:81]
	v_mfma_f32_16x16x32_bf16 v[74:77], v[162:165], v[214:217], v[74:77]
	v_mfma_f32_16x16x32_bf16 v[126:129], v[158:161], v[190:193], v[126:129]
	v_mfma_f32_16x16x32_bf16 v[122:125], v[166:169], v[190:193], v[122:125]
	v_mfma_f32_16x16x32_bf16 v[110:113], v[158:161], v[198:201], v[110:113]
	v_mfma_f32_16x16x32_bf16 v[106:109], v[166:169], v[198:201], v[106:109]
	v_mfma_f32_16x16x32_bf16 v[94:97], v[158:161], v[210:213], v[94:97]
	v_mfma_f32_16x16x32_bf16 v[90:93], v[166:169], v[210:213], v[90:93]
	v_mfma_f32_16x16x32_bf16 v[78:81], v[158:161], v[218:221], v[78:81]
	v_mfma_f32_16x16x32_bf16 v[74:77], v[166:169], v[218:221], v[74:77]
	s_setprio 0
	s_setprio 1
	v_mfma_f32_16x16x32_bf16 v[118:121], v[170:173], v[186:189], v[118:121]
	v_mfma_f32_16x16x32_bf16 v[114:117], v[178:181], v[186:189], v[114:117]
	v_mfma_f32_16x16x32_bf16 v[102:105], v[170:173], v[194:197], v[102:105]
	v_mfma_f32_16x16x32_bf16 v[98:101], v[178:181], v[194:197], v[98:101]
	v_mfma_f32_16x16x32_bf16 v[86:89], v[170:173], v[202:205], v[86:89]
	v_mfma_f32_16x16x32_bf16 v[82:85], v[178:181], v[202:205], v[82:85]
	v_mfma_f32_16x16x32_bf16 v[70:73], v[170:173], v[214:217], v[70:73]
	v_mfma_f32_16x16x32_bf16 v[66:69], v[178:181], v[214:217], v[66:69]
	v_mfma_f32_16x16x32_bf16 v[118:121], v[174:177], v[190:193], v[118:121]
	v_mfma_f32_16x16x32_bf16 v[114:117], v[182:185], v[190:193], v[114:117]
	v_mfma_f32_16x16x32_bf16 v[102:105], v[174:177], v[198:201], v[102:105]
	v_mfma_f32_16x16x32_bf16 v[98:101], v[182:185], v[198:201], v[98:101]
	v_mfma_f32_16x16x32_bf16 v[86:89], v[174:177], v[210:213], v[86:89]
	v_mfma_f32_16x16x32_bf16 v[82:85], v[182:185], v[210:213], v[82:85]
	v_mfma_f32_16x16x32_bf16 v[70:73], v[174:177], v[218:221], v[70:73]
	v_mfma_f32_16x16x32_bf16 v[66:69], v[182:185], v[218:221], v[66:69]
	s_setprio 0
	s_barrier
	s_add_i32 s24, s49, s29
	v_lshl_add_u64 v[146:147], v[146:147], 0, s[6:7]
	s_mov_b32 m0, s24
	ds_read_b128 v[186:189], v152 offset:49152
	ds_read_b128 v[190:193], v152 offset:50176
	ds_read_b128 v[194:197], v152 offset:51200
	ds_read_b128 v[198:201], v152 offset:52224
	ds_read_b128 v[202:205], v152 offset:53248
	ds_read_b128 v[210:213], v152 offset:54272
	ds_read_b128 v[214:217], v152 offset:55296
	ds_read_b128 v[218:221], v152 offset:56320
	global_load_lds_dwordx4 v[146:147], off
	s_add_i32 m0, s24, 0x2000
	s_add_u32 s22, s22, 0x80080
	v_lshl_add_u64 v[146:147], v[206:207], 0, s[6:7]
	s_addc_u32 s23, s23, 0
	s_add_i32 s24, s50, s29
	global_load_lds_dwordx4 v[146:147], off
	v_lshl_add_u64 v[146:147], s[22:23], 0, v[134:135]
	s_mov_b32 m0, s24
	s_nop 0
	global_load_lds_dwordx4 v[146:147], off
	v_lshl_add_u64 v[146:147], s[22:23], 0, v[130:131]
	s_add_i32 m0, s24, 0x2000
	s_nop 0
	global_load_lds_dwordx4 v[146:147], off
	v_lshl_add_u64 v[146:147], v[222:223], 0, s[6:7]
	s_mov_b32 m0, s37
	s_nop 0
	global_load_lds_dwordx4 v[146:147], off
	v_lshl_add_u64 v[146:147], v[224:225], 0, s[6:7]
	s_mov_b32 m0, s38
	s_nop 0
	global_load_lds_dwordx4 v[146:147], off
	s_waitcnt vmcnt(8)
	s_waitcnt lgkmcnt(0)
	s_barrier
	s_setprio 1
	s_waitcnt lgkmcnt(0)
	v_mfma_f32_16x16x32_bf16 v[62:65], v[154:157], v[186:189], v[62:65]
	v_mfma_f32_16x16x32_bf16 v[58:61], v[162:165], v[186:189], v[58:61]
	v_mfma_f32_16x16x32_bf16 v[46:49], v[154:157], v[194:197], v[46:49]
	v_mfma_f32_16x16x32_bf16 v[42:45], v[162:165], v[194:197], v[42:45]
	v_mfma_f32_16x16x32_bf16 v[30:33], v[154:157], v[202:205], v[30:33]
	v_mfma_f32_16x16x32_bf16 v[26:29], v[162:165], v[202:205], v[26:29]
	v_mfma_f32_16x16x32_bf16 v[14:17], v[154:157], v[214:217], v[14:17]
	v_mfma_f32_16x16x32_bf16 v[10:13], v[162:165], v[214:217], v[10:13]
	v_mfma_f32_16x16x32_bf16 v[62:65], v[158:161], v[190:193], v[62:65]
	v_mfma_f32_16x16x32_bf16 v[58:61], v[166:169], v[190:193], v[58:61]
	v_mfma_f32_16x16x32_bf16 v[46:49], v[158:161], v[198:201], v[46:49]
	v_mfma_f32_16x16x32_bf16 v[42:45], v[166:169], v[198:201], v[42:45]
	v_mfma_f32_16x16x32_bf16 v[30:33], v[158:161], v[210:213], v[30:33]
	v_mfma_f32_16x16x32_bf16 v[26:29], v[166:169], v[210:213], v[26:29]
	v_mfma_f32_16x16x32_bf16 v[14:17], v[158:161], v[218:221], v[14:17]
	v_mfma_f32_16x16x32_bf16 v[10:13], v[166:169], v[218:221], v[10:13]
	s_setprio 0
	s_setprio 1
	v_mfma_f32_16x16x32_bf16 v[54:57], v[170:173], v[186:189], v[54:57]
	v_mfma_f32_16x16x32_bf16 v[50:53], v[178:181], v[186:189], v[50:53]
	v_mfma_f32_16x16x32_bf16 v[38:41], v[170:173], v[194:197], v[38:41]
	v_mfma_f32_16x16x32_bf16 v[34:37], v[178:181], v[194:197], v[34:37]
	v_mfma_f32_16x16x32_bf16 v[22:25], v[170:173], v[202:205], v[22:25]
	v_mfma_f32_16x16x32_bf16 v[18:21], v[178:181], v[202:205], v[18:21]
	v_mfma_f32_16x16x32_bf16 v[6:9], v[170:173], v[214:217], v[6:9]
	v_mfma_f32_16x16x32_bf16 v[2:5], v[178:181], v[214:217], v[2:5]
	v_mfma_f32_16x16x32_bf16 v[54:57], v[174:177], v[190:193], v[54:57]
	v_mfma_f32_16x16x32_bf16 v[50:53], v[182:185], v[190:193], v[50:53]
	v_mfma_f32_16x16x32_bf16 v[38:41], v[174:177], v[198:201], v[38:41]
	v_mfma_f32_16x16x32_bf16 v[34:37], v[182:185], v[198:201], v[34:37]
	v_mfma_f32_16x16x32_bf16 v[22:25], v[174:177], v[210:213], v[22:25]
	v_mfma_f32_16x16x32_bf16 v[18:21], v[182:185], v[210:213], v[18:21]
	v_mfma_f32_16x16x32_bf16 v[6:9], v[174:177], v[218:221], v[6:9]
	v_mfma_f32_16x16x32_bf16 v[2:5], v[182:185], v[218:221], v[2:5]
	s_setprio 0
	s_barrier
	s_add_i32 s48, s48, 2
	s_add_u32 s20, s20, 0x100
	s_addc_u32 s21, s21, 0
	s_add_u32 s46, s46, 0x100
	s_addc_u32 s47, s47, 0
	s_cmp_gt_u32 s48, 29
	s_cbranch_scc1 .Lpeel_exit_34
	.p2align 6

; __global__ void __launch_bounds__(512, 2) mega_fwd(const Args args) {
	.amdhsa_kernel _Z8mega_fwd4Args
		.amdhsa_group_segment_fixed_size 0
		.amdhsa_private_segment_fixed_size 0
		.amdhsa_kernarg_size 656
		.amdhsa_user_sgpr_count 2
		.amdhsa_user_sgpr_dispatch_ptr 0
		.amdhsa_user_sgpr_queue_ptr 0
		.amdhsa_user_sgpr_kernarg_segment_ptr 1
		.amdhsa_user_sgpr_dispatch_id 0
		.amdhsa_user_sgpr_kernarg_preload_length 0
		.amdhsa_user_sgpr_kernarg_preload_offset 0
		.amdhsa_user_sgpr_private_segment_size 0
		.amdhsa_uses_dynamic_stack 0
		.amdhsa_enable_private_segment 0
		.amdhsa_system_sgpr_workgroup_id_x 1
		.amdhsa_system_sgpr_workgroup_id_y 0
		.amdhsa_system_sgpr_workgroup_id_z 0
		.amdhsa_system_sgpr_workgroup_info 0
		.amdhsa_system_vgpr_workitem_id 0
		.amdhsa_next_free_vgpr 256
		.amdhsa_next_free_sgpr 102
		.amdhsa_accum_offset 256
		.amdhsa_reserve_vcc 1
		.amdhsa_float_round_mode_32 0
		.amdhsa_float_round_mode_16_64 0
		.amdhsa_float_denorm_mode_32 3
		.amdhsa_float_denorm_mode_16_64 3
		.amdhsa_dx10_clamp 1
		.amdhsa_ieee_mode 1
		.amdhsa_fp16_overflow 0
		.amdhsa_tg_split 0
		.amdhsa_exception_fp_ieee_invalid_op 0
		.amdhsa_exception_fp_denorm_src 0
		.amdhsa_exception_fp_ieee_div_zero 0
		.amdhsa_exception_fp_ieee_overflow 0
		.amdhsa_exception_fp_ieee_underflow 0
		.amdhsa_exception_fp_ieee_inexact 0
		.amdhsa_exception_int_div_zero 0
	.end_amdhsa_kernel

; __global__ void __launch_bounds__(512, 2) mega_fwd(const Args args) {
amdhsa.kernels:
  - .agpr_count:     0
    .args:
      - .offset:         0
        .size:           400
        .value_kind:     by_value
      - .offset:         400
        .size:           4
        .value_kind:     hidden_block_count_x
      - .offset:         404
        .size:           4
        .value_kind:     hidden_block_count_y
      - .offset:         408
        .size:           4
        .value_kind:     hidden_block_count_z
      - .offset:         412
        .size:           2
        .value_kind:     hidden_group_size_x
      - .offset:         414
        .size:           2
        .value_kind:     hidden_group_size_y
      - .offset:         416
        .size:           2
        .value_kind:     hidden_group_size_z
      - .offset:         418
        .size:           2
        .value_kind:     hidden_remainder_x
      - .offset:         420
        .size:           2
        .value_kind:     hidden_remainder_y
      - .offset:         422
        .size:           2
        .value_kind:     hidden_remainder_z
      - .offset:         440
        .size:           8
        .value_kind:     hidden_global_offset_x
      - .offset:         448
        .size:           8
        .value_kind:     hidden_global_offset_y
      - .offset:         456
        .size:           8
        .value_kind:     hidden_global_offset_z
      - .offset:         464
        .size:           2
        .value_kind:     hidden_grid_dims
      - .offset:         520
        .size:           4
        .value_kind:     hidden_dynamic_lds_size
    .group_segment_fixed_size: 0
    .kernarg_segment_align: 8
    .kernarg_segment_size: 656
    .language:       OpenCL C
    .language_version:
      - 2
      - 0
    .max_flat_workgroup_size: 512
    .name:           _Z8mega_fwd4Args
    .private_segment_fixed_size: 0
    .sgpr_count:     108
    .sgpr_spill_count: 80
    .symbol:         _Z8mega_fwd4Args.kd
    .uniform_work_group_size: 1
    .uses_dynamic_stack: false
    .vgpr_count:     256
    .vgpr_spill_count: 0
    .wavefront_size: 64
